# MFMA issue order within each 16-MFMA block changed to acc-chained snake (m, n-snake, k) in all GEMM loops
# speedup vs baseline: 1.0195x; 1.0195x over previous
.LBB0_211:
	ds_read_b128 v[160:163], v153
	ds_read_b128 v[164:167], v153 offset:1024
	ds_read_b128 v[172:175], v153 offset:2048
	ds_read_b128 v[176:179], v153 offset:3072
	ds_read_b128 v[180:183], v157
	ds_read_b128 v[184:187], v157 offset:1024
	ds_read_b128 v[188:191], v157 offset:2048
	ds_read_b128 v[192:195], v157 offset:3072
	s_add_u32 s20, s52, 0xfff00080
	s_addc_u32 s21, s53, -1
	s_cmp_eq_u32 s77, 60
	s_cselect_b32 s57, s17, s21
	s_cselect_b32 s56, s41, s20
	s_cselect_b32 s55, s15, s76
	s_cselect_b32 s54, s74, s75
	v_lshl_add_u64 v[144:145], s[52:53], 0, v[140:141]
	s_add_i32 m0, s62, 0xc000
	ds_read_b128 v[196:199], v158
	ds_read_b128 v[200:203], v158 offset:1024
	ds_read_b128 v[204:207], v158 offset:2048
	ds_read_b128 v[208:211], v158 offset:3072
	ds_read_b128 v[212:215], v158 offset:4096
	ds_read_b128 v[216:219], v158 offset:5120
	ds_read_b128 v[220:223], v158 offset:6144
	ds_read_b128 v[224:227], v158 offset:7168
	global_load_lds_dwordx4 v[144:145], off
	v_lshl_add_u64 v[144:145], s[52:53], 0, v[142:143]
	s_add_i32 m0, s62, 0xe000
	s_nop 0
	global_load_lds_dwordx4 v[144:145], off
	s_waitcnt vmcnt(8)
	s_waitcnt lgkmcnt(0)
	s_barrier
	s_setprio 1
	s_waitcnt lgkmcnt(0)
	v_mfma_f32_16x16x32_bf16 v[126:129], v[160:163], v[196:199], v[126:129]
	v_mfma_f32_16x16x32_bf16 v[126:129], v[164:167], v[200:203], v[126:129]
	v_mfma_f32_16x16x32_bf16 v[118:121], v[172:175], v[196:199], v[118:121]
	v_mfma_f32_16x16x32_bf16 v[118:121], v[176:179], v[200:203], v[118:121]
	v_mfma_f32_16x16x32_bf16 v[106:109], v[172:175], v[204:207], v[106:109]
	v_mfma_f32_16x16x32_bf16 v[106:109], v[176:179], v[208:211], v[106:109]
	v_mfma_f32_16x16x32_bf16 v[110:113], v[160:163], v[204:207], v[110:113]
	v_mfma_f32_16x16x32_bf16 v[110:113], v[164:167], v[208:211], v[110:113]
	v_mfma_f32_16x16x32_bf16 v[94:97], v[160:163], v[212:215], v[94:97]
	v_mfma_f32_16x16x32_bf16 v[94:97], v[164:167], v[216:219], v[94:97]
	v_mfma_f32_16x16x32_bf16 v[90:93], v[172:175], v[212:215], v[90:93]
	v_mfma_f32_16x16x32_bf16 v[90:93], v[176:179], v[216:219], v[90:93]
	v_mfma_f32_16x16x32_bf16 v[74:77], v[172:175], v[220:223], v[74:77]
	v_mfma_f32_16x16x32_bf16 v[74:77], v[176:179], v[224:227], v[74:77]
	v_mfma_f32_16x16x32_bf16 v[78:81], v[160:163], v[220:223], v[78:81]
	v_mfma_f32_16x16x32_bf16 v[78:81], v[164:167], v[224:227], v[78:81]
	s_setprio 0
	s_setprio 1
	v_mfma_f32_16x16x32_bf16 v[122:125], v[180:183], v[196:199], v[122:125]
	v_mfma_f32_16x16x32_bf16 v[122:125], v[184:187], v[200:203], v[122:125]
	v_mfma_f32_16x16x32_bf16 v[114:117], v[188:191], v[196:199], v[114:117]
	v_mfma_f32_16x16x32_bf16 v[114:117], v[192:195], v[200:203], v[114:117]
	v_mfma_f32_16x16x32_bf16 v[98:101], v[188:191], v[204:207], v[98:101]
	v_mfma_f32_16x16x32_bf16 v[98:101], v[192:195], v[208:211], v[98:101]
	v_mfma_f32_16x16x32_bf16 v[102:105], v[180:183], v[204:207], v[102:105]
	v_mfma_f32_16x16x32_bf16 v[102:105], v[184:187], v[208:211], v[102:105]
	v_mfma_f32_16x16x32_bf16 v[86:89], v[180:183], v[212:215], v[86:89]
	v_mfma_f32_16x16x32_bf16 v[86:89], v[184:187], v[216:219], v[86:89]
	v_mfma_f32_16x16x32_bf16 v[82:85], v[188:191], v[212:215], v[82:85]
	v_mfma_f32_16x16x32_bf16 v[82:85], v[192:195], v[216:219], v[82:85]
	v_mfma_f32_16x16x32_bf16 v[66:69], v[188:191], v[220:223], v[66:69]
	v_mfma_f32_16x16x32_bf16 v[66:69], v[192:195], v[224:227], v[66:69]
	v_mfma_f32_16x16x32_bf16 v[70:73], v[180:183], v[220:223], v[70:73]
	v_mfma_f32_16x16x32_bf16 v[70:73], v[184:187], v[224:227], v[70:73]
	s_setprio 0
	s_barrier
	s_add_i32 s20, s72, s33
	v_lshl_add_u64 v[144:145], s[54:55], 0, v[132:133]
	s_mov_b32 m0, s20
	ds_read_b128 v[196:199], v158 offset:16384
	ds_read_b128 v[200:203], v158 offset:17408
	ds_read_b128 v[204:207], v158 offset:18432
	ds_read_b128 v[208:211], v158 offset:19456
	ds_read_b128 v[212:215], v158 offset:20480
	ds_read_b128 v[216:219], v158 offset:21504
	ds_read_b128 v[220:223], v158 offset:22528
	ds_read_b128 v[224:227], v158 offset:23552
	global_load_lds_dwordx4 v[144:145], off
	s_add_i32 m0, s20, 0x2000
	s_add_u32 s20, s54, 0x100000
	v_lshl_add_u64 v[168:169], s[54:55], 0, v[136:137]
	s_addc_u32 s21, s55, 0
	s_add_i32 s22, s73, s33
	global_load_lds_dwordx4 v[168:169], off
	v_lshl_add_u64 v[228:229], s[20:21], 0, v[132:133]
	s_mov_b32 m0, s22
	v_lshl_add_u64 v[230:231], s[56:57], 0, v[134:135]
	global_load_lds_dwordx4 v[228:229], off
	v_lshl_add_u64 v[228:229], s[20:21], 0, v[136:137]
	s_add_i32 m0, s22, 0x2000
	s_nop 0
	global_load_lds_dwordx4 v[228:229], off
	v_lshl_add_u64 v[228:229], s[56:57], 0, v[130:131]
	s_mov_b32 m0, s62
	s_nop 0
	global_load_lds_dwordx4 v[228:229], off
	s_mov_b32 m0, s63
	s_nop 0
	global_load_lds_dwordx4 v[230:231], off
	s_waitcnt vmcnt(8)
	s_waitcnt lgkmcnt(0)
	s_barrier
	s_setprio 1
	s_waitcnt lgkmcnt(0)
	v_mfma_f32_16x16x32_bf16 v[62:65], v[160:163], v[196:199], v[62:65]
	v_mfma_f32_16x16x32_bf16 v[62:65], v[164:167], v[200:203], v[62:65]
	v_mfma_f32_16x16x32_bf16 v[58:61], v[172:175], v[196:199], v[58:61]
	v_mfma_f32_16x16x32_bf16 v[58:61], v[176:179], v[200:203], v[58:61]
	v_mfma_f32_16x16x32_bf16 v[42:45], v[172:175], v[204:207], v[42:45]
	v_mfma_f32_16x16x32_bf16 v[42:45], v[176:179], v[208:211], v[42:45]
	v_mfma_f32_16x16x32_bf16 v[50:53], v[160:163], v[204:207], v[50:53]
	v_mfma_f32_16x16x32_bf16 v[50:53], v[164:167], v[208:211], v[50:53]
	v_mfma_f32_16x16x32_bf16 v[34:37], v[160:163], v[212:215], v[34:37]
	v_mfma_f32_16x16x32_bf16 v[34:37], v[164:167], v[216:219], v[34:37]
	v_mfma_f32_16x16x32_bf16 v[26:29], v[172:175], v[212:215], v[26:29]
	v_mfma_f32_16x16x32_bf16 v[26:29], v[176:179], v[216:219], v[26:29]
	v_mfma_f32_16x16x32_bf16 v[6:9], v[172:175], v[220:223], v[6:9]
	v_mfma_f32_16x16x32_bf16 v[6:9], v[176:179], v[224:227], v[6:9]
	v_mfma_f32_16x16x32_bf16 v[14:17], v[160:163], v[220:223], v[14:17]
	v_mfma_f32_16x16x32_bf16 v[14:17], v[164:167], v[224:227], v[14:17]
	s_setprio 0
	s_setprio 1
	v_mfma_f32_16x16x32_bf16 v[54:57], v[180:183], v[196:199], v[54:57]
	v_mfma_f32_16x16x32_bf16 v[54:57], v[184:187], v[200:203], v[54:57]
	v_mfma_f32_16x16x32_bf16 v[46:49], v[188:191], v[196:199], v[46:49]
	v_mfma_f32_16x16x32_bf16 v[46:49], v[192:195], v[200:203], v[46:49]
	v_mfma_f32_16x16x32_bf16 v[30:33], v[188:191], v[204:207], v[30:33]
	v_mfma_f32_16x16x32_bf16 v[30:33], v[192:195], v[208:211], v[30:33]
	v_mfma_f32_16x16x32_bf16 v[38:41], v[180:183], v[204:207], v[38:41]
	v_mfma_f32_16x16x32_bf16 v[38:41], v[184:187], v[208:211], v[38:41]
	v_mfma_f32_16x16x32_bf16 v[22:25], v[180:183], v[212:215], v[22:25]
	v_mfma_f32_16x16x32_bf16 v[22:25], v[184:187], v[216:219], v[22:25]
	v_mfma_f32_16x16x32_bf16 v[18:21], v[188:191], v[212:215], v[18:21]
	v_mfma_f32_16x16x32_bf16 v[18:21], v[192:195], v[216:219], v[18:21]
	v_mfma_f32_16x16x32_bf16 v[2:5], v[188:191], v[220:223], v[2:5]
	v_mfma_f32_16x16x32_bf16 v[2:5], v[192:195], v[224:227], v[2:5]
	v_mfma_f32_16x16x32_bf16 v[10:13], v[180:183], v[220:223], v[10:13]
	v_mfma_f32_16x16x32_bf16 v[10:13], v[184:187], v[224:227], v[10:13]
	s_setprio 0
	s_barrier
	s_add_i32 s22, 0, 0x18000
	v_add_u32_e32 v159, s22, v150
	s_add_i32 s23, 0, 0x1c000
	ds_read_b128 v[160:163], v159
	ds_read_b128 v[164:167], v159 offset:1024
	ds_read_b128 v[172:175], v159 offset:2048
	ds_read_b128 v[176:179], v159 offset:3072
	v_add_u32_e32 v159, s23, v150
	ds_read_b128 v[180:183], v159
	ds_read_b128 v[184:187], v159 offset:1024
	ds_read_b128 v[188:191], v159 offset:2048
	ds_read_b128 v[192:195], v159 offset:3072
	s_add_u32 s20, s56, 0x100000
	s_addc_u32 s21, s57, 0
	s_mov_b32 m0, s64
	v_lshl_add_u64 v[232:233], s[20:21], 0, v[130:131]
	ds_read_b128 v[196:199], v158 offset:32768
	ds_read_b128 v[200:203], v158 offset:33792
	ds_read_b128 v[204:207], v158 offset:34816
	ds_read_b128 v[208:211], v158 offset:35840
	ds_read_b128 v[212:215], v158 offset:36864
	ds_read_b128 v[216:219], v158 offset:37888
	ds_read_b128 v[220:223], v158 offset:38912
	ds_read_b128 v[224:227], v158 offset:39936
	global_load_lds_dwordx4 v[232:233], off
	v_lshl_add_u64 v[232:233], s[20:21], 0, v[134:135]
	s_mov_b32 m0, s65
	s_nop 0
	global_load_lds_dwordx4 v[232:233], off
	s_waitcnt vmcnt(8)
	s_waitcnt lgkmcnt(0)
	s_barrier
	s_setprio 1
	s_waitcnt lgkmcnt(0)
	v_mfma_f32_16x16x32_bf16 v[126:129], v[160:163], v[196:199], v[126:129]
	v_mfma_f32_16x16x32_bf16 v[126:129], v[164:167], v[200:203], v[126:129]
	v_mfma_f32_16x16x32_bf16 v[118:121], v[172:175], v[196:199], v[118:121]
	v_mfma_f32_16x16x32_bf16 v[118:121], v[176:179], v[200:203], v[118:121]
	v_mfma_f32_16x16x32_bf16 v[106:109], v[172:175], v[204:207], v[106:109]
	v_mfma_f32_16x16x32_bf16 v[106:109], v[176:179], v[208:211], v[106:109]
	v_mfma_f32_16x16x32_bf16 v[110:113], v[160:163], v[204:207], v[110:113]
	v_mfma_f32_16x16x32_bf16 v[110:113], v[164:167], v[208:211], v[110:113]
	v_mfma_f32_16x16x32_bf16 v[94:97], v[160:163], v[212:215], v[94:97]
	v_mfma_f32_16x16x32_bf16 v[94:97], v[164:167], v[216:219], v[94:97]
	v_mfma_f32_16x16x32_bf16 v[90:93], v[172:175], v[212:215], v[90:93]
	v_mfma_f32_16x16x32_bf16 v[90:93], v[176:179], v[216:219], v[90:93]
	v_mfma_f32_16x16x32_bf16 v[74:77], v[172:175], v[220:223], v[74:77]
	v_mfma_f32_16x16x32_bf16 v[74:77], v[176:179], v[224:227], v[74:77]
	v_mfma_f32_16x16x32_bf16 v[78:81], v[160:163], v[220:223], v[78:81]
	v_mfma_f32_16x16x32_bf16 v[78:81], v[164:167], v[224:227], v[78:81]
	s_setprio 0
	s_setprio 1
	v_mfma_f32_16x16x32_bf16 v[122:125], v[180:183], v[196:199], v[122:125]
	v_mfma_f32_16x16x32_bf16 v[122:125], v[184:187], v[200:203], v[122:125]
	v_mfma_f32_16x16x32_bf16 v[114:117], v[188:191], v[196:199], v[114:117]
	v_mfma_f32_16x16x32_bf16 v[114:117], v[192:195], v[200:203], v[114:117]
	v_mfma_f32_16x16x32_bf16 v[98:101], v[188:191], v[204:207], v[98:101]
	v_mfma_f32_16x16x32_bf16 v[98:101], v[192:195], v[208:211], v[98:101]
	v_mfma_f32_16x16x32_bf16 v[102:105], v[180:183], v[204:207], v[102:105]
	v_mfma_f32_16x16x32_bf16 v[102:105], v[184:187], v[208:211], v[102:105]
	v_mfma_f32_16x16x32_bf16 v[86:89], v[180:183], v[212:215], v[86:89]
	v_mfma_f32_16x16x32_bf16 v[86:89], v[184:187], v[216:219], v[86:89]
	v_mfma_f32_16x16x32_bf16 v[82:85], v[188:191], v[212:215], v[82:85]
	v_mfma_f32_16x16x32_bf16 v[82:85], v[192:195], v[216:219], v[82:85]
	v_mfma_f32_16x16x32_bf16 v[66:69], v[188:191], v[220:223], v[66:69]
	v_mfma_f32_16x16x32_bf16 v[66:69], v[192:195], v[224:227], v[66:69]
	v_mfma_f32_16x16x32_bf16 v[70:73], v[180:183], v[220:223], v[70:73]
	v_mfma_f32_16x16x32_bf16 v[70:73], v[184:187], v[224:227], v[70:73]
	s_setprio 0
	s_barrier
	s_add_i32 s20, s22, s33
	v_lshl_add_u64 v[144:145], v[144:145], 0, s[8:9]
	s_mov_b32 m0, s20
	ds_read_b128 v[196:199], v158 offset:49152
	ds_read_b128 v[200:203], v158 offset:50176
	ds_read_b128 v[204:207], v158 offset:51200
	ds_read_b128 v[208:211], v158 offset:52224
	ds_read_b128 v[212:215], v158 offset:53248
	ds_read_b128 v[216:219], v158 offset:54272
	ds_read_b128 v[220:223], v158 offset:55296
	ds_read_b128 v[224:227], v158 offset:56320
	global_load_lds_dwordx4 v[144:145], off
	s_add_i32 m0, s20, 0x2000
	s_add_u32 s20, s54, 0x100080
	v_lshl_add_u64 v[144:145], v[168:169], 0, s[8:9]
	s_addc_u32 s21, s55, 0
	s_add_i32 s22, s23, s33
	global_load_lds_dwordx4 v[144:145], off
	v_lshl_add_u64 v[144:145], s[20:21], 0, v[132:133]
	s_mov_b32 m0, s22
	s_nop 0
	global_load_lds_dwordx4 v[144:145], off
	v_lshl_add_u64 v[144:145], s[20:21], 0, v[136:137]
	s_add_i32 m0, s22, 0x2000
	s_nop 0
	global_load_lds_dwordx4 v[144:145], off
	v_lshl_add_u64 v[144:145], v[228:229], 0, s[8:9]
	s_mov_b32 m0, s66
	s_nop 0
	global_load_lds_dwordx4 v[144:145], off
	v_lshl_add_u64 v[144:145], v[230:231], 0, s[8:9]
	s_mov_b32 m0, s67
	s_nop 0
	global_load_lds_dwordx4 v[144:145], off
	s_waitcnt vmcnt(8)
	s_waitcnt lgkmcnt(0)
	s_barrier
	s_setprio 1
	s_waitcnt lgkmcnt(0)
	v_mfma_f32_16x16x32_bf16 v[62:65], v[160:163], v[196:199], v[62:65]
	v_mfma_f32_16x16x32_bf16 v[62:65], v[164:167], v[200:203], v[62:65]
	v_mfma_f32_16x16x32_bf16 v[58:61], v[172:175], v[196:199], v[58:61]
	v_mfma_f32_16x16x32_bf16 v[58:61], v[176:179], v[200:203], v[58:61]
	v_mfma_f32_16x16x32_bf16 v[42:45], v[172:175], v[204:207], v[42:45]
	v_mfma_f32_16x16x32_bf16 v[42:45], v[176:179], v[208:211], v[42:45]
	v_mfma_f32_16x16x32_bf16 v[50:53], v[160:163], v[204:207], v[50:53]
	v_mfma_f32_16x16x32_bf16 v[50:53], v[164:167], v[208:211], v[50:53]
	v_mfma_f32_16x16x32_bf16 v[34:37], v[160:163], v[212:215], v[34:37]
	v_mfma_f32_16x16x32_bf16 v[34:37], v[164:167], v[216:219], v[34:37]
	v_mfma_f32_16x16x32_bf16 v[26:29], v[172:175], v[212:215], v[26:29]
	v_mfma_f32_16x16x32_bf16 v[26:29], v[176:179], v[216:219], v[26:29]
	v_mfma_f32_16x16x32_bf16 v[6:9], v[172:175], v[220:223], v[6:9]
	v_mfma_f32_16x16x32_bf16 v[6:9], v[176:179], v[224:227], v[6:9]
	v_mfma_f32_16x16x32_bf16 v[14:17], v[160:163], v[220:223], v[14:17]
	v_mfma_f32_16x16x32_bf16 v[14:17], v[164:167], v[224:227], v[14:17]
	s_setprio 0
	s_setprio 1
	v_mfma_f32_16x16x32_bf16 v[54:57], v[180:183], v[196:199], v[54:57]
	v_mfma_f32_16x16x32_bf16 v[54:57], v[184:187], v[200:203], v[54:57]
	v_mfma_f32_16x16x32_bf16 v[46:49], v[188:191], v[196:199], v[46:49]
	v_mfma_f32_16x16x32_bf16 v[46:49], v[192:195], v[200:203], v[46:49]
	v_mfma_f32_16x16x32_bf16 v[30:33], v[188:191], v[204:207], v[30:33]
	v_mfma_f32_16x16x32_bf16 v[30:33], v[192:195], v[208:211], v[30:33]
	v_mfma_f32_16x16x32_bf16 v[38:41], v[180:183], v[204:207], v[38:41]
	v_mfma_f32_16x16x32_bf16 v[38:41], v[184:187], v[208:211], v[38:41]
	v_mfma_f32_16x16x32_bf16 v[22:25], v[180:183], v[212:215], v[22:25]
	v_mfma_f32_16x16x32_bf16 v[22:25], v[184:187], v[216:219], v[22:25]
	v_mfma_f32_16x16x32_bf16 v[18:21], v[188:191], v[212:215], v[18:21]
	v_mfma_f32_16x16x32_bf16 v[18:21], v[192:195], v[216:219], v[18:21]
	v_mfma_f32_16x16x32_bf16 v[2:5], v[188:191], v[220:223], v[2:5]
	v_mfma_f32_16x16x32_bf16 v[2:5], v[192:195], v[224:227], v[2:5]
	v_mfma_f32_16x16x32_bf16 v[10:13], v[180:183], v[220:223], v[10:13]
	v_mfma_f32_16x16x32_bf16 v[10:13], v[184:187], v[224:227], v[10:13]
	s_setprio 0
	s_barrier
	s_add_i32 s77, s77, 2
	s_add_u32 s52, s52, 0x100
	s_addc_u32 s53, s53, 0
	s_add_u32 s75, s75, 0x100
	s_addc_u32 s76, s76, 0
	s_cmp_gt_u32 s77, 61
	s_cbranch_scc0 .LBB0_211
	s_and_b64 vcc, exec, s[10:11]
	s_cbranch_vccz .LBB0_214
	s_barrier

.LBB0_232:
	s_add_u32 s20, s2, 0xfff00080
	s_addc_u32 s21, s3, -1
	s_add_i32 s22, 0, 0x10000
	v_add_u32_e32 v168, s22, v143
	ds_read_b128 v[156:159], v168
	ds_read_b128 v[160:163], v168 offset:1024
	ds_read_b128 v[164:167], v168 offset:2048
	ds_read_b128 v[174:177], v168 offset:3072
	ds_read_b128 v[178:181], v172
	ds_read_b128 v[182:185], v172 offset:1024
	ds_read_b128 v[186:189], v172 offset:2048
	ds_read_b128 v[190:193], v172 offset:3072
	s_cmp_eq_u32 s79, 60
	s_cselect_b32 s57, s39, s21
	s_cselect_b32 s56, s58, s20
	s_cselect_b32 s53, s31, s78
	s_cselect_b32 s52, s59, s77
	v_lshl_add_u64 v[168:169], s[2:3], 0, v[152:153]
	s_add_i32 m0, s64, 0xc000
	ds_read_b128 v[194:197], v173
	ds_read_b128 v[198:201], v173 offset:1024
	ds_read_b128 v[202:205], v173 offset:2048
	ds_read_b128 v[206:209], v173 offset:3072
	ds_read_b128 v[210:213], v173 offset:4096
	ds_read_b128 v[214:217], v173 offset:5120
	ds_read_b128 v[218:221], v173 offset:6144
	ds_read_b128 v[222:225], v173 offset:7168
	global_load_lds_dwordx4 v[168:169], off
	v_lshl_add_u64 v[168:169], s[2:3], 0, v[154:155]
	s_add_i32 m0, s64, 0xe000
	s_nop 0
	global_load_lds_dwordx4 v[168:169], off
	s_waitcnt vmcnt(8)
	s_waitcnt lgkmcnt(0)
	s_barrier
	s_setprio 1
	s_waitcnt lgkmcnt(0)
	v_mfma_f32_16x16x32_bf16 v[126:129], v[156:159], v[194:197], v[126:129]
	v_mfma_f32_16x16x32_bf16 v[126:129], v[160:163], v[198:201], v[126:129]
	v_mfma_f32_16x16x32_bf16 v[122:125], v[164:167], v[194:197], v[122:125]
	v_mfma_f32_16x16x32_bf16 v[122:125], v[174:177], v[198:201], v[122:125]
	v_mfma_f32_16x16x32_bf16 v[106:109], v[164:167], v[202:205], v[106:109]
	v_mfma_f32_16x16x32_bf16 v[106:109], v[174:177], v[206:209], v[106:109]
	v_mfma_f32_16x16x32_bf16 v[110:113], v[156:159], v[202:205], v[110:113]
	v_mfma_f32_16x16x32_bf16 v[110:113], v[160:163], v[206:209], v[110:113]
	v_mfma_f32_16x16x32_bf16 v[94:97], v[156:159], v[210:213], v[94:97]
	v_mfma_f32_16x16x32_bf16 v[94:97], v[160:163], v[214:217], v[94:97]
	v_mfma_f32_16x16x32_bf16 v[90:93], v[164:167], v[210:213], v[90:93]
	v_mfma_f32_16x16x32_bf16 v[90:93], v[174:177], v[214:217], v[90:93]
	v_mfma_f32_16x16x32_bf16 v[74:77], v[164:167], v[218:221], v[74:77]
	v_mfma_f32_16x16x32_bf16 v[74:77], v[174:177], v[222:225], v[74:77]
	v_mfma_f32_16x16x32_bf16 v[78:81], v[156:159], v[218:221], v[78:81]
	v_mfma_f32_16x16x32_bf16 v[78:81], v[160:163], v[222:225], v[78:81]
	s_setprio 0
	s_setprio 1
	v_mfma_f32_16x16x32_bf16 v[118:121], v[178:181], v[194:197], v[118:121]
	v_mfma_f32_16x16x32_bf16 v[118:121], v[182:185], v[198:201], v[118:121]
	v_mfma_f32_16x16x32_bf16 v[114:117], v[186:189], v[194:197], v[114:117]
	v_mfma_f32_16x16x32_bf16 v[114:117], v[190:193], v[198:201], v[114:117]
	v_mfma_f32_16x16x32_bf16 v[98:101], v[186:189], v[202:205], v[98:101]
	v_mfma_f32_16x16x32_bf16 v[98:101], v[190:193], v[206:209], v[98:101]
	v_mfma_f32_16x16x32_bf16 v[102:105], v[178:181], v[202:205], v[102:105]
	v_mfma_f32_16x16x32_bf16 v[102:105], v[182:185], v[206:209], v[102:105]
	v_mfma_f32_16x16x32_bf16 v[86:89], v[178:181], v[210:213], v[86:89]
	v_mfma_f32_16x16x32_bf16 v[86:89], v[182:185], v[214:217], v[86:89]
	v_mfma_f32_16x16x32_bf16 v[82:85], v[186:189], v[210:213], v[82:85]
	v_mfma_f32_16x16x32_bf16 v[82:85], v[190:193], v[214:217], v[82:85]
	v_mfma_f32_16x16x32_bf16 v[66:69], v[186:189], v[218:221], v[66:69]
	v_mfma_f32_16x16x32_bf16 v[66:69], v[190:193], v[222:225], v[66:69]
	v_mfma_f32_16x16x32_bf16 v[70:73], v[178:181], v[218:221], v[70:73]
	v_mfma_f32_16x16x32_bf16 v[70:73], v[182:185], v[222:225], v[70:73]
	s_setprio 0
	s_barrier
	s_add_i32 s20, s22, s63
	v_lshl_add_u64 v[168:169], s[52:53], 0, v[132:133]
	s_mov_b32 m0, s20
	ds_read_b128 v[194:197], v173 offset:16384
	ds_read_b128 v[198:201], v173 offset:17408
	ds_read_b128 v[202:205], v173 offset:18432
	ds_read_b128 v[206:209], v173 offset:19456
	ds_read_b128 v[210:213], v173 offset:20480
	ds_read_b128 v[214:217], v173 offset:21504
	ds_read_b128 v[218:221], v173 offset:22528
	ds_read_b128 v[222:225], v173 offset:23552
	global_load_lds_dwordx4 v[168:169], off
	s_add_i32 m0, s20, 0x2000
	s_add_u32 s20, s52, 0x100000
	v_lshl_add_u64 v[226:227], s[52:53], 0, v[136:137]
	s_addc_u32 s21, s53, 0
	s_add_i32 s22, s73, s63
	global_load_lds_dwordx4 v[226:227], off
	v_lshl_add_u64 v[228:229], s[20:21], 0, v[132:133]
	s_mov_b32 m0, s22
	v_lshl_add_u64 v[230:231], s[56:57], 0, v[134:135]
	global_load_lds_dwordx4 v[228:229], off
	v_lshl_add_u64 v[228:229], s[20:21], 0, v[136:137]
	s_add_i32 m0, s22, 0x2000
	s_nop 0
	global_load_lds_dwordx4 v[228:229], off
	v_lshl_add_u64 v[228:229], s[56:57], 0, v[130:131]
	s_mov_b32 m0, s64
	s_nop 0
	global_load_lds_dwordx4 v[228:229], off
	s_mov_b32 m0, s65
	s_nop 0
	global_load_lds_dwordx4 v[230:231], off
	s_waitcnt vmcnt(8)
	s_waitcnt lgkmcnt(0)
	s_barrier
	s_setprio 1
	s_waitcnt lgkmcnt(0)
	v_mfma_f32_16x16x32_bf16 v[62:65], v[156:159], v[194:197], v[62:65]
	v_mfma_f32_16x16x32_bf16 v[62:65], v[160:163], v[198:201], v[62:65]
	v_mfma_f32_16x16x32_bf16 v[58:61], v[164:167], v[194:197], v[58:61]
	v_mfma_f32_16x16x32_bf16 v[58:61], v[174:177], v[198:201], v[58:61]
	v_mfma_f32_16x16x32_bf16 v[42:45], v[164:167], v[202:205], v[42:45]
	v_mfma_f32_16x16x32_bf16 v[42:45], v[174:177], v[206:209], v[42:45]
	v_mfma_f32_16x16x32_bf16 v[46:49], v[156:159], v[202:205], v[46:49]
	v_mfma_f32_16x16x32_bf16 v[46:49], v[160:163], v[206:209], v[46:49]
	v_mfma_f32_16x16x32_bf16 v[30:33], v[156:159], v[210:213], v[30:33]
	v_mfma_f32_16x16x32_bf16 v[30:33], v[160:163], v[214:217], v[30:33]
	v_mfma_f32_16x16x32_bf16 v[26:29], v[164:167], v[210:213], v[26:29]
	v_mfma_f32_16x16x32_bf16 v[26:29], v[174:177], v[214:217], v[26:29]
	v_mfma_f32_16x16x32_bf16 v[10:13], v[164:167], v[218:221], v[10:13]
	v_mfma_f32_16x16x32_bf16 v[10:13], v[174:177], v[222:225], v[10:13]
	v_mfma_f32_16x16x32_bf16 v[14:17], v[156:159], v[218:221], v[14:17]
	v_mfma_f32_16x16x32_bf16 v[14:17], v[160:163], v[222:225], v[14:17]
	s_setprio 0
	s_setprio 1
	v_mfma_f32_16x16x32_bf16 v[54:57], v[178:181], v[194:197], v[54:57]
	v_mfma_f32_16x16x32_bf16 v[54:57], v[182:185], v[198:201], v[54:57]
	v_mfma_f32_16x16x32_bf16 v[50:53], v[186:189], v[194:197], v[50:53]
	v_mfma_f32_16x16x32_bf16 v[50:53], v[190:193], v[198:201], v[50:53]
	v_mfma_f32_16x16x32_bf16 v[34:37], v[186:189], v[202:205], v[34:37]
	v_mfma_f32_16x16x32_bf16 v[34:37], v[190:193], v[206:209], v[34:37]
	v_mfma_f32_16x16x32_bf16 v[38:41], v[178:181], v[202:205], v[38:41]
	v_mfma_f32_16x16x32_bf16 v[38:41], v[182:185], v[206:209], v[38:41]
	v_mfma_f32_16x16x32_bf16 v[22:25], v[178:181], v[210:213], v[22:25]
	v_mfma_f32_16x16x32_bf16 v[22:25], v[182:185], v[214:217], v[22:25]
	v_mfma_f32_16x16x32_bf16 v[18:21], v[186:189], v[210:213], v[18:21]
	v_mfma_f32_16x16x32_bf16 v[18:21], v[190:193], v[214:217], v[18:21]
	v_mfma_f32_16x16x32_bf16 v[2:5], v[186:189], v[218:221], v[2:5]
	v_mfma_f32_16x16x32_bf16 v[2:5], v[190:193], v[222:225], v[2:5]
	v_mfma_f32_16x16x32_bf16 v[6:9], v[178:181], v[218:221], v[6:9]
	v_mfma_f32_16x16x32_bf16 v[6:9], v[182:185], v[222:225], v[6:9]
	s_setprio 0
	s_barrier
	s_add_i32 s22, 0, 0x18000
	s_add_i32 s23, 0, 0x1c000
	v_add_u32_e32 v174, s22, v143
	v_add_u32_e32 v190, s23, v143
	ds_read_b128 v[156:159], v174
	ds_read_b128 v[160:163], v174 offset:1024
	ds_read_b128 v[164:167], v174 offset:2048
	ds_read_b128 v[174:177], v174 offset:3072
	ds_read_b128 v[178:181], v190
	ds_read_b128 v[182:185], v190 offset:1024
	ds_read_b128 v[186:189], v190 offset:2048
	ds_read_b128 v[190:193], v190 offset:3072
	s_add_u32 s20, s56, 0x100000
	s_addc_u32 s21, s57, 0
	s_mov_b32 m0, s66
	v_lshl_add_u64 v[232:233], s[20:21], 0, v[130:131]
	ds_read_b128 v[194:197], v173 offset:32768
	ds_read_b128 v[198:201], v173 offset:33792
	ds_read_b128 v[202:205], v173 offset:34816
	ds_read_b128 v[206:209], v173 offset:35840
	ds_read_b128 v[210:213], v173 offset:36864
	ds_read_b128 v[214:217], v173 offset:37888
	ds_read_b128 v[218:221], v173 offset:38912
	ds_read_b128 v[222:225], v173 offset:39936
	global_load_lds_dwordx4 v[232:233], off
	v_lshl_add_u64 v[232:233], s[20:21], 0, v[134:135]
	s_mov_b32 m0, s67
	s_nop 0
	global_load_lds_dwordx4 v[232:233], off
	s_waitcnt vmcnt(8)
	s_waitcnt lgkmcnt(0)
	s_barrier
	s_setprio 1
	s_waitcnt lgkmcnt(0)
	v_mfma_f32_16x16x32_bf16 v[126:129], v[156:159], v[194:197], v[126:129]
	v_mfma_f32_16x16x32_bf16 v[126:129], v[160:163], v[198:201], v[126:129]
	v_mfma_f32_16x16x32_bf16 v[122:125], v[164:167], v[194:197], v[122:125]
	v_mfma_f32_16x16x32_bf16 v[122:125], v[174:177], v[198:201], v[122:125]
	v_mfma_f32_16x16x32_bf16 v[106:109], v[164:167], v[202:205], v[106:109]
	v_mfma_f32_16x16x32_bf16 v[106:109], v[174:177], v[206:209], v[106:109]
	v_mfma_f32_16x16x32_bf16 v[110:113], v[156:159], v[202:205], v[110:113]
	v_mfma_f32_16x16x32_bf16 v[110:113], v[160:163], v[206:209], v[110:113]
	v_mfma_f32_16x16x32_bf16 v[94:97], v[156:159], v[210:213], v[94:97]
	v_mfma_f32_16x16x32_bf16 v[94:97], v[160:163], v[214:217], v[94:97]
	v_mfma_f32_16x16x32_bf16 v[90:93], v[164:167], v[210:213], v[90:93]
	v_mfma_f32_16x16x32_bf16 v[90:93], v[174:177], v[214:217], v[90:93]
	v_mfma_f32_16x16x32_bf16 v[74:77], v[164:167], v[218:221], v[74:77]
	v_mfma_f32_16x16x32_bf16 v[74:77], v[174:177], v[222:225], v[74:77]
	v_mfma_f32_16x16x32_bf16 v[78:81], v[156:159], v[218:221], v[78:81]
	v_mfma_f32_16x16x32_bf16 v[78:81], v[160:163], v[222:225], v[78:81]
	s_setprio 0
	s_setprio 1
	v_mfma_f32_16x16x32_bf16 v[118:121], v[178:181], v[194:197], v[118:121]
	v_mfma_f32_16x16x32_bf16 v[118:121], v[182:185], v[198:201], v[118:121]
	v_mfma_f32_16x16x32_bf16 v[114:117], v[186:189], v[194:197], v[114:117]
	v_mfma_f32_16x16x32_bf16 v[114:117], v[190:193], v[198:201], v[114:117]
	v_mfma_f32_16x16x32_bf16 v[98:101], v[186:189], v[202:205], v[98:101]
	v_mfma_f32_16x16x32_bf16 v[98:101], v[190:193], v[206:209], v[98:101]
	v_mfma_f32_16x16x32_bf16 v[102:105], v[178:181], v[202:205], v[102:105]
	v_mfma_f32_16x16x32_bf16 v[102:105], v[182:185], v[206:209], v[102:105]
	v_mfma_f32_16x16x32_bf16 v[86:89], v[178:181], v[210:213], v[86:89]
	v_mfma_f32_16x16x32_bf16 v[86:89], v[182:185], v[214:217], v[86:89]
	v_mfma_f32_16x16x32_bf16 v[82:85], v[186:189], v[210:213], v[82:85]
	v_mfma_f32_16x16x32_bf16 v[82:85], v[190:193], v[214:217], v[82:85]
	v_mfma_f32_16x16x32_bf16 v[66:69], v[186:189], v[218:221], v[66:69]
	v_mfma_f32_16x16x32_bf16 v[66:69], v[190:193], v[222:225], v[66:69]
	v_mfma_f32_16x16x32_bf16 v[70:73], v[178:181], v[218:221], v[70:73]
	v_mfma_f32_16x16x32_bf16 v[70:73], v[182:185], v[222:225], v[70:73]
	s_setprio 0
	s_barrier
	s_add_i32 s20, s22, s63
	v_lshl_add_u64 v[168:169], v[168:169], 0, s[14:15]
	s_mov_b32 m0, s20
	ds_read_b128 v[194:197], v173 offset:49152
	ds_read_b128 v[198:201], v173 offset:50176
	ds_read_b128 v[202:205], v173 offset:51200
	ds_read_b128 v[206:209], v173 offset:52224
	ds_read_b128 v[210:213], v173 offset:53248
	ds_read_b128 v[214:217], v173 offset:54272
	ds_read_b128 v[218:221], v173 offset:55296
	ds_read_b128 v[222:225], v173 offset:56320
	global_load_lds_dwordx4 v[168:169], off
	s_add_i32 m0, s20, 0x2000
	s_add_u32 s20, s52, 0x100080
	v_lshl_add_u64 v[168:169], v[226:227], 0, s[14:15]
	s_addc_u32 s21, s53, 0
	s_add_i32 s22, s23, s63
	global_load_lds_dwordx4 v[168:169], off
	v_lshl_add_u64 v[168:169], s[20:21], 0, v[132:133]
	s_mov_b32 m0, s22
	s_nop 0
	global_load_lds_dwordx4 v[168:169], off
	v_lshl_add_u64 v[168:169], s[20:21], 0, v[136:137]
	s_add_i32 m0, s22, 0x2000
	s_nop 0
	global_load_lds_dwordx4 v[168:169], off
	v_lshl_add_u64 v[168:169], v[228:229], 0, s[14:15]
	s_mov_b32 m0, s70
	s_nop 0
	global_load_lds_dwordx4 v[168:169], off
	v_lshl_add_u64 v[168:169], v[230:231], 0, s[14:15]
	s_mov_b32 m0, s71
	s_nop 0
	global_load_lds_dwordx4 v[168:169], off
	s_waitcnt vmcnt(8)
	s_waitcnt lgkmcnt(0)
	s_barrier
	s_setprio 1
	s_waitcnt lgkmcnt(0)
	v_mfma_f32_16x16x32_bf16 v[62:65], v[156:159], v[194:197], v[62:65]
	v_mfma_f32_16x16x32_bf16 v[62:65], v[160:163], v[198:201], v[62:65]
	v_mfma_f32_16x16x32_bf16 v[58:61], v[164:167], v[194:197], v[58:61]
	v_mfma_f32_16x16x32_bf16 v[58:61], v[174:177], v[198:201], v[58:61]
	v_mfma_f32_16x16x32_bf16 v[42:45], v[164:167], v[202:205], v[42:45]
	v_mfma_f32_16x16x32_bf16 v[42:45], v[174:177], v[206:209], v[42:45]
	v_mfma_f32_16x16x32_bf16 v[46:49], v[156:159], v[202:205], v[46:49]
	v_mfma_f32_16x16x32_bf16 v[46:49], v[160:163], v[206:209], v[46:49]
	v_mfma_f32_16x16x32_bf16 v[30:33], v[156:159], v[210:213], v[30:33]
	v_mfma_f32_16x16x32_bf16 v[30:33], v[160:163], v[214:217], v[30:33]
	v_mfma_f32_16x16x32_bf16 v[26:29], v[164:167], v[210:213], v[26:29]
	v_mfma_f32_16x16x32_bf16 v[26:29], v[174:177], v[214:217], v[26:29]
	v_mfma_f32_16x16x32_bf16 v[10:13], v[164:167], v[218:221], v[10:13]
	v_mfma_f32_16x16x32_bf16 v[10:13], v[174:177], v[222:225], v[10:13]
	v_mfma_f32_16x16x32_bf16 v[14:17], v[156:159], v[218:221], v[14:17]
	v_mfma_f32_16x16x32_bf16 v[14:17], v[160:163], v[222:225], v[14:17]
	s_setprio 0
	s_setprio 1
	v_mfma_f32_16x16x32_bf16 v[54:57], v[178:181], v[194:197], v[54:57]
	v_mfma_f32_16x16x32_bf16 v[54:57], v[182:185], v[198:201], v[54:57]
	v_mfma_f32_16x16x32_bf16 v[50:53], v[186:189], v[194:197], v[50:53]
	v_mfma_f32_16x16x32_bf16 v[50:53], v[190:193], v[198:201], v[50:53]
	v_mfma_f32_16x16x32_bf16 v[34:37], v[186:189], v[202:205], v[34:37]
	v_mfma_f32_16x16x32_bf16 v[34:37], v[190:193], v[206:209], v[34:37]
	v_mfma_f32_16x16x32_bf16 v[38:41], v[178:181], v[202:205], v[38:41]
	v_mfma_f32_16x16x32_bf16 v[38:41], v[182:185], v[206:209], v[38:41]
	v_mfma_f32_16x16x32_bf16 v[22:25], v[178:181], v[210:213], v[22:25]
	v_mfma_f32_16x16x32_bf16 v[22:25], v[182:185], v[214:217], v[22:25]
	v_mfma_f32_16x16x32_bf16 v[18:21], v[186:189], v[210:213], v[18:21]
	v_mfma_f32_16x16x32_bf16 v[18:21], v[190:193], v[214:217], v[18:21]
	v_mfma_f32_16x16x32_bf16 v[2:5], v[186:189], v[218:221], v[2:5]
	v_mfma_f32_16x16x32_bf16 v[2:5], v[190:193], v[222:225], v[2:5]
	v_mfma_f32_16x16x32_bf16 v[6:9], v[178:181], v[218:221], v[6:9]
	v_mfma_f32_16x16x32_bf16 v[6:9], v[182:185], v[222:225], v[6:9]
	s_setprio 0
	s_barrier
	s_add_i32 s79, s79, 2
	s_add_u32 s2, s2, 0x100
	s_addc_u32 s3, s3, 0
	s_add_u32 s77, s77, 0x100
	s_addc_u32 s78, s78, 0
	s_cmp_gt_u32 s79, 61
	s_cbranch_scc0 .LBB0_232
	s_and_b64 vcc, exec, s[16:17]
	s_cbranch_vccz .LBB0_235
	s_barrier

.LBB0_402:
	ds_read_b128 v[146:149], v156
	ds_read_b128 v[160:163], v156 offset:1024
	ds_read_b128 v[164:167], v156 offset:2048
	ds_read_b128 v[172:175], v156 offset:3072
	ds_read_b128 v[176:179], v157
	ds_read_b128 v[180:183], v157 offset:1024
	ds_read_b128 v[184:187], v157 offset:2048
	ds_read_b128 v[188:191], v157 offset:3072
	s_add_i32 s79, s58, 2
	s_add_u32 s22, s52, 0xffd50080
	s_addc_u32 s23, s53, -1
	s_cmp_eq_u32 s73, s58
	s_cselect_b32 s58, s68, s77
	s_cselect_b32 s61, s1, s23
	s_cselect_b32 s60, s0, s22
	s_cselect_b32 s59, s69, s78
	v_lshl_add_u64 v[150:151], s[52:53], 0, v[142:143]
	s_add_i32 m0, s87, 0xc000
	ds_read_b128 v[192:195], v158
	ds_read_b128 v[196:199], v158 offset:1024
	ds_read_b128 v[200:203], v158 offset:2048
	ds_read_b128 v[204:207], v158 offset:3072
	ds_read_b128 v[208:211], v158 offset:4096
	ds_read_b128 v[212:215], v158 offset:5120
	ds_read_b128 v[216:219], v158 offset:6144
	ds_read_b128 v[220:223], v158 offset:7168
	global_load_lds_dwordx4 v[150:151], off
	v_lshl_add_u64 v[150:151], s[52:53], 0, v[144:145]
	s_add_i32 m0, s87, 0xe000
	s_nop 0
	global_load_lds_dwordx4 v[150:151], off
	s_waitcnt vmcnt(8)
	s_waitcnt lgkmcnt(0)
	s_barrier
	s_setprio 1
	s_waitcnt lgkmcnt(0)
	v_mfma_f32_16x16x32_bf16 v[126:129], v[146:149], v[192:195], v[126:129]
	v_mfma_f32_16x16x32_bf16 v[126:129], v[160:163], v[196:199], v[126:129]
	v_mfma_f32_16x16x32_bf16 v[122:125], v[164:167], v[192:195], v[122:125]
	v_mfma_f32_16x16x32_bf16 v[122:125], v[172:175], v[196:199], v[122:125]
	v_mfma_f32_16x16x32_bf16 v[114:117], v[164:167], v[200:203], v[114:117]
	v_mfma_f32_16x16x32_bf16 v[114:117], v[172:175], v[204:207], v[114:117]
	v_mfma_f32_16x16x32_bf16 v[118:121], v[146:149], v[200:203], v[118:121]
	v_mfma_f32_16x16x32_bf16 v[118:121], v[160:163], v[204:207], v[118:121]
	v_mfma_f32_16x16x32_bf16 v[110:113], v[146:149], v[208:211], v[110:113]
	v_mfma_f32_16x16x32_bf16 v[110:113], v[160:163], v[212:215], v[110:113]
	v_mfma_f32_16x16x32_bf16 v[106:109], v[164:167], v[208:211], v[106:109]
	v_mfma_f32_16x16x32_bf16 v[106:109], v[172:175], v[212:215], v[106:109]
	v_mfma_f32_16x16x32_bf16 v[98:101], v[164:167], v[216:219], v[98:101]
	v_mfma_f32_16x16x32_bf16 v[98:101], v[172:175], v[220:223], v[98:101]
	v_mfma_f32_16x16x32_bf16 v[102:105], v[146:149], v[216:219], v[102:105]
	v_mfma_f32_16x16x32_bf16 v[102:105], v[160:163], v[220:223], v[102:105]
	s_setprio 0
	s_setprio 1
	v_mfma_f32_16x16x32_bf16 v[94:97], v[176:179], v[192:195], v[94:97]
	v_mfma_f32_16x16x32_bf16 v[94:97], v[180:183], v[196:199], v[94:97]
	v_mfma_f32_16x16x32_bf16 v[90:93], v[184:187], v[192:195], v[90:93]
	v_mfma_f32_16x16x32_bf16 v[90:93], v[188:191], v[196:199], v[90:93]
	v_mfma_f32_16x16x32_bf16 v[82:85], v[184:187], v[200:203], v[82:85]
	v_mfma_f32_16x16x32_bf16 v[82:85], v[188:191], v[204:207], v[82:85]
	v_mfma_f32_16x16x32_bf16 v[86:89], v[176:179], v[200:203], v[86:89]
	v_mfma_f32_16x16x32_bf16 v[86:89], v[180:183], v[204:207], v[86:89]
	v_mfma_f32_16x16x32_bf16 v[78:81], v[176:179], v[208:211], v[78:81]
	v_mfma_f32_16x16x32_bf16 v[78:81], v[180:183], v[212:215], v[78:81]
	v_mfma_f32_16x16x32_bf16 v[74:77], v[184:187], v[208:211], v[74:77]
	v_mfma_f32_16x16x32_bf16 v[74:77], v[188:191], v[212:215], v[74:77]
	v_mfma_f32_16x16x32_bf16 v[66:69], v[184:187], v[216:219], v[66:69]
	v_mfma_f32_16x16x32_bf16 v[66:69], v[188:191], v[220:223], v[66:69]
	v_mfma_f32_16x16x32_bf16 v[70:73], v[176:179], v[216:219], v[70:73]
	v_mfma_f32_16x16x32_bf16 v[70:73], v[180:183], v[220:223], v[70:73]
	s_setprio 0
	s_barrier
	s_add_i32 s22, s17, s66
	v_lshl_add_u64 v[150:151], s[58:59], 0, v[132:133]
	s_mov_b32 m0, s22
	ds_read_b128 v[192:195], v158 offset:16384
	ds_read_b128 v[196:199], v158 offset:17408
	ds_read_b128 v[200:203], v158 offset:18432
	ds_read_b128 v[204:207], v158 offset:19456
	ds_read_b128 v[208:211], v158 offset:20480
	ds_read_b128 v[212:215], v158 offset:21504
	ds_read_b128 v[216:219], v158 offset:22528
	ds_read_b128 v[220:223], v158 offset:23552
	global_load_lds_dwordx4 v[150:151], off
	s_add_i32 m0, s22, 0x2000
	s_add_u32 s22, s58, 0x2b0000
	v_lshl_add_u64 v[168:169], s[58:59], 0, v[136:137]
	s_addc_u32 s23, s59, 0
	s_add_i32 s24, s63, s66
	global_load_lds_dwordx4 v[168:169], off
	v_lshl_add_u64 v[224:225], s[22:23], 0, v[132:133]
	s_mov_b32 m0, s24
	v_lshl_add_u64 v[226:227], s[60:61], 0, v[134:135]
	global_load_lds_dwordx4 v[224:225], off
	v_lshl_add_u64 v[224:225], s[22:23], 0, v[136:137]
	s_add_i32 m0, s24, 0x2000
	s_nop 0
	global_load_lds_dwordx4 v[224:225], off
	v_lshl_add_u64 v[224:225], s[60:61], 0, v[130:131]
	s_mov_b32 m0, s87
	s_nop 0
	global_load_lds_dwordx4 v[224:225], off
	s_mov_b32 m0, s89
	s_nop 0
	global_load_lds_dwordx4 v[226:227], off
	s_waitcnt vmcnt(8)
	s_waitcnt lgkmcnt(0)
	s_barrier
	s_setprio 1
	s_waitcnt lgkmcnt(0)
	v_mfma_f32_16x16x32_bf16 v[62:65], v[146:149], v[192:195], v[62:65]
	v_mfma_f32_16x16x32_bf16 v[62:65], v[160:163], v[196:199], v[62:65]
	v_mfma_f32_16x16x32_bf16 v[58:61], v[164:167], v[192:195], v[58:61]
	v_mfma_f32_16x16x32_bf16 v[58:61], v[172:175], v[196:199], v[58:61]
	v_mfma_f32_16x16x32_bf16 v[50:53], v[164:167], v[200:203], v[50:53]
	v_mfma_f32_16x16x32_bf16 v[50:53], v[172:175], v[204:207], v[50:53]
	v_mfma_f32_16x16x32_bf16 v[54:57], v[146:149], v[200:203], v[54:57]
	v_mfma_f32_16x16x32_bf16 v[54:57], v[160:163], v[204:207], v[54:57]
	v_mfma_f32_16x16x32_bf16 v[46:49], v[146:149], v[208:211], v[46:49]
	v_mfma_f32_16x16x32_bf16 v[46:49], v[160:163], v[212:215], v[46:49]
	v_mfma_f32_16x16x32_bf16 v[42:45], v[164:167], v[208:211], v[42:45]
	v_mfma_f32_16x16x32_bf16 v[42:45], v[172:175], v[212:215], v[42:45]
	v_mfma_f32_16x16x32_bf16 v[34:37], v[164:167], v[216:219], v[34:37]
	v_mfma_f32_16x16x32_bf16 v[34:37], v[172:175], v[220:223], v[34:37]
	v_mfma_f32_16x16x32_bf16 v[38:41], v[146:149], v[216:219], v[38:41]
	v_mfma_f32_16x16x32_bf16 v[38:41], v[160:163], v[220:223], v[38:41]
	s_setprio 0
	s_setprio 1
	v_mfma_f32_16x16x32_bf16 v[30:33], v[176:179], v[192:195], v[30:33]
	v_mfma_f32_16x16x32_bf16 v[30:33], v[180:183], v[196:199], v[30:33]
	v_mfma_f32_16x16x32_bf16 v[26:29], v[184:187], v[192:195], v[26:29]
	v_mfma_f32_16x16x32_bf16 v[26:29], v[188:191], v[196:199], v[26:29]
	v_mfma_f32_16x16x32_bf16 v[18:21], v[184:187], v[200:203], v[18:21]
	v_mfma_f32_16x16x32_bf16 v[18:21], v[188:191], v[204:207], v[18:21]
	v_mfma_f32_16x16x32_bf16 v[22:25], v[176:179], v[200:203], v[22:25]
	v_mfma_f32_16x16x32_bf16 v[22:25], v[180:183], v[204:207], v[22:25]
	v_mfma_f32_16x16x32_bf16 v[14:17], v[176:179], v[208:211], v[14:17]
	v_mfma_f32_16x16x32_bf16 v[14:17], v[180:183], v[212:215], v[14:17]
	v_mfma_f32_16x16x32_bf16 v[10:13], v[184:187], v[208:211], v[10:13]
	v_mfma_f32_16x16x32_bf16 v[10:13], v[188:191], v[212:215], v[10:13]
	v_mfma_f32_16x16x32_bf16 v[2:5], v[184:187], v[216:219], v[2:5]
	v_mfma_f32_16x16x32_bf16 v[2:5], v[188:191], v[220:223], v[2:5]
	v_mfma_f32_16x16x32_bf16 v[6:9], v[176:179], v[216:219], v[6:9]
	v_mfma_f32_16x16x32_bf16 v[6:9], v[180:183], v[220:223], v[6:9]
	s_setprio 0
	s_barrier
	s_add_i32 s24, 0, 0x18000
	v_add_u32_e32 v171, s24, v154
	s_add_i32 s25, 0, 0x1c000
	ds_read_b128 v[146:149], v171
	ds_read_b128 v[160:163], v171 offset:1024
	ds_read_b128 v[164:167], v171 offset:2048
	ds_read_b128 v[172:175], v171 offset:3072
	v_add_u32_e32 v171, s25, v154
	ds_read_b128 v[176:179], v171
	ds_read_b128 v[180:183], v171 offset:1024
	ds_read_b128 v[184:187], v171 offset:2048
	ds_read_b128 v[188:191], v171 offset:3072
	s_add_u32 s22, s60, 0x2b0000
	s_addc_u32 s23, s61, 0
	s_mov_b32 m0, s90
	v_lshl_add_u64 v[228:229], s[22:23], 0, v[130:131]
	ds_read_b128 v[192:195], v158 offset:32768
	ds_read_b128 v[196:199], v158 offset:33792
	ds_read_b128 v[200:203], v158 offset:34816
	ds_read_b128 v[204:207], v158 offset:35840
	ds_read_b128 v[208:211], v158 offset:36864
	ds_read_b128 v[212:215], v158 offset:37888
	ds_read_b128 v[216:219], v158 offset:38912
	ds_read_b128 v[220:223], v158 offset:39936
	global_load_lds_dwordx4 v[228:229], off
	v_lshl_add_u64 v[228:229], s[22:23], 0, v[134:135]
	s_mov_b32 m0, s91
	s_nop 0
	global_load_lds_dwordx4 v[228:229], off
	s_waitcnt vmcnt(8)
	s_waitcnt lgkmcnt(0)
	s_barrier
	s_setprio 1
	s_waitcnt lgkmcnt(0)
	v_mfma_f32_16x16x32_bf16 v[126:129], v[146:149], v[192:195], v[126:129]
	v_mfma_f32_16x16x32_bf16 v[126:129], v[160:163], v[196:199], v[126:129]
	v_mfma_f32_16x16x32_bf16 v[122:125], v[164:167], v[192:195], v[122:125]
	v_mfma_f32_16x16x32_bf16 v[122:125], v[172:175], v[196:199], v[122:125]
	v_mfma_f32_16x16x32_bf16 v[114:117], v[164:167], v[200:203], v[114:117]
	v_mfma_f32_16x16x32_bf16 v[114:117], v[172:175], v[204:207], v[114:117]
	v_mfma_f32_16x16x32_bf16 v[118:121], v[146:149], v[200:203], v[118:121]
	v_mfma_f32_16x16x32_bf16 v[118:121], v[160:163], v[204:207], v[118:121]
	v_mfma_f32_16x16x32_bf16 v[110:113], v[146:149], v[208:211], v[110:113]
	v_mfma_f32_16x16x32_bf16 v[110:113], v[160:163], v[212:215], v[110:113]
	v_mfma_f32_16x16x32_bf16 v[106:109], v[164:167], v[208:211], v[106:109]
	v_mfma_f32_16x16x32_bf16 v[106:109], v[172:175], v[212:215], v[106:109]
	v_mfma_f32_16x16x32_bf16 v[98:101], v[164:167], v[216:219], v[98:101]
	v_mfma_f32_16x16x32_bf16 v[98:101], v[172:175], v[220:223], v[98:101]
	v_mfma_f32_16x16x32_bf16 v[102:105], v[146:149], v[216:219], v[102:105]
	v_mfma_f32_16x16x32_bf16 v[102:105], v[160:163], v[220:223], v[102:105]
	s_setprio 0
	s_setprio 1
	v_mfma_f32_16x16x32_bf16 v[94:97], v[176:179], v[192:195], v[94:97]
	v_mfma_f32_16x16x32_bf16 v[94:97], v[180:183], v[196:199], v[94:97]
	v_mfma_f32_16x16x32_bf16 v[90:93], v[184:187], v[192:195], v[90:93]
	v_mfma_f32_16x16x32_bf16 v[90:93], v[188:191], v[196:199], v[90:93]
	v_mfma_f32_16x16x32_bf16 v[82:85], v[184:187], v[200:203], v[82:85]
	v_mfma_f32_16x16x32_bf16 v[82:85], v[188:191], v[204:207], v[82:85]
	v_mfma_f32_16x16x32_bf16 v[86:89], v[176:179], v[200:203], v[86:89]
	v_mfma_f32_16x16x32_bf16 v[86:89], v[180:183], v[204:207], v[86:89]
	v_mfma_f32_16x16x32_bf16 v[78:81], v[176:179], v[208:211], v[78:81]
	v_mfma_f32_16x16x32_bf16 v[78:81], v[180:183], v[212:215], v[78:81]
	v_mfma_f32_16x16x32_bf16 v[74:77], v[184:187], v[208:211], v[74:77]
	v_mfma_f32_16x16x32_bf16 v[74:77], v[188:191], v[212:215], v[74:77]
	v_mfma_f32_16x16x32_bf16 v[66:69], v[184:187], v[216:219], v[66:69]
	v_mfma_f32_16x16x32_bf16 v[66:69], v[188:191], v[220:223], v[66:69]
	v_mfma_f32_16x16x32_bf16 v[70:73], v[176:179], v[216:219], v[70:73]
	v_mfma_f32_16x16x32_bf16 v[70:73], v[180:183], v[220:223], v[70:73]
	s_setprio 0
	s_barrier
	s_add_i32 s22, s24, s66
	v_lshl_add_u64 v[150:151], v[150:151], 0, s[38:39]
	s_mov_b32 m0, s22
	ds_read_b128 v[192:195], v158 offset:49152
	ds_read_b128 v[196:199], v158 offset:50176
	ds_read_b128 v[200:203], v158 offset:51200
	ds_read_b128 v[204:207], v158 offset:52224
	ds_read_b128 v[208:211], v158 offset:53248
	ds_read_b128 v[212:215], v158 offset:54272
	ds_read_b128 v[216:219], v158 offset:55296
	ds_read_b128 v[220:223], v158 offset:56320
	global_load_lds_dwordx4 v[150:151], off
	s_add_i32 m0, s22, 0x2000
	s_add_u32 s22, s58, 0x2b0080
	v_lshl_add_u64 v[150:151], v[168:169], 0, s[38:39]
	s_addc_u32 s23, s59, 0
	s_add_i32 s24, s25, s66
	global_load_lds_dwordx4 v[150:151], off
	v_lshl_add_u64 v[150:151], s[22:23], 0, v[132:133]
	s_mov_b32 m0, s24
	s_nop 0
	global_load_lds_dwordx4 v[150:151], off
	v_lshl_add_u64 v[150:151], s[22:23], 0, v[136:137]
	s_add_i32 m0, s24, 0x2000
	s_nop 0
	global_load_lds_dwordx4 v[150:151], off
	v_lshl_add_u64 v[150:151], v[224:225], 0, s[38:39]
	s_mov_b32 m0, s14
	s_nop 0
	global_load_lds_dwordx4 v[150:151], off
	v_lshl_add_u64 v[150:151], v[226:227], 0, s[38:39]
	s_mov_b32 m0, s15
	s_nop 0
	global_load_lds_dwordx4 v[150:151], off
	s_waitcnt vmcnt(8)
	s_waitcnt lgkmcnt(0)
	s_barrier
	s_setprio 1
	s_waitcnt lgkmcnt(0)
	v_mfma_f32_16x16x32_bf16 v[62:65], v[146:149], v[192:195], v[62:65]
	v_mfma_f32_16x16x32_bf16 v[62:65], v[160:163], v[196:199], v[62:65]
	v_mfma_f32_16x16x32_bf16 v[58:61], v[164:167], v[192:195], v[58:61]
	v_mfma_f32_16x16x32_bf16 v[58:61], v[172:175], v[196:199], v[58:61]
	v_mfma_f32_16x16x32_bf16 v[50:53], v[164:167], v[200:203], v[50:53]
	v_mfma_f32_16x16x32_bf16 v[50:53], v[172:175], v[204:207], v[50:53]
	v_mfma_f32_16x16x32_bf16 v[54:57], v[146:149], v[200:203], v[54:57]
	v_mfma_f32_16x16x32_bf16 v[54:57], v[160:163], v[204:207], v[54:57]
	v_mfma_f32_16x16x32_bf16 v[46:49], v[146:149], v[208:211], v[46:49]
	v_mfma_f32_16x16x32_bf16 v[46:49], v[160:163], v[212:215], v[46:49]
	v_mfma_f32_16x16x32_bf16 v[42:45], v[164:167], v[208:211], v[42:45]
	v_mfma_f32_16x16x32_bf16 v[42:45], v[172:175], v[212:215], v[42:45]
	v_mfma_f32_16x16x32_bf16 v[34:37], v[164:167], v[216:219], v[34:37]
	v_mfma_f32_16x16x32_bf16 v[34:37], v[172:175], v[220:223], v[34:37]
	v_mfma_f32_16x16x32_bf16 v[38:41], v[146:149], v[216:219], v[38:41]
	v_mfma_f32_16x16x32_bf16 v[38:41], v[160:163], v[220:223], v[38:41]
	s_setprio 0
	s_setprio 1
	v_mfma_f32_16x16x32_bf16 v[30:33], v[176:179], v[192:195], v[30:33]
	v_mfma_f32_16x16x32_bf16 v[30:33], v[180:183], v[196:199], v[30:33]
	v_mfma_f32_16x16x32_bf16 v[26:29], v[184:187], v[192:195], v[26:29]
	v_mfma_f32_16x16x32_bf16 v[26:29], v[188:191], v[196:199], v[26:29]
	v_mfma_f32_16x16x32_bf16 v[18:21], v[184:187], v[200:203], v[18:21]
	v_mfma_f32_16x16x32_bf16 v[18:21], v[188:191], v[204:207], v[18:21]
	v_mfma_f32_16x16x32_bf16 v[22:25], v[176:179], v[200:203], v[22:25]
	v_mfma_f32_16x16x32_bf16 v[22:25], v[180:183], v[204:207], v[22:25]
	v_mfma_f32_16x16x32_bf16 v[14:17], v[176:179], v[208:211], v[14:17]
	v_mfma_f32_16x16x32_bf16 v[14:17], v[180:183], v[212:215], v[14:17]
	v_mfma_f32_16x16x32_bf16 v[10:13], v[184:187], v[208:211], v[10:13]
	v_mfma_f32_16x16x32_bf16 v[10:13], v[188:191], v[212:215], v[10:13]
	v_mfma_f32_16x16x32_bf16 v[2:5], v[184:187], v[216:219], v[2:5]
	v_mfma_f32_16x16x32_bf16 v[2:5], v[188:191], v[220:223], v[2:5]
	v_mfma_f32_16x16x32_bf16 v[6:9], v[176:179], v[216:219], v[6:9]
	v_mfma_f32_16x16x32_bf16 v[6:9], v[180:183], v[220:223], v[6:9]
	s_setprio 0
	s_barrier
	s_add_u32 s52, s52, 0x100
	s_addc_u32 s53, s53, 0
	s_add_u32 s77, s77, 0x100
	s_addc_u32 s78, s78, 0
	s_cmp_ge_i32 s79, s76
	s_mov_b32 s58, s79
	s_cbranch_scc0 .LBB0_402
	s_and_b64 vcc, exec, s[40:41]
	s_cbranch_vccz .LBB0_405

.LBB0_649:
	ds_read_b128 v[146:149], v161
	ds_read_b128 v[150:153], v161 offset:1024
	ds_read_b128 v[164:167], v161 offset:2048
	ds_read_b128 v[168:171], v161 offset:3072
	ds_read_b128 v[172:175], v162
	ds_read_b128 v[176:179], v162 offset:1024
	ds_read_b128 v[180:183], v162 offset:2048
	ds_read_b128 v[184:187], v162 offset:3072
	s_add_u32 s8, s4, 0xfff00080
	s_addc_u32 s9, s5, -1
	s_cmp_eq_u32 s57, 60
	s_cselect_b32 s53, s1, s9
	s_cselect_b32 s52, s7, s8
	s_cselect_b32 s9, s11, s55
	s_cselect_b32 s8, s12, s33
	v_lshl_add_u64 v[154:155], s[4:5], 0, v[142:143]
	s_add_i32 m0, s64, 0xc000
	ds_read_b128 v[188:191], v163
	ds_read_b128 v[192:195], v163 offset:1024
	ds_read_b128 v[196:199], v163 offset:2048
	ds_read_b128 v[200:203], v163 offset:3072
	ds_read_b128 v[206:209], v163 offset:4096
	ds_read_b128 v[210:213], v163 offset:5120
	ds_read_b128 v[214:217], v163 offset:6144
	ds_read_b128 v[218:221], v163 offset:7168
	global_load_lds_dwordx4 v[154:155], off
	v_lshl_add_u64 v[154:155], s[4:5], 0, v[144:145]
	s_add_i32 m0, s64, 0xe000
	s_nop 0
	global_load_lds_dwordx4 v[154:155], off
	s_waitcnt vmcnt(8)
	s_waitcnt lgkmcnt(0)
	s_barrier
	s_setprio 1
	s_waitcnt lgkmcnt(0)
	v_mfma_f32_16x16x32_bf16 v[126:129], v[146:149], v[188:191], v[126:129]
	v_mfma_f32_16x16x32_bf16 v[126:129], v[150:153], v[192:195], v[126:129]
	v_mfma_f32_16x16x32_bf16 v[122:125], v[164:167], v[188:191], v[122:125]
	v_mfma_f32_16x16x32_bf16 v[122:125], v[168:171], v[192:195], v[122:125]
	v_mfma_f32_16x16x32_bf16 v[106:109], v[164:167], v[196:199], v[106:109]
	v_mfma_f32_16x16x32_bf16 v[106:109], v[168:171], v[200:203], v[106:109]
	v_mfma_f32_16x16x32_bf16 v[110:113], v[146:149], v[196:199], v[110:113]
	v_mfma_f32_16x16x32_bf16 v[110:113], v[150:153], v[200:203], v[110:113]
	v_mfma_f32_16x16x32_bf16 v[94:97], v[146:149], v[206:209], v[94:97]
	v_mfma_f32_16x16x32_bf16 v[94:97], v[150:153], v[210:213], v[94:97]
	v_mfma_f32_16x16x32_bf16 v[90:93], v[164:167], v[206:209], v[90:93]
	v_mfma_f32_16x16x32_bf16 v[90:93], v[168:171], v[210:213], v[90:93]
	v_mfma_f32_16x16x32_bf16 v[74:77], v[164:167], v[214:217], v[74:77]
	v_mfma_f32_16x16x32_bf16 v[74:77], v[168:171], v[218:221], v[74:77]
	v_mfma_f32_16x16x32_bf16 v[78:81], v[146:149], v[214:217], v[78:81]
	v_mfma_f32_16x16x32_bf16 v[78:81], v[150:153], v[218:221], v[78:81]
	s_setprio 0
	s_setprio 1
	v_mfma_f32_16x16x32_bf16 v[118:121], v[172:175], v[188:191], v[118:121]
	v_mfma_f32_16x16x32_bf16 v[118:121], v[176:179], v[192:195], v[118:121]
	v_mfma_f32_16x16x32_bf16 v[114:117], v[180:183], v[188:191], v[114:117]
	v_mfma_f32_16x16x32_bf16 v[114:117], v[184:187], v[192:195], v[114:117]
	v_mfma_f32_16x16x32_bf16 v[98:101], v[180:183], v[196:199], v[98:101]
	v_mfma_f32_16x16x32_bf16 v[98:101], v[184:187], v[200:203], v[98:101]
	v_mfma_f32_16x16x32_bf16 v[102:105], v[172:175], v[196:199], v[102:105]
	v_mfma_f32_16x16x32_bf16 v[102:105], v[176:179], v[200:203], v[102:105]
	v_mfma_f32_16x16x32_bf16 v[86:89], v[172:175], v[206:209], v[86:89]
	v_mfma_f32_16x16x32_bf16 v[86:89], v[176:179], v[210:213], v[86:89]
	v_mfma_f32_16x16x32_bf16 v[82:85], v[180:183], v[206:209], v[82:85]
	v_mfma_f32_16x16x32_bf16 v[82:85], v[184:187], v[210:213], v[82:85]
	v_mfma_f32_16x16x32_bf16 v[66:69], v[180:183], v[214:217], v[66:69]
	v_mfma_f32_16x16x32_bf16 v[66:69], v[184:187], v[218:221], v[66:69]
	v_mfma_f32_16x16x32_bf16 v[70:73], v[172:175], v[214:217], v[70:73]
	v_mfma_f32_16x16x32_bf16 v[70:73], v[176:179], v[218:221], v[70:73]
	s_setprio 0
	s_barrier
	s_add_i32 s26, s86, s59
	v_lshl_add_u64 v[154:155], s[8:9], 0, v[132:133]
	s_mov_b32 m0, s26
	ds_read_b128 v[188:191], v163 offset:16384
	ds_read_b128 v[192:195], v163 offset:17408
	ds_read_b128 v[196:199], v163 offset:18432
	ds_read_b128 v[200:203], v163 offset:19456
	ds_read_b128 v[206:209], v163 offset:20480
	ds_read_b128 v[210:213], v163 offset:21504
	ds_read_b128 v[214:217], v163 offset:22528
	ds_read_b128 v[218:221], v163 offset:23552
	global_load_lds_dwordx4 v[154:155], off
	s_add_i32 m0, s26, 0x2000
	s_add_u32 s26, s8, 0x100000
	v_lshl_add_u64 v[222:223], s[8:9], 0, v[136:137]
	s_addc_u32 s27, s9, 0
	s_add_i32 s28, s87, s59
	global_load_lds_dwordx4 v[222:223], off
	v_lshl_add_u64 v[224:225], s[26:27], 0, v[132:133]
	s_mov_b32 m0, s28
	v_lshl_add_u64 v[226:227], s[52:53], 0, v[134:135]
	global_load_lds_dwordx4 v[224:225], off
	v_lshl_add_u64 v[224:225], s[26:27], 0, v[136:137]
	s_add_i32 m0, s28, 0x2000
	s_nop 0
	global_load_lds_dwordx4 v[224:225], off
	v_lshl_add_u64 v[224:225], s[52:53], 0, v[130:131]
	s_mov_b32 m0, s64
	s_nop 0
	global_load_lds_dwordx4 v[224:225], off
	s_mov_b32 m0, s65
	s_nop 0
	global_load_lds_dwordx4 v[226:227], off
	s_waitcnt vmcnt(8)
	s_waitcnt lgkmcnt(0)
	s_barrier
	s_setprio 1
	s_waitcnt lgkmcnt(0)
	v_mfma_f32_16x16x32_bf16 v[62:65], v[146:149], v[188:191], v[62:65]
	v_mfma_f32_16x16x32_bf16 v[62:65], v[150:153], v[192:195], v[62:65]
	v_mfma_f32_16x16x32_bf16 v[58:61], v[164:167], v[188:191], v[58:61]
	v_mfma_f32_16x16x32_bf16 v[58:61], v[168:171], v[192:195], v[58:61]
	v_mfma_f32_16x16x32_bf16 v[42:45], v[164:167], v[196:199], v[42:45]
	v_mfma_f32_16x16x32_bf16 v[42:45], v[168:171], v[200:203], v[42:45]
	v_mfma_f32_16x16x32_bf16 v[46:49], v[146:149], v[196:199], v[46:49]
	v_mfma_f32_16x16x32_bf16 v[46:49], v[150:153], v[200:203], v[46:49]
	v_mfma_f32_16x16x32_bf16 v[30:33], v[146:149], v[206:209], v[30:33]
	v_mfma_f32_16x16x32_bf16 v[30:33], v[150:153], v[210:213], v[30:33]
	v_mfma_f32_16x16x32_bf16 v[26:29], v[164:167], v[206:209], v[26:29]
	v_mfma_f32_16x16x32_bf16 v[26:29], v[168:171], v[210:213], v[26:29]
	v_mfma_f32_16x16x32_bf16 v[10:13], v[164:167], v[214:217], v[10:13]
	v_mfma_f32_16x16x32_bf16 v[10:13], v[168:171], v[218:221], v[10:13]
	v_mfma_f32_16x16x32_bf16 v[14:17], v[146:149], v[214:217], v[14:17]
	v_mfma_f32_16x16x32_bf16 v[14:17], v[150:153], v[218:221], v[14:17]
	s_setprio 0
	s_setprio 1
	v_mfma_f32_16x16x32_bf16 v[54:57], v[172:175], v[188:191], v[54:57]
	v_mfma_f32_16x16x32_bf16 v[54:57], v[176:179], v[192:195], v[54:57]
	v_mfma_f32_16x16x32_bf16 v[50:53], v[180:183], v[188:191], v[50:53]
	v_mfma_f32_16x16x32_bf16 v[50:53], v[184:187], v[192:195], v[50:53]
	v_mfma_f32_16x16x32_bf16 v[34:37], v[180:183], v[196:199], v[34:37]
	v_mfma_f32_16x16x32_bf16 v[34:37], v[184:187], v[200:203], v[34:37]
	v_mfma_f32_16x16x32_bf16 v[38:41], v[172:175], v[196:199], v[38:41]
	v_mfma_f32_16x16x32_bf16 v[38:41], v[176:179], v[200:203], v[38:41]
	v_mfma_f32_16x16x32_bf16 v[22:25], v[172:175], v[206:209], v[22:25]
	v_mfma_f32_16x16x32_bf16 v[22:25], v[176:179], v[210:213], v[22:25]
	v_mfma_f32_16x16x32_bf16 v[18:21], v[180:183], v[206:209], v[18:21]
	v_mfma_f32_16x16x32_bf16 v[18:21], v[184:187], v[210:213], v[18:21]
	v_mfma_f32_16x16x32_bf16 v[2:5], v[180:183], v[214:217], v[2:5]
	v_mfma_f32_16x16x32_bf16 v[2:5], v[184:187], v[218:221], v[2:5]
	v_mfma_f32_16x16x32_bf16 v[6:9], v[172:175], v[214:217], v[6:9]
	v_mfma_f32_16x16x32_bf16 v[6:9], v[176:179], v[218:221], v[6:9]
	s_setprio 0
	s_barrier
	s_add_i32 s28, 0, 0x18000
	v_add_u32_e32 v140, s28, v156
	s_add_i32 s29, 0, 0x1c000
	ds_read_b128 v[146:149], v140
	ds_read_b128 v[150:153], v140 offset:1024
	ds_read_b128 v[164:167], v140 offset:2048
	ds_read_b128 v[168:171], v140 offset:3072
	v_add_u32_e32 v140, s29, v156
	ds_read_b128 v[172:175], v140
	ds_read_b128 v[176:179], v140 offset:1024
	ds_read_b128 v[180:183], v140 offset:2048
	ds_read_b128 v[184:187], v140 offset:3072
	s_add_u32 s26, s52, 0x100000
	s_addc_u32 s27, s53, 0
	s_mov_b32 m0, s66
	v_lshl_add_u64 v[228:229], s[26:27], 0, v[130:131]
	ds_read_b128 v[188:191], v163 offset:32768
	ds_read_b128 v[192:195], v163 offset:33792
	ds_read_b128 v[196:199], v163 offset:34816
	ds_read_b128 v[200:203], v163 offset:35840
	ds_read_b128 v[206:209], v163 offset:36864
	ds_read_b128 v[210:213], v163 offset:37888
	ds_read_b128 v[214:217], v163 offset:38912
	ds_read_b128 v[218:221], v163 offset:39936
	global_load_lds_dwordx4 v[228:229], off
	v_lshl_add_u64 v[228:229], s[26:27], 0, v[134:135]
	s_mov_b32 m0, s67
	s_nop 0
	global_load_lds_dwordx4 v[228:229], off
	s_waitcnt vmcnt(8)
	s_waitcnt lgkmcnt(0)
	s_barrier
	s_setprio 1
	s_waitcnt lgkmcnt(0)
	v_mfma_f32_16x16x32_bf16 v[126:129], v[146:149], v[188:191], v[126:129]
	v_mfma_f32_16x16x32_bf16 v[126:129], v[150:153], v[192:195], v[126:129]
	v_mfma_f32_16x16x32_bf16 v[122:125], v[164:167], v[188:191], v[122:125]
	v_mfma_f32_16x16x32_bf16 v[122:125], v[168:171], v[192:195], v[122:125]
	v_mfma_f32_16x16x32_bf16 v[106:109], v[164:167], v[196:199], v[106:109]
	v_mfma_f32_16x16x32_bf16 v[106:109], v[168:171], v[200:203], v[106:109]
	v_mfma_f32_16x16x32_bf16 v[110:113], v[146:149], v[196:199], v[110:113]
	v_mfma_f32_16x16x32_bf16 v[110:113], v[150:153], v[200:203], v[110:113]
	v_mfma_f32_16x16x32_bf16 v[94:97], v[146:149], v[206:209], v[94:97]
	v_mfma_f32_16x16x32_bf16 v[94:97], v[150:153], v[210:213], v[94:97]
	v_mfma_f32_16x16x32_bf16 v[90:93], v[164:167], v[206:209], v[90:93]
	v_mfma_f32_16x16x32_bf16 v[90:93], v[168:171], v[210:213], v[90:93]
	v_mfma_f32_16x16x32_bf16 v[74:77], v[164:167], v[214:217], v[74:77]
	v_mfma_f32_16x16x32_bf16 v[74:77], v[168:171], v[218:221], v[74:77]
	v_mfma_f32_16x16x32_bf16 v[78:81], v[146:149], v[214:217], v[78:81]
	v_mfma_f32_16x16x32_bf16 v[78:81], v[150:153], v[218:221], v[78:81]
	s_setprio 0
	s_setprio 1
	v_mfma_f32_16x16x32_bf16 v[118:121], v[172:175], v[188:191], v[118:121]
	v_mfma_f32_16x16x32_bf16 v[118:121], v[176:179], v[192:195], v[118:121]
	v_mfma_f32_16x16x32_bf16 v[114:117], v[180:183], v[188:191], v[114:117]
	v_mfma_f32_16x16x32_bf16 v[114:117], v[184:187], v[192:195], v[114:117]
	v_mfma_f32_16x16x32_bf16 v[98:101], v[180:183], v[196:199], v[98:101]
	v_mfma_f32_16x16x32_bf16 v[98:101], v[184:187], v[200:203], v[98:101]
	v_mfma_f32_16x16x32_bf16 v[102:105], v[172:175], v[196:199], v[102:105]
	v_mfma_f32_16x16x32_bf16 v[102:105], v[176:179], v[200:203], v[102:105]
	v_mfma_f32_16x16x32_bf16 v[86:89], v[172:175], v[206:209], v[86:89]
	v_mfma_f32_16x16x32_bf16 v[86:89], v[176:179], v[210:213], v[86:89]
	v_mfma_f32_16x16x32_bf16 v[82:85], v[180:183], v[206:209], v[82:85]
	v_mfma_f32_16x16x32_bf16 v[82:85], v[184:187], v[210:213], v[82:85]
	v_mfma_f32_16x16x32_bf16 v[66:69], v[180:183], v[214:217], v[66:69]
	v_mfma_f32_16x16x32_bf16 v[66:69], v[184:187], v[218:221], v[66:69]
	v_mfma_f32_16x16x32_bf16 v[70:73], v[172:175], v[214:217], v[70:73]
	v_mfma_f32_16x16x32_bf16 v[70:73], v[176:179], v[218:221], v[70:73]
	s_setprio 0
	s_barrier
	s_add_i32 s26, s28, s59
	v_lshl_add_u64 v[154:155], v[154:155], 0, s[38:39]
	s_mov_b32 m0, s26
	ds_read_b128 v[188:191], v163 offset:49152
	ds_read_b128 v[192:195], v163 offset:50176
	ds_read_b128 v[196:199], v163 offset:51200
	ds_read_b128 v[200:203], v163 offset:52224
	ds_read_b128 v[206:209], v163 offset:53248
	ds_read_b128 v[210:213], v163 offset:54272
	ds_read_b128 v[214:217], v163 offset:55296
	ds_read_b128 v[218:221], v163 offset:56320
	global_load_lds_dwordx4 v[154:155], off
	s_add_i32 m0, s26, 0x2000
	s_add_u32 s8, s8, 0x100080
	v_lshl_add_u64 v[154:155], v[222:223], 0, s[38:39]
	s_addc_u32 s9, s9, 0
	s_add_i32 s26, s29, s59
	global_load_lds_dwordx4 v[154:155], off
	v_lshl_add_u64 v[154:155], s[8:9], 0, v[132:133]
	s_mov_b32 m0, s26
	s_nop 0
	global_load_lds_dwordx4 v[154:155], off
	v_lshl_add_u64 v[154:155], s[8:9], 0, v[136:137]
	s_add_i32 m0, s26, 0x2000
	s_nop 0
	global_load_lds_dwordx4 v[154:155], off
	v_lshl_add_u64 v[154:155], v[224:225], 0, s[38:39]
	s_mov_b32 m0, s22
	s_nop 0
	global_load_lds_dwordx4 v[154:155], off
	v_lshl_add_u64 v[154:155], v[226:227], 0, s[38:39]
	s_mov_b32 m0, s23
	s_nop 0
	global_load_lds_dwordx4 v[154:155], off
	s_waitcnt vmcnt(8)
	s_waitcnt lgkmcnt(0)
	s_barrier
	s_setprio 1
	s_waitcnt lgkmcnt(0)
	v_mfma_f32_16x16x32_bf16 v[62:65], v[146:149], v[188:191], v[62:65]
	v_mfma_f32_16x16x32_bf16 v[62:65], v[150:153], v[192:195], v[62:65]
	v_mfma_f32_16x16x32_bf16 v[58:61], v[164:167], v[188:191], v[58:61]
	v_mfma_f32_16x16x32_bf16 v[58:61], v[168:171], v[192:195], v[58:61]
	v_mfma_f32_16x16x32_bf16 v[42:45], v[164:167], v[196:199], v[42:45]
	v_mfma_f32_16x16x32_bf16 v[42:45], v[168:171], v[200:203], v[42:45]
	v_mfma_f32_16x16x32_bf16 v[46:49], v[146:149], v[196:199], v[46:49]
	v_mfma_f32_16x16x32_bf16 v[46:49], v[150:153], v[200:203], v[46:49]
	v_mfma_f32_16x16x32_bf16 v[30:33], v[146:149], v[206:209], v[30:33]
	v_mfma_f32_16x16x32_bf16 v[30:33], v[150:153], v[210:213], v[30:33]
	v_mfma_f32_16x16x32_bf16 v[26:29], v[164:167], v[206:209], v[26:29]
	v_mfma_f32_16x16x32_bf16 v[26:29], v[168:171], v[210:213], v[26:29]
	v_mfma_f32_16x16x32_bf16 v[10:13], v[164:167], v[214:217], v[10:13]
	v_mfma_f32_16x16x32_bf16 v[10:13], v[168:171], v[218:221], v[10:13]
	v_mfma_f32_16x16x32_bf16 v[14:17], v[146:149], v[214:217], v[14:17]
	v_mfma_f32_16x16x32_bf16 v[14:17], v[150:153], v[218:221], v[14:17]
	s_setprio 0
	s_setprio 1
	v_mfma_f32_16x16x32_bf16 v[54:57], v[172:175], v[188:191], v[54:57]
	v_mfma_f32_16x16x32_bf16 v[54:57], v[176:179], v[192:195], v[54:57]
	v_mfma_f32_16x16x32_bf16 v[50:53], v[180:183], v[188:191], v[50:53]
	v_mfma_f32_16x16x32_bf16 v[50:53], v[184:187], v[192:195], v[50:53]
	v_mfma_f32_16x16x32_bf16 v[34:37], v[180:183], v[196:199], v[34:37]
	v_mfma_f32_16x16x32_bf16 v[34:37], v[184:187], v[200:203], v[34:37]
	v_mfma_f32_16x16x32_bf16 v[38:41], v[172:175], v[196:199], v[38:41]
	v_mfma_f32_16x16x32_bf16 v[38:41], v[176:179], v[200:203], v[38:41]
	v_mfma_f32_16x16x32_bf16 v[22:25], v[172:175], v[206:209], v[22:25]
	v_mfma_f32_16x16x32_bf16 v[22:25], v[176:179], v[210:213], v[22:25]
	v_mfma_f32_16x16x32_bf16 v[18:21], v[180:183], v[206:209], v[18:21]
	v_mfma_f32_16x16x32_bf16 v[18:21], v[184:187], v[210:213], v[18:21]
	v_mfma_f32_16x16x32_bf16 v[2:5], v[180:183], v[214:217], v[2:5]
	v_mfma_f32_16x16x32_bf16 v[2:5], v[184:187], v[218:221], v[2:5]
	v_mfma_f32_16x16x32_bf16 v[6:9], v[172:175], v[214:217], v[6:9]
	v_mfma_f32_16x16x32_bf16 v[6:9], v[176:179], v[218:221], v[6:9]
	s_setprio 0
	s_barrier
	s_add_i32 s57, s57, 2
	s_add_u32 s4, s4, 0x100
	s_addc_u32 s5, s5, 0
	s_add_u32 s33, s33, 0x100
	s_addc_u32 s55, s55, 0
	s_cmp_gt_u32 s57, 61
	s_cbranch_scc0 .LBB0_649
	s_and_b64 vcc, exec, s[40:41]
	s_cbranch_vccz .LBB0_652
	s_barrier

.LBB0_955:
	s_add_u32 s28, s72, s60
	s_addc_u32 s29, s73, 0
	s_add_u32 s36, s28, 0x100
	s_addc_u32 s37, s29, 0
	s_and_b64 s[26:27], s[58:59], exec
	s_cselect_b32 s63, s39, s37
	s_cselect_b32 s62, s78, s36
	s_add_u32 s26, s70, s60
	s_addc_u32 s27, s71, 0
	s_add_u32 s36, s26, 0x100
	s_addc_u32 s37, s27, 0
	s_and_b64 s[26:27], s[58:59], exec
	s_cselect_b32 s65, s31, s37
	s_cselect_b32 s64, s79, s36
	s_add_u32 vcc_lo, s28, 0x20080
	ds_read_b128 v[130:133], v181
	ds_read_b128 v[134:137], v181 offset:1024
	ds_read_b128 v[150:153], v181 offset:2048
	ds_read_b128 v[154:157], v181 offset:3072
	ds_read_b128 v[158:161], v182
	ds_read_b128 v[162:165], v182 offset:1024
	ds_read_b128 v[166:169], v182 offset:2048
	ds_read_b128 v[170:173], v182 offset:3072
	s_addc_u32 vcc_hi, s29, 0
	s_add_i32 s27, s4, s86
	s_add_i32 m0, s69, 0xc000
	s_add_i32 s37, s69, 0xe000
	s_add_i32 s36, s27, 0x2000
	s_add_u32 s66, s64, 0x10000
	s_addc_u32 s67, s65, 0
	s_add_i32 s29, s5, s86
	s_add_i32 s28, s29, 0x2000
	s_add_i32 s83, 0, 0x18000
	s_add_i32 s82, 0, 0x1c000
	s_add_u32 s60, s62, 0x20000
	s_addc_u32 s61, s63, 0
	s_add_i32 s81, s83, s86
	s_add_i32 s26, s81, 0x2000
	s_add_u32 s58, s64, 0x10080
	s_addc_u32 s59, s65, 0
	s_add_i32 s80, s82, s86
	s_add_i32 s93, s80, 0x2000
	v_lshl_add_u64 v[218:219], vcc, 0, v[140:141]
	ds_read_b128 v[184:187], v183
	ds_read_b128 v[188:191], v183 offset:1024
	ds_read_b128 v[192:195], v183 offset:2048
	ds_read_b128 v[196:199], v183 offset:3072
	ds_read_b128 v[200:203], v183 offset:4096
	ds_read_b128 v[206:209], v183 offset:5120
	ds_read_b128 v[210:213], v183 offset:6144
	ds_read_b128 v[214:217], v183 offset:7168
	global_load_lds_dwordx4 v[218:219], off
	v_lshl_add_u64 v[218:219], vcc, 0, v[144:145]
	s_mov_b32 m0, s37
	s_nop 0
	global_load_lds_dwordx4 v[218:219], off
	s_waitcnt vmcnt(8)
	s_waitcnt lgkmcnt(0)
	s_barrier
	s_setprio 1
	s_waitcnt lgkmcnt(0)
	v_mfma_f32_16x16x32_bf16 v[126:129], v[130:133], v[184:187], v[126:129]
	v_mfma_f32_16x16x32_bf16 v[126:129], v[134:137], v[188:191], v[126:129]
	v_mfma_f32_16x16x32_bf16 v[122:125], v[150:153], v[184:187], v[122:125]
	v_mfma_f32_16x16x32_bf16 v[122:125], v[154:157], v[188:191], v[122:125]
	v_mfma_f32_16x16x32_bf16 v[114:117], v[150:153], v[192:195], v[114:117]
	v_mfma_f32_16x16x32_bf16 v[114:117], v[154:157], v[196:199], v[114:117]
	v_mfma_f32_16x16x32_bf16 v[118:121], v[130:133], v[192:195], v[118:121]
	v_mfma_f32_16x16x32_bf16 v[118:121], v[134:137], v[196:199], v[118:121]
	v_mfma_f32_16x16x32_bf16 v[110:113], v[130:133], v[200:203], v[110:113]
	v_mfma_f32_16x16x32_bf16 v[110:113], v[134:137], v[206:209], v[110:113]
	v_mfma_f32_16x16x32_bf16 v[106:109], v[150:153], v[200:203], v[106:109]
	v_mfma_f32_16x16x32_bf16 v[106:109], v[154:157], v[206:209], v[106:109]
	v_mfma_f32_16x16x32_bf16 v[98:101], v[150:153], v[210:213], v[98:101]
	v_mfma_f32_16x16x32_bf16 v[98:101], v[154:157], v[214:217], v[98:101]
	v_mfma_f32_16x16x32_bf16 v[102:105], v[130:133], v[210:213], v[102:105]
	v_mfma_f32_16x16x32_bf16 v[102:105], v[134:137], v[214:217], v[102:105]
	s_setprio 0
	s_setprio 1
	v_mfma_f32_16x16x32_bf16 v[62:65], v[158:161], v[184:187], v[62:65]
	v_mfma_f32_16x16x32_bf16 v[62:65], v[162:165], v[188:191], v[62:65]
	v_mfma_f32_16x16x32_bf16 v[58:61], v[166:169], v[184:187], v[58:61]
	v_mfma_f32_16x16x32_bf16 v[58:61], v[170:173], v[188:191], v[58:61]
	v_mfma_f32_16x16x32_bf16 v[50:53], v[166:169], v[192:195], v[50:53]
	v_mfma_f32_16x16x32_bf16 v[50:53], v[170:173], v[196:199], v[50:53]
	v_mfma_f32_16x16x32_bf16 v[54:57], v[158:161], v[192:195], v[54:57]
	v_mfma_f32_16x16x32_bf16 v[54:57], v[162:165], v[196:199], v[54:57]
	v_mfma_f32_16x16x32_bf16 v[46:49], v[158:161], v[200:203], v[46:49]
	v_mfma_f32_16x16x32_bf16 v[46:49], v[162:165], v[206:209], v[46:49]
	v_mfma_f32_16x16x32_bf16 v[42:45], v[166:169], v[200:203], v[42:45]
	v_mfma_f32_16x16x32_bf16 v[42:45], v[170:173], v[206:209], v[42:45]
	v_mfma_f32_16x16x32_bf16 v[34:37], v[166:169], v[210:213], v[34:37]
	v_mfma_f32_16x16x32_bf16 v[34:37], v[170:173], v[214:217], v[34:37]
	v_mfma_f32_16x16x32_bf16 v[38:41], v[158:161], v[210:213], v[38:41]
	v_mfma_f32_16x16x32_bf16 v[38:41], v[162:165], v[214:217], v[38:41]
	s_setprio 0
	s_barrier
	s_mov_b32 m0, s27
	v_lshl_add_u64 v[218:219], s[64:65], 0, v[142:143]
	ds_read_b128 v[184:187], v183 offset:16384
	ds_read_b128 v[188:191], v183 offset:17408
	ds_read_b128 v[192:195], v183 offset:18432
	ds_read_b128 v[196:199], v183 offset:19456
	ds_read_b128 v[200:203], v183 offset:20480
	ds_read_b128 v[206:209], v183 offset:21504
	ds_read_b128 v[210:213], v183 offset:22528
	ds_read_b128 v[214:217], v183 offset:23552
	global_load_lds_dwordx4 v[218:219], off
	v_lshl_add_u64 v[220:221], s[64:65], 0, v[146:147]
	s_mov_b32 m0, s36
	v_lshl_add_u64 v[222:223], s[66:67], 0, v[142:143]
	global_load_lds_dwordx4 v[220:221], off
	s_mov_b32 m0, s29
	v_lshl_add_u64 v[224:225], s[62:63], 0, v[144:145]
	global_load_lds_dwordx4 v[222:223], off
	v_lshl_add_u64 v[222:223], s[66:67], 0, v[146:147]
	s_mov_b32 m0, s28
	s_nop 0
	global_load_lds_dwordx4 v[222:223], off
	v_lshl_add_u64 v[222:223], s[62:63], 0, v[140:141]
	s_mov_b32 m0, s69
	s_nop 0
	global_load_lds_dwordx4 v[222:223], off
	s_mov_b32 m0, s87
	s_nop 0
	global_load_lds_dwordx4 v[224:225], off
	s_waitcnt vmcnt(8)
	s_waitcnt lgkmcnt(0)
	s_barrier
	s_setprio 1
	s_waitcnt lgkmcnt(0)
	v_mfma_f32_16x16x32_bf16 v[94:97], v[130:133], v[184:187], v[94:97]
	v_mfma_f32_16x16x32_bf16 v[94:97], v[134:137], v[188:191], v[94:97]
	v_mfma_f32_16x16x32_bf16 v[90:93], v[150:153], v[184:187], v[90:93]
	v_mfma_f32_16x16x32_bf16 v[90:93], v[154:157], v[188:191], v[90:93]
	v_mfma_f32_16x16x32_bf16 v[82:85], v[150:153], v[192:195], v[82:85]
	v_mfma_f32_16x16x32_bf16 v[82:85], v[154:157], v[196:199], v[82:85]
	v_mfma_f32_16x16x32_bf16 v[86:89], v[130:133], v[192:195], v[86:89]
	v_mfma_f32_16x16x32_bf16 v[86:89], v[134:137], v[196:199], v[86:89]
	v_mfma_f32_16x16x32_bf16 v[78:81], v[130:133], v[200:203], v[78:81]
	v_mfma_f32_16x16x32_bf16 v[78:81], v[134:137], v[206:209], v[78:81]
	v_mfma_f32_16x16x32_bf16 v[74:77], v[150:153], v[200:203], v[74:77]
	v_mfma_f32_16x16x32_bf16 v[74:77], v[154:157], v[206:209], v[74:77]
	v_mfma_f32_16x16x32_bf16 v[66:69], v[150:153], v[210:213], v[66:69]
	v_mfma_f32_16x16x32_bf16 v[66:69], v[154:157], v[214:217], v[66:69]
	v_mfma_f32_16x16x32_bf16 v[70:73], v[130:133], v[210:213], v[70:73]
	v_mfma_f32_16x16x32_bf16 v[70:73], v[134:137], v[214:217], v[70:73]
	s_setprio 0
	s_setprio 1
	v_mfma_f32_16x16x32_bf16 v[30:33], v[158:161], v[184:187], v[30:33]
	v_mfma_f32_16x16x32_bf16 v[30:33], v[162:165], v[188:191], v[30:33]
	v_mfma_f32_16x16x32_bf16 v[26:29], v[166:169], v[184:187], v[26:29]
	v_mfma_f32_16x16x32_bf16 v[26:29], v[170:173], v[188:191], v[26:29]
	v_mfma_f32_16x16x32_bf16 v[18:21], v[166:169], v[192:195], v[18:21]
	v_mfma_f32_16x16x32_bf16 v[18:21], v[170:173], v[196:199], v[18:21]
	v_mfma_f32_16x16x32_bf16 v[22:25], v[158:161], v[192:195], v[22:25]
	v_mfma_f32_16x16x32_bf16 v[22:25], v[162:165], v[196:199], v[22:25]
	v_mfma_f32_16x16x32_bf16 v[14:17], v[158:161], v[200:203], v[14:17]
	v_mfma_f32_16x16x32_bf16 v[14:17], v[162:165], v[206:209], v[14:17]
	v_mfma_f32_16x16x32_bf16 v[10:13], v[166:169], v[200:203], v[10:13]
	v_mfma_f32_16x16x32_bf16 v[10:13], v[170:173], v[206:209], v[10:13]
	v_mfma_f32_16x16x32_bf16 v[2:5], v[166:169], v[210:213], v[2:5]
	v_mfma_f32_16x16x32_bf16 v[2:5], v[170:173], v[214:217], v[2:5]
	v_mfma_f32_16x16x32_bf16 v[6:9], v[158:161], v[210:213], v[6:9]
	v_mfma_f32_16x16x32_bf16 v[6:9], v[162:165], v[214:217], v[6:9]
	s_setprio 0
	s_barrier
	v_add_u32_e32 v148, s83, v179
	ds_read_b128 v[130:133], v148
	ds_read_b128 v[134:137], v148 offset:1024
	ds_read_b128 v[150:153], v148 offset:2048
	ds_read_b128 v[154:157], v148 offset:3072
	v_add_u32_e32 v148, s82, v179
	ds_read_b128 v[158:161], v148
	ds_read_b128 v[162:165], v148 offset:1024
	ds_read_b128 v[166:169], v148 offset:2048
	ds_read_b128 v[170:173], v148 offset:3072
	s_mov_b32 m0, s88
	v_lshl_add_u64 v[226:227], s[60:61], 0, v[140:141]
	ds_read_b128 v[184:187], v183 offset:32768
	ds_read_b128 v[188:191], v183 offset:33792
	ds_read_b128 v[192:195], v183 offset:34816
	ds_read_b128 v[196:199], v183 offset:35840
	ds_read_b128 v[200:203], v183 offset:36864
	ds_read_b128 v[206:209], v183 offset:37888
	ds_read_b128 v[210:213], v183 offset:38912
	ds_read_b128 v[214:217], v183 offset:39936
	global_load_lds_dwordx4 v[226:227], off
	v_lshl_add_u64 v[226:227], s[60:61], 0, v[144:145]
	s_mov_b32 m0, s89
	s_nop 0
	global_load_lds_dwordx4 v[226:227], off
	s_waitcnt vmcnt(8)
	s_waitcnt lgkmcnt(0)
	s_barrier
	s_setprio 1
	s_waitcnt lgkmcnt(0)
	v_mfma_f32_16x16x32_bf16 v[126:129], v[130:133], v[184:187], v[126:129]
	v_mfma_f32_16x16x32_bf16 v[126:129], v[134:137], v[188:191], v[126:129]
	v_mfma_f32_16x16x32_bf16 v[122:125], v[150:153], v[184:187], v[122:125]
	v_mfma_f32_16x16x32_bf16 v[122:125], v[154:157], v[188:191], v[122:125]
	v_mfma_f32_16x16x32_bf16 v[114:117], v[150:153], v[192:195], v[114:117]
	v_mfma_f32_16x16x32_bf16 v[114:117], v[154:157], v[196:199], v[114:117]
	v_mfma_f32_16x16x32_bf16 v[118:121], v[130:133], v[192:195], v[118:121]
	v_mfma_f32_16x16x32_bf16 v[118:121], v[134:137], v[196:199], v[118:121]
	v_mfma_f32_16x16x32_bf16 v[110:113], v[130:133], v[200:203], v[110:113]
	v_mfma_f32_16x16x32_bf16 v[110:113], v[134:137], v[206:209], v[110:113]
	v_mfma_f32_16x16x32_bf16 v[106:109], v[150:153], v[200:203], v[106:109]
	v_mfma_f32_16x16x32_bf16 v[106:109], v[154:157], v[206:209], v[106:109]
	v_mfma_f32_16x16x32_bf16 v[98:101], v[150:153], v[210:213], v[98:101]
	v_mfma_f32_16x16x32_bf16 v[98:101], v[154:157], v[214:217], v[98:101]
	v_mfma_f32_16x16x32_bf16 v[102:105], v[130:133], v[210:213], v[102:105]
	v_mfma_f32_16x16x32_bf16 v[102:105], v[134:137], v[214:217], v[102:105]
	s_setprio 0
	s_setprio 1
	v_mfma_f32_16x16x32_bf16 v[62:65], v[158:161], v[184:187], v[62:65]
	v_mfma_f32_16x16x32_bf16 v[62:65], v[162:165], v[188:191], v[62:65]
	v_mfma_f32_16x16x32_bf16 v[58:61], v[166:169], v[184:187], v[58:61]
	v_mfma_f32_16x16x32_bf16 v[58:61], v[170:173], v[188:191], v[58:61]
	v_mfma_f32_16x16x32_bf16 v[50:53], v[166:169], v[192:195], v[50:53]
	v_mfma_f32_16x16x32_bf16 v[50:53], v[170:173], v[196:199], v[50:53]
	v_mfma_f32_16x16x32_bf16 v[54:57], v[158:161], v[192:195], v[54:57]
	v_mfma_f32_16x16x32_bf16 v[54:57], v[162:165], v[196:199], v[54:57]
	v_mfma_f32_16x16x32_bf16 v[46:49], v[158:161], v[200:203], v[46:49]
	v_mfma_f32_16x16x32_bf16 v[46:49], v[162:165], v[206:209], v[46:49]
	v_mfma_f32_16x16x32_bf16 v[42:45], v[166:169], v[200:203], v[42:45]
	v_mfma_f32_16x16x32_bf16 v[42:45], v[170:173], v[206:209], v[42:45]
	v_mfma_f32_16x16x32_bf16 v[34:37], v[166:169], v[210:213], v[34:37]
	v_mfma_f32_16x16x32_bf16 v[34:37], v[170:173], v[214:217], v[34:37]
	v_mfma_f32_16x16x32_bf16 v[38:41], v[158:161], v[210:213], v[38:41]
	v_mfma_f32_16x16x32_bf16 v[38:41], v[162:165], v[214:217], v[38:41]
	s_setprio 0
	s_barrier
	s_mov_b32 m0, s81
	v_lshl_add_u64 v[218:219], v[218:219], 0, s[10:11]
	ds_read_b128 v[184:187], v183 offset:49152
	ds_read_b128 v[188:191], v183 offset:50176
	ds_read_b128 v[192:195], v183 offset:51200
	ds_read_b128 v[196:199], v183 offset:52224
	ds_read_b128 v[200:203], v183 offset:53248
	ds_read_b128 v[206:209], v183 offset:54272
	ds_read_b128 v[210:213], v183 offset:55296
	ds_read_b128 v[214:217], v183 offset:56320
	global_load_lds_dwordx4 v[218:219], off
	v_lshl_add_u64 v[218:219], v[220:221], 0, s[10:11]
	s_mov_b32 m0, s26
	s_nop 0
	global_load_lds_dwordx4 v[218:219], off
	v_lshl_add_u64 v[218:219], s[58:59], 0, v[142:143]
	s_mov_b32 m0, s80
	s_nop 0
	global_load_lds_dwordx4 v[218:219], off
	v_lshl_add_u64 v[218:219], s[58:59], 0, v[146:147]
	s_mov_b32 m0, s93
	s_nop 0
	global_load_lds_dwordx4 v[218:219], off
	v_lshl_add_u64 v[218:219], v[222:223], 0, s[10:11]
	s_mov_b32 m0, s90
	s_nop 0
	global_load_lds_dwordx4 v[218:219], off
	v_lshl_add_u64 v[218:219], v[224:225], 0, s[10:11]
	s_mov_b32 m0, s91
	s_nop 0
	global_load_lds_dwordx4 v[218:219], off
	s_waitcnt vmcnt(8)
	s_waitcnt lgkmcnt(0)
	s_barrier
	s_setprio 1
	s_waitcnt lgkmcnt(0)
	v_mfma_f32_16x16x32_bf16 v[94:97], v[130:133], v[184:187], v[94:97]
	v_mfma_f32_16x16x32_bf16 v[94:97], v[134:137], v[188:191], v[94:97]
	v_mfma_f32_16x16x32_bf16 v[90:93], v[150:153], v[184:187], v[90:93]
	v_mfma_f32_16x16x32_bf16 v[90:93], v[154:157], v[188:191], v[90:93]
	v_mfma_f32_16x16x32_bf16 v[82:85], v[150:153], v[192:195], v[82:85]
	v_mfma_f32_16x16x32_bf16 v[82:85], v[154:157], v[196:199], v[82:85]
	v_mfma_f32_16x16x32_bf16 v[86:89], v[130:133], v[192:195], v[86:89]
	v_mfma_f32_16x16x32_bf16 v[86:89], v[134:137], v[196:199], v[86:89]
	v_mfma_f32_16x16x32_bf16 v[78:81], v[130:133], v[200:203], v[78:81]
	v_mfma_f32_16x16x32_bf16 v[78:81], v[134:137], v[206:209], v[78:81]
	v_mfma_f32_16x16x32_bf16 v[74:77], v[150:153], v[200:203], v[74:77]
	v_mfma_f32_16x16x32_bf16 v[74:77], v[154:157], v[206:209], v[74:77]
	v_mfma_f32_16x16x32_bf16 v[66:69], v[150:153], v[210:213], v[66:69]
	v_mfma_f32_16x16x32_bf16 v[66:69], v[154:157], v[214:217], v[66:69]
	v_mfma_f32_16x16x32_bf16 v[70:73], v[130:133], v[210:213], v[70:73]
	v_mfma_f32_16x16x32_bf16 v[70:73], v[134:137], v[214:217], v[70:73]
	s_setprio 0
	s_setprio 1
	v_mfma_f32_16x16x32_bf16 v[30:33], v[158:161], v[184:187], v[30:33]
	v_mfma_f32_16x16x32_bf16 v[30:33], v[162:165], v[188:191], v[30:33]
	v_mfma_f32_16x16x32_bf16 v[26:29], v[166:169], v[184:187], v[26:29]
	v_mfma_f32_16x16x32_bf16 v[26:29], v[170:173], v[188:191], v[26:29]
	v_mfma_f32_16x16x32_bf16 v[18:21], v[166:169], v[192:195], v[18:21]
	v_mfma_f32_16x16x32_bf16 v[18:21], v[170:173], v[196:199], v[18:21]
	v_mfma_f32_16x16x32_bf16 v[22:25], v[158:161], v[192:195], v[22:25]
	v_mfma_f32_16x16x32_bf16 v[22:25], v[162:165], v[196:199], v[22:25]
	v_mfma_f32_16x16x32_bf16 v[14:17], v[158:161], v[200:203], v[14:17]
	v_mfma_f32_16x16x32_bf16 v[14:17], v[162:165], v[206:209], v[14:17]
	v_mfma_f32_16x16x32_bf16 v[10:13], v[166:169], v[200:203], v[10:13]
	v_mfma_f32_16x16x32_bf16 v[10:13], v[170:173], v[206:209], v[10:13]
	v_mfma_f32_16x16x32_bf16 v[2:5], v[166:169], v[210:213], v[2:5]
	v_mfma_f32_16x16x32_bf16 v[2:5], v[170:173], v[214:217], v[2:5]
	v_mfma_f32_16x16x32_bf16 v[6:9], v[158:161], v[210:213], v[6:9]
	v_mfma_f32_16x16x32_bf16 v[6:9], v[162:165], v[214:217], v[6:9]
	s_setprio 0
	s_barrier
	s_movk_i32 s60, 0x100
	s_andn2_b64 vcc, exec, s[52:53]
	s_mov_b64 s[58:59], -1
	s_mov_b64 s[52:53], 0
	s_cbranch_vccz .LBB0_955
	s_and_b64 vcc, exec, s[14:15]
	s_cbranch_vccz .LBB0_958
	s_barrier

.LBB0_985:
	s_add_u32 s41, s30, s40
	s_addc_u32 s42, s31, 0
	s_add_u32 s43, s41, 0x100
	s_addc_u32 s44, s42, 0
	s_and_b64 s[26:27], s[38:39], exec
	s_cselect_b32 s53, s17, s44
	s_cselect_b32 s52, s19, s43
	s_add_u32 s26, s28, s40
	s_addc_u32 s27, s29, 0
	s_add_u32 s40, s26, 0x100
	s_addc_u32 s43, s27, 0
	s_and_b64 s[26:27], s[38:39], exec
	s_cselect_b32 s55, s15, s43
	s_cselect_b32 s54, s73, s40
	s_add_u32 s58, s41, 0x20080
	ds_read_b128 v[148:151], v133
	ds_read_b128 v[152:155], v133 offset:1024
	ds_read_b128 v[156:159], v133 offset:2048
	ds_read_b128 v[160:163], v133 offset:3072
	ds_read_b128 v[164:167], v134
	ds_read_b128 v[168:171], v134 offset:1024
	ds_read_b128 v[172:175], v134 offset:2048
	ds_read_b128 v[176:179], v134 offset:3072
	s_addc_u32 s59, s42, 0
	s_add_i32 s81, s71, s60
	s_add_i32 m0, s61, 0xc000
	s_add_i32 s42, s61, 0xe000
	s_add_i32 s26, s81, 0x2000
	s_add_u32 s56, s54, 0x10000
	s_addc_u32 s57, s55, 0
	s_add_i32 s80, s72, s60
	s_add_i32 s27, s80, 0x2000
	s_add_i32 s79, 0, 0x18000
	s_add_i32 s78, 0, 0x1c000
	s_add_u32 s40, s52, 0x20000
	s_addc_u32 s41, s53, 0
	s_add_i32 s77, s79, s60
	s_add_i32 s75, s77, 0x2000
	s_add_u32 s38, s54, 0x10080
	s_addc_u32 s39, s55, 0
	s_add_i32 s76, s78, s60
	s_add_i32 s74, s76, 0x2000
	v_lshl_add_u64 v[136:137], s[58:59], 0, v[140:141]
	ds_read_b128 v[180:183], v135
	ds_read_b128 v[184:187], v135 offset:1024
	ds_read_b128 v[188:191], v135 offset:2048
	ds_read_b128 v[192:195], v135 offset:3072
	ds_read_b128 v[196:199], v135 offset:4096
	ds_read_b128 v[200:203], v135 offset:5120
	ds_read_b128 v[206:209], v135 offset:6144
	ds_read_b128 v[210:213], v135 offset:7168
	global_load_lds_dwordx4 v[136:137], off
	v_lshl_add_u64 v[136:137], s[58:59], 0, v[144:145]
	s_mov_b32 m0, s42
	s_nop 0
	global_load_lds_dwordx4 v[136:137], off
	s_waitcnt vmcnt(8)
	s_waitcnt lgkmcnt(0)
	s_barrier
	s_setprio 1
	s_waitcnt lgkmcnt(0)
	v_mfma_f32_16x16x32_bf16 v[126:129], v[148:151], v[180:183], v[126:129]
	v_mfma_f32_16x16x32_bf16 v[126:129], v[152:155], v[184:187], v[126:129]
	v_mfma_f32_16x16x32_bf16 v[122:125], v[156:159], v[180:183], v[122:125]
	v_mfma_f32_16x16x32_bf16 v[122:125], v[160:163], v[184:187], v[122:125]
	v_mfma_f32_16x16x32_bf16 v[114:117], v[156:159], v[188:191], v[114:117]
	v_mfma_f32_16x16x32_bf16 v[114:117], v[160:163], v[192:195], v[114:117]
	v_mfma_f32_16x16x32_bf16 v[118:121], v[148:151], v[188:191], v[118:121]
	v_mfma_f32_16x16x32_bf16 v[118:121], v[152:155], v[192:195], v[118:121]
	v_mfma_f32_16x16x32_bf16 v[102:105], v[148:151], v[196:199], v[102:105]
	v_mfma_f32_16x16x32_bf16 v[102:105], v[152:155], v[200:203], v[102:105]
	v_mfma_f32_16x16x32_bf16 v[98:101], v[156:159], v[196:199], v[98:101]
	v_mfma_f32_16x16x32_bf16 v[98:101], v[160:163], v[200:203], v[98:101]
	v_mfma_f32_16x16x32_bf16 v[82:85], v[156:159], v[206:209], v[82:85]
	v_mfma_f32_16x16x32_bf16 v[82:85], v[160:163], v[210:213], v[82:85]
	v_mfma_f32_16x16x32_bf16 v[86:89], v[148:151], v[206:209], v[86:89]
	v_mfma_f32_16x16x32_bf16 v[86:89], v[152:155], v[210:213], v[86:89]
	s_setprio 0
	s_setprio 1
	v_mfma_f32_16x16x32_bf16 v[110:113], v[164:167], v[180:183], v[110:113]
	v_mfma_f32_16x16x32_bf16 v[110:113], v[168:171], v[184:187], v[110:113]
	v_mfma_f32_16x16x32_bf16 v[106:109], v[172:175], v[180:183], v[106:109]
	v_mfma_f32_16x16x32_bf16 v[106:109], v[176:179], v[184:187], v[106:109]
	v_mfma_f32_16x16x32_bf16 v[90:93], v[172:175], v[188:191], v[90:93]
	v_mfma_f32_16x16x32_bf16 v[90:93], v[176:179], v[192:195], v[90:93]
	v_mfma_f32_16x16x32_bf16 v[94:97], v[164:167], v[188:191], v[94:97]
	v_mfma_f32_16x16x32_bf16 v[94:97], v[168:171], v[192:195], v[94:97]
	v_mfma_f32_16x16x32_bf16 v[78:81], v[164:167], v[196:199], v[78:81]
	v_mfma_f32_16x16x32_bf16 v[78:81], v[168:171], v[200:203], v[78:81]
	v_mfma_f32_16x16x32_bf16 v[74:77], v[172:175], v[196:199], v[74:77]
	v_mfma_f32_16x16x32_bf16 v[74:77], v[176:179], v[200:203], v[74:77]
	v_mfma_f32_16x16x32_bf16 v[66:69], v[172:175], v[206:209], v[66:69]
	v_mfma_f32_16x16x32_bf16 v[66:69], v[176:179], v[210:213], v[66:69]
	v_mfma_f32_16x16x32_bf16 v[70:73], v[164:167], v[206:209], v[70:73]
	v_mfma_f32_16x16x32_bf16 v[70:73], v[168:171], v[210:213], v[70:73]
	s_setprio 0
	s_barrier
	s_mov_b32 m0, s81
	v_lshl_add_u64 v[136:137], s[54:55], 0, v[142:143]
	ds_read_b128 v[180:183], v135 offset:16384
	ds_read_b128 v[184:187], v135 offset:17408
	ds_read_b128 v[188:191], v135 offset:18432
	ds_read_b128 v[192:195], v135 offset:19456
	ds_read_b128 v[196:199], v135 offset:20480
	ds_read_b128 v[200:203], v135 offset:21504
	ds_read_b128 v[206:209], v135 offset:22528
	ds_read_b128 v[210:213], v135 offset:23552
	global_load_lds_dwordx4 v[136:137], off
	v_lshl_add_u64 v[214:215], s[54:55], 0, v[146:147]
	s_mov_b32 m0, s26
	v_lshl_add_u64 v[216:217], s[56:57], 0, v[142:143]
	global_load_lds_dwordx4 v[214:215], off
	s_mov_b32 m0, s80
	v_lshl_add_u64 v[218:219], s[52:53], 0, v[144:145]
	global_load_lds_dwordx4 v[216:217], off
	v_lshl_add_u64 v[216:217], s[56:57], 0, v[146:147]
	s_mov_b32 m0, s27
	s_nop 0
	global_load_lds_dwordx4 v[216:217], off
	v_lshl_add_u64 v[216:217], s[52:53], 0, v[140:141]
	s_mov_b32 m0, s61
	s_nop 0
	global_load_lds_dwordx4 v[216:217], off
	s_mov_b32 m0, s62
	s_nop 0
	global_load_lds_dwordx4 v[218:219], off
	s_waitcnt vmcnt(8)
	s_waitcnt lgkmcnt(0)
	s_barrier
	s_setprio 1
	s_waitcnt lgkmcnt(0)
	v_mfma_f32_16x16x32_bf16 v[62:65], v[148:151], v[180:183], v[62:65]
	v_mfma_f32_16x16x32_bf16 v[62:65], v[152:155], v[184:187], v[62:65]
	v_mfma_f32_16x16x32_bf16 v[58:61], v[156:159], v[180:183], v[58:61]
	v_mfma_f32_16x16x32_bf16 v[58:61], v[160:163], v[184:187], v[58:61]
	v_mfma_f32_16x16x32_bf16 v[50:53], v[156:159], v[188:191], v[50:53]
	v_mfma_f32_16x16x32_bf16 v[50:53], v[160:163], v[192:195], v[50:53]
	v_mfma_f32_16x16x32_bf16 v[54:57], v[148:151], v[188:191], v[54:57]
	v_mfma_f32_16x16x32_bf16 v[54:57], v[152:155], v[192:195], v[54:57]
	v_mfma_f32_16x16x32_bf16 v[38:41], v[148:151], v[196:199], v[38:41]
	v_mfma_f32_16x16x32_bf16 v[38:41], v[152:155], v[200:203], v[38:41]
	v_mfma_f32_16x16x32_bf16 v[34:37], v[156:159], v[196:199], v[34:37]
	v_mfma_f32_16x16x32_bf16 v[34:37], v[160:163], v[200:203], v[34:37]
	v_mfma_f32_16x16x32_bf16 v[18:21], v[156:159], v[206:209], v[18:21]
	v_mfma_f32_16x16x32_bf16 v[18:21], v[160:163], v[210:213], v[18:21]
	v_mfma_f32_16x16x32_bf16 v[22:25], v[148:151], v[206:209], v[22:25]
	v_mfma_f32_16x16x32_bf16 v[22:25], v[152:155], v[210:213], v[22:25]
	s_setprio 0
	s_setprio 1
	v_mfma_f32_16x16x32_bf16 v[46:49], v[164:167], v[180:183], v[46:49]
	v_mfma_f32_16x16x32_bf16 v[46:49], v[168:171], v[184:187], v[46:49]
	v_mfma_f32_16x16x32_bf16 v[42:45], v[172:175], v[180:183], v[42:45]
	v_mfma_f32_16x16x32_bf16 v[42:45], v[176:179], v[184:187], v[42:45]
	v_mfma_f32_16x16x32_bf16 v[26:29], v[172:175], v[188:191], v[26:29]
	v_mfma_f32_16x16x32_bf16 v[26:29], v[176:179], v[192:195], v[26:29]
	v_mfma_f32_16x16x32_bf16 v[30:33], v[164:167], v[188:191], v[30:33]
	v_mfma_f32_16x16x32_bf16 v[30:33], v[168:171], v[192:195], v[30:33]
	v_mfma_f32_16x16x32_bf16 v[14:17], v[164:167], v[196:199], v[14:17]
	v_mfma_f32_16x16x32_bf16 v[14:17], v[168:171], v[200:203], v[14:17]
	v_mfma_f32_16x16x32_bf16 v[10:13], v[172:175], v[196:199], v[10:13]
	v_mfma_f32_16x16x32_bf16 v[10:13], v[176:179], v[200:203], v[10:13]
	v_mfma_f32_16x16x32_bf16 v[2:5], v[172:175], v[206:209], v[2:5]
	v_mfma_f32_16x16x32_bf16 v[2:5], v[176:179], v[210:213], v[2:5]
	v_mfma_f32_16x16x32_bf16 v[6:9], v[164:167], v[206:209], v[6:9]
	v_mfma_f32_16x16x32_bf16 v[6:9], v[168:171], v[210:213], v[6:9]
	s_setprio 0
	s_barrier
	v_add_u32_e32 v160, s79, v131
	v_add_u32_e32 v176, s78, v131
	ds_read_b128 v[148:151], v160
	ds_read_b128 v[152:155], v160 offset:1024
	ds_read_b128 v[156:159], v160 offset:2048
	ds_read_b128 v[160:163], v160 offset:3072
	ds_read_b128 v[164:167], v176
	ds_read_b128 v[168:171], v176 offset:1024
	ds_read_b128 v[172:175], v176 offset:2048
	ds_read_b128 v[176:179], v176 offset:3072
	s_mov_b32 m0, s63
	v_lshl_add_u64 v[220:221], s[40:41], 0, v[140:141]
	ds_read_b128 v[180:183], v135 offset:32768
	ds_read_b128 v[184:187], v135 offset:33792
	ds_read_b128 v[188:191], v135 offset:34816
	ds_read_b128 v[192:195], v135 offset:35840
	ds_read_b128 v[196:199], v135 offset:36864
	ds_read_b128 v[200:203], v135 offset:37888
	ds_read_b128 v[206:209], v135 offset:38912
	ds_read_b128 v[210:213], v135 offset:39936
	global_load_lds_dwordx4 v[220:221], off
	v_lshl_add_u64 v[220:221], s[40:41], 0, v[144:145]
	s_mov_b32 m0, s64
	s_nop 0
	global_load_lds_dwordx4 v[220:221], off
	s_waitcnt vmcnt(8)
	s_waitcnt lgkmcnt(0)
	s_barrier
	s_setprio 1
	s_waitcnt lgkmcnt(0)
	v_mfma_f32_16x16x32_bf16 v[126:129], v[148:151], v[180:183], v[126:129]
	v_mfma_f32_16x16x32_bf16 v[126:129], v[152:155], v[184:187], v[126:129]
	v_mfma_f32_16x16x32_bf16 v[122:125], v[156:159], v[180:183], v[122:125]
	v_mfma_f32_16x16x32_bf16 v[122:125], v[160:163], v[184:187], v[122:125]
	v_mfma_f32_16x16x32_bf16 v[114:117], v[156:159], v[188:191], v[114:117]
	v_mfma_f32_16x16x32_bf16 v[114:117], v[160:163], v[192:195], v[114:117]
	v_mfma_f32_16x16x32_bf16 v[118:121], v[148:151], v[188:191], v[118:121]
	v_mfma_f32_16x16x32_bf16 v[118:121], v[152:155], v[192:195], v[118:121]
	v_mfma_f32_16x16x32_bf16 v[102:105], v[148:151], v[196:199], v[102:105]
	v_mfma_f32_16x16x32_bf16 v[102:105], v[152:155], v[200:203], v[102:105]
	v_mfma_f32_16x16x32_bf16 v[98:101], v[156:159], v[196:199], v[98:101]
	v_mfma_f32_16x16x32_bf16 v[98:101], v[160:163], v[200:203], v[98:101]
	v_mfma_f32_16x16x32_bf16 v[82:85], v[156:159], v[206:209], v[82:85]
	v_mfma_f32_16x16x32_bf16 v[82:85], v[160:163], v[210:213], v[82:85]
	v_mfma_f32_16x16x32_bf16 v[86:89], v[148:151], v[206:209], v[86:89]
	v_mfma_f32_16x16x32_bf16 v[86:89], v[152:155], v[210:213], v[86:89]
	s_setprio 0
	s_setprio 1
	v_mfma_f32_16x16x32_bf16 v[110:113], v[164:167], v[180:183], v[110:113]
	v_mfma_f32_16x16x32_bf16 v[110:113], v[168:171], v[184:187], v[110:113]
	v_mfma_f32_16x16x32_bf16 v[106:109], v[172:175], v[180:183], v[106:109]
	v_mfma_f32_16x16x32_bf16 v[106:109], v[176:179], v[184:187], v[106:109]
	v_mfma_f32_16x16x32_bf16 v[90:93], v[172:175], v[188:191], v[90:93]
	v_mfma_f32_16x16x32_bf16 v[90:93], v[176:179], v[192:195], v[90:93]
	v_mfma_f32_16x16x32_bf16 v[94:97], v[164:167], v[188:191], v[94:97]
	v_mfma_f32_16x16x32_bf16 v[94:97], v[168:171], v[192:195], v[94:97]
	v_mfma_f32_16x16x32_bf16 v[78:81], v[164:167], v[196:199], v[78:81]
	v_mfma_f32_16x16x32_bf16 v[78:81], v[168:171], v[200:203], v[78:81]
	v_mfma_f32_16x16x32_bf16 v[74:77], v[172:175], v[196:199], v[74:77]
	v_mfma_f32_16x16x32_bf16 v[74:77], v[176:179], v[200:203], v[74:77]
	v_mfma_f32_16x16x32_bf16 v[66:69], v[172:175], v[206:209], v[66:69]
	v_mfma_f32_16x16x32_bf16 v[66:69], v[176:179], v[210:213], v[66:69]
	v_mfma_f32_16x16x32_bf16 v[70:73], v[164:167], v[206:209], v[70:73]
	v_mfma_f32_16x16x32_bf16 v[70:73], v[168:171], v[210:213], v[70:73]
	s_setprio 0
	s_barrier
	s_mov_b32 m0, s77
	v_lshl_add_u64 v[136:137], v[136:137], 0, s[8:9]
	ds_read_b128 v[180:183], v135 offset:49152
	ds_read_b128 v[184:187], v135 offset:50176
	ds_read_b128 v[188:191], v135 offset:51200
	ds_read_b128 v[192:195], v135 offset:52224
	ds_read_b128 v[196:199], v135 offset:53248
	ds_read_b128 v[200:203], v135 offset:54272
	ds_read_b128 v[206:209], v135 offset:55296
	ds_read_b128 v[210:213], v135 offset:56320
	global_load_lds_dwordx4 v[136:137], off
	v_lshl_add_u64 v[136:137], v[214:215], 0, s[8:9]
	s_mov_b32 m0, s75
	s_nop 0
	global_load_lds_dwordx4 v[136:137], off
	v_lshl_add_u64 v[136:137], s[38:39], 0, v[142:143]
	s_mov_b32 m0, s76
	s_nop 0
	global_load_lds_dwordx4 v[136:137], off
	v_lshl_add_u64 v[136:137], s[38:39], 0, v[146:147]
	s_mov_b32 m0, s74
	s_nop 0
	global_load_lds_dwordx4 v[136:137], off
	v_lshl_add_u64 v[136:137], v[216:217], 0, s[8:9]
	s_mov_b32 m0, s65
	s_nop 0
	global_load_lds_dwordx4 v[136:137], off
	v_lshl_add_u64 v[136:137], v[218:219], 0, s[8:9]
	s_mov_b32 m0, s66
	s_nop 0
	global_load_lds_dwordx4 v[136:137], off
	s_waitcnt vmcnt(8)
	s_waitcnt lgkmcnt(0)
	s_barrier
	s_setprio 1
	s_waitcnt lgkmcnt(0)
	v_mfma_f32_16x16x32_bf16 v[62:65], v[148:151], v[180:183], v[62:65]
	v_mfma_f32_16x16x32_bf16 v[62:65], v[152:155], v[184:187], v[62:65]
	v_mfma_f32_16x16x32_bf16 v[58:61], v[156:159], v[180:183], v[58:61]
	v_mfma_f32_16x16x32_bf16 v[58:61], v[160:163], v[184:187], v[58:61]
	v_mfma_f32_16x16x32_bf16 v[50:53], v[156:159], v[188:191], v[50:53]
	v_mfma_f32_16x16x32_bf16 v[50:53], v[160:163], v[192:195], v[50:53]
	v_mfma_f32_16x16x32_bf16 v[54:57], v[148:151], v[188:191], v[54:57]
	v_mfma_f32_16x16x32_bf16 v[54:57], v[152:155], v[192:195], v[54:57]
	v_mfma_f32_16x16x32_bf16 v[38:41], v[148:151], v[196:199], v[38:41]
	v_mfma_f32_16x16x32_bf16 v[38:41], v[152:155], v[200:203], v[38:41]
	v_mfma_f32_16x16x32_bf16 v[34:37], v[156:159], v[196:199], v[34:37]
	v_mfma_f32_16x16x32_bf16 v[34:37], v[160:163], v[200:203], v[34:37]
	v_mfma_f32_16x16x32_bf16 v[18:21], v[156:159], v[206:209], v[18:21]
	v_mfma_f32_16x16x32_bf16 v[18:21], v[160:163], v[210:213], v[18:21]
	v_mfma_f32_16x16x32_bf16 v[22:25], v[148:151], v[206:209], v[22:25]
	v_mfma_f32_16x16x32_bf16 v[22:25], v[152:155], v[210:213], v[22:25]
	s_setprio 0
	s_setprio 1
	v_mfma_f32_16x16x32_bf16 v[46:49], v[164:167], v[180:183], v[46:49]
	v_mfma_f32_16x16x32_bf16 v[46:49], v[168:171], v[184:187], v[46:49]
	v_mfma_f32_16x16x32_bf16 v[42:45], v[172:175], v[180:183], v[42:45]
	v_mfma_f32_16x16x32_bf16 v[42:45], v[176:179], v[184:187], v[42:45]
	v_mfma_f32_16x16x32_bf16 v[26:29], v[172:175], v[188:191], v[26:29]
	v_mfma_f32_16x16x32_bf16 v[26:29], v[176:179], v[192:195], v[26:29]
	v_mfma_f32_16x16x32_bf16 v[30:33], v[164:167], v[188:191], v[30:33]
	v_mfma_f32_16x16x32_bf16 v[30:33], v[168:171], v[192:195], v[30:33]
	v_mfma_f32_16x16x32_bf16 v[14:17], v[164:167], v[196:199], v[14:17]
	v_mfma_f32_16x16x32_bf16 v[14:17], v[168:171], v[200:203], v[14:17]
	v_mfma_f32_16x16x32_bf16 v[10:13], v[172:175], v[196:199], v[10:13]
	v_mfma_f32_16x16x32_bf16 v[10:13], v[176:179], v[200:203], v[10:13]
	v_mfma_f32_16x16x32_bf16 v[2:5], v[172:175], v[206:209], v[2:5]
	v_mfma_f32_16x16x32_bf16 v[2:5], v[176:179], v[210:213], v[2:5]
	v_mfma_f32_16x16x32_bf16 v[6:9], v[164:167], v[206:209], v[6:9]
	v_mfma_f32_16x16x32_bf16 v[6:9], v[168:171], v[210:213], v[6:9]
	s_setprio 0
	s_barrier
	s_movk_i32 s40, 0x100
	s_andn2_b64 vcc, exec, s[36:37]
	s_mov_b64 s[38:39], -1
	s_mov_b64 s[36:37], 0
	s_cbranch_vccz .LBB0_985
	s_and_b64 vcc, exec, s[10:11]
	s_cbranch_vccz .LBB0_988
	s_barrier

.LBB0_1285:
	v_add_u32_e32 v3, s90, v206
	ds_read_b128 v[176:179], v3
	ds_read_b128 v[180:183], v3 offset:1024
	ds_read_b128 v[184:187], v3 offset:2048
	ds_read_b128 v[188:191], v3 offset:3072
	v_add_u32_e32 v3, s91, v206
	ds_read_b128 v[192:195], v3
	ds_read_b128 v[196:199], v3 offset:1024
	ds_read_b128 v[200:203], v3 offset:2048
	ds_read_b128 v[210:213], v3 offset:3072
	s_add_i32 s14, s58, 2
	s_add_u32 s59, s56, 0xfff00080
	s_addc_u32 s60, s57, -1
	s_cmp_eq_u32 s92, s58
	s_cselect_b32 s61, s1, s60
	s_cselect_b32 s60, s45, s59
	s_cselect_b32 s59, s47, s82
	s_cselect_b32 s58, s49, s93
	v_lshl_add_u64 v[4:5], s[56:57], 0, v[148:149]
	s_add_i32 m0, s55, 0xc000
	ds_read_b128 v[214:217], v208
	ds_read_b128 v[218:221], v208 offset:1024
	ds_read_b128 v[222:225], v208 offset:2048
	ds_read_b128 v[226:229], v208 offset:3072
	ds_read_b128 v[230:233], v208 offset:4096
	ds_read_b128 v[234:237], v208 offset:5120
	ds_read_b128 v[238:241], v208 offset:6144
	ds_read_b128 v[242:245], v208 offset:7168
	global_load_lds_dwordx4 v[4:5], off
	v_lshl_add_u64 v[4:5], s[56:57], 0, v[150:151]
	s_add_i32 m0, s55, 0xe000
	s_nop 0
	global_load_lds_dwordx4 v[4:5], off
	s_waitcnt vmcnt(8)
	s_waitcnt lgkmcnt(0)
	s_barrier
	s_setprio 1
	s_waitcnt lgkmcnt(0)
	v_mfma_f32_16x16x32_bf16 v[106:109], v[176:179], v[214:217], v[106:109]
	v_mfma_f32_16x16x32_bf16 v[106:109], v[180:183], v[218:221], v[106:109]
	v_mfma_f32_16x16x32_bf16 v[114:117], v[184:187], v[214:217], v[114:117]
	v_mfma_f32_16x16x32_bf16 v[114:117], v[188:191], v[218:221], v[114:117]
	v_mfma_f32_16x16x32_bf16 v[110:113], v[184:187], v[222:225], v[110:113]
	v_mfma_f32_16x16x32_bf16 v[110:113], v[188:191], v[226:229], v[110:113]
	v_mfma_f32_16x16x32_bf16 v[102:105], v[176:179], v[222:225], v[102:105]
	v_mfma_f32_16x16x32_bf16 v[102:105], v[180:183], v[226:229], v[102:105]
	v_mfma_f32_16x16x32_bf16 v[90:93], v[176:179], v[230:233], v[90:93]
	v_mfma_f32_16x16x32_bf16 v[90:93], v[180:183], v[234:237], v[90:93]
	v_mfma_f32_16x16x32_bf16 v[86:89], v[184:187], v[230:233], v[86:89]
	v_mfma_f32_16x16x32_bf16 v[86:89], v[188:191], v[234:237], v[86:89]
	v_mfma_f32_16x16x32_bf16 v[70:73], v[184:187], v[238:241], v[70:73]
	v_mfma_f32_16x16x32_bf16 v[70:73], v[188:191], v[242:245], v[70:73]
	v_mfma_f32_16x16x32_bf16 v[74:77], v[176:179], v[238:241], v[74:77]
	v_mfma_f32_16x16x32_bf16 v[74:77], v[180:183], v[242:245], v[74:77]
	s_setprio 0
	s_setprio 1
	v_mfma_f32_16x16x32_bf16 v[126:129], v[192:195], v[214:217], v[126:129]
	v_mfma_f32_16x16x32_bf16 v[126:129], v[196:199], v[218:221], v[126:129]
	v_mfma_f32_16x16x32_bf16 v[130:133], v[200:203], v[214:217], v[130:133]
	v_mfma_f32_16x16x32_bf16 v[130:133], v[210:213], v[218:221], v[130:133]
	v_mfma_f32_16x16x32_bf16 v[118:121], v[200:203], v[222:225], v[118:121]
	v_mfma_f32_16x16x32_bf16 v[118:121], v[210:213], v[226:229], v[118:121]
	v_mfma_f32_16x16x32_bf16 v[122:125], v[192:195], v[222:225], v[122:125]
	v_mfma_f32_16x16x32_bf16 v[122:125], v[196:199], v[226:229], v[122:125]
	v_mfma_f32_16x16x32_bf16 v[98:101], v[192:195], v[230:233], v[98:101]
	v_mfma_f32_16x16x32_bf16 v[98:101], v[196:199], v[234:237], v[98:101]
	v_mfma_f32_16x16x32_bf16 v[94:97], v[200:203], v[230:233], v[94:97]
	v_mfma_f32_16x16x32_bf16 v[94:97], v[210:213], v[234:237], v[94:97]
	v_mfma_f32_16x16x32_bf16 v[78:81], v[200:203], v[238:241], v[78:81]
	v_mfma_f32_16x16x32_bf16 v[78:81], v[210:213], v[242:245], v[78:81]
	v_mfma_f32_16x16x32_bf16 v[82:85], v[192:195], v[238:241], v[82:85]
	v_mfma_f32_16x16x32_bf16 v[82:85], v[196:199], v[242:245], v[82:85]
	s_setprio 0
	s_barrier
	s_add_i32 vcc_lo, s90, s66
	v_lshl_add_u64 v[246:247], s[58:59], 0, v[140:141]
	s_mov_b32 m0, vcc_lo
	ds_read_b128 v[214:217], v208 offset:16384
	ds_read_b128 v[218:221], v208 offset:17408
	ds_read_b128 v[222:225], v208 offset:18432
	ds_read_b128 v[226:229], v208 offset:19456
	ds_read_b128 v[230:233], v208 offset:20480
	ds_read_b128 v[234:237], v208 offset:21504
	ds_read_b128 v[238:241], v208 offset:22528
	ds_read_b128 v[242:245], v208 offset:23552
	global_load_lds_dwordx4 v[246:247], off
	s_add_i32 m0, vcc_lo, 0x2000
	s_add_u32 vcc_lo, s58, 0x100000
	v_lshl_add_u64 v[248:249], s[58:59], 0, v[144:145]
	s_addc_u32 vcc_hi, s59, 0
	s_add_i32 s83, s91, s66
	global_load_lds_dwordx4 v[248:249], off
	v_lshl_add_u64 v[4:5], vcc, 0, v[140:141]
	s_mov_b32 m0, s83
	v_lshl_add_u64 v[250:251], s[60:61], 0, v[136:137]
	global_load_lds_dwordx4 v[4:5], off
	v_lshl_add_u64 v[4:5], vcc, 0, v[144:145]
	s_add_i32 m0, s83, 0x2000
	v_lshl_add_u64 v[252:253], s[60:61], 0, v[142:143]
	global_load_lds_dwordx4 v[4:5], off
	s_mov_b32 m0, s55
	s_nop 0
	global_load_lds_dwordx4 v[250:251], off
	s_mov_b32 m0, s72
	s_nop 0
	global_load_lds_dwordx4 v[252:253], off
	s_waitcnt vmcnt(8)
	s_waitcnt lgkmcnt(0)
	s_barrier
	s_setprio 1
	s_waitcnt lgkmcnt(0)
	v_mfma_f32_16x16x32_bf16 v[66:69], v[176:179], v[214:217], v[66:69]
	v_mfma_f32_16x16x32_bf16 v[66:69], v[180:183], v[218:221], v[66:69]
	v_mfma_f32_16x16x32_bf16 v[58:61], v[184:187], v[214:217], v[58:61]
	v_mfma_f32_16x16x32_bf16 v[58:61], v[188:191], v[218:221], v[58:61]
	v_mfma_f32_16x16x32_bf16 v[42:45], v[184:187], v[222:225], v[42:45]
	v_mfma_f32_16x16x32_bf16 v[42:45], v[188:191], v[226:229], v[42:45]
	v_mfma_f32_16x16x32_bf16 v[50:53], v[176:179], v[222:225], v[50:53]
	v_mfma_f32_16x16x32_bf16 v[50:53], v[180:183], v[226:229], v[50:53]
	v_mfma_f32_16x16x32_bf16 v[34:37], v[176:179], v[230:233], v[34:37]
	v_mfma_f32_16x16x32_bf16 v[34:37], v[180:183], v[234:237], v[34:37]
	v_mfma_f32_16x16x32_bf16 v[26:29], v[184:187], v[230:233], v[26:29]
	v_mfma_f32_16x16x32_bf16 v[26:29], v[188:191], v[234:237], v[26:29]
	v_mfma_f32_16x16x32_bf16 v[10:13], v[184:187], v[238:241], v[10:13]
	v_mfma_f32_16x16x32_bf16 v[10:13], v[188:191], v[242:245], v[10:13]
	v_mfma_f32_16x16x32_bf16 v[18:21], v[176:179], v[238:241], v[18:21]
	v_mfma_f32_16x16x32_bf16 v[18:21], v[180:183], v[242:245], v[18:21]
	s_setprio 0
	s_setprio 1
	v_mfma_f32_16x16x32_bf16 v[62:65], v[192:195], v[214:217], v[62:65]
	v_mfma_f32_16x16x32_bf16 v[62:65], v[196:199], v[218:221], v[62:65]
	v_mfma_f32_16x16x32_bf16 v[54:57], v[200:203], v[214:217], v[54:57]
	v_mfma_f32_16x16x32_bf16 v[54:57], v[210:213], v[218:221], v[54:57]
	v_mfma_f32_16x16x32_bf16 v[38:41], v[200:203], v[222:225], v[38:41]
	v_mfma_f32_16x16x32_bf16 v[38:41], v[210:213], v[226:229], v[38:41]
	v_mfma_f32_16x16x32_bf16 v[46:49], v[192:195], v[222:225], v[46:49]
	v_mfma_f32_16x16x32_bf16 v[46:49], v[196:199], v[226:229], v[46:49]
	v_mfma_f32_16x16x32_bf16 v[30:33], v[192:195], v[230:233], v[30:33]
	v_mfma_f32_16x16x32_bf16 v[30:33], v[196:199], v[234:237], v[30:33]
	v_mfma_f32_16x16x32_bf16 v[22:25], v[200:203], v[230:233], v[22:25]
	v_mfma_f32_16x16x32_bf16 v[22:25], v[210:213], v[234:237], v[22:25]
	v_mfma_f32_16x16x32_bf16 v[4:7], v[200:203], v[238:241], v[6:9]
	v_mfma_f32_16x16x32_bf16 v[4:7], v[210:213], v[242:245], v[4:7]
	v_mfma_f32_16x16x32_bf16 v[14:17], v[192:195], v[238:241], v[14:17]
	v_mfma_f32_16x16x32_bf16 v[14:17], v[196:199], v[242:245], v[14:17]
	s_setprio 0
	s_barrier
	s_add_i32 s83, 0, 0x18000
	v_add_u32_e32 v3, s83, v206
	s_add_i32 vcc_lo, 0, 0x1c000
	ds_read_b128 v[176:179], v3
	ds_read_b128 v[180:183], v3 offset:1024
	ds_read_b128 v[184:187], v3 offset:2048
	ds_read_b128 v[188:191], v3 offset:3072
	v_add_u32_e32 v3, vcc_lo, v206
	ds_read_b128 v[192:195], v3
	ds_read_b128 v[196:199], v3 offset:1024
	ds_read_b128 v[200:203], v3 offset:2048
	ds_read_b128 v[210:213], v3 offset:3072
	s_add_u32 s60, s60, 0x100000
	s_addc_u32 s61, s61, 0
	s_mov_b32 m0, s73
	v_lshl_add_u64 v[8:9], s[60:61], 0, v[136:137]
	ds_read_b128 v[214:217], v208 offset:32768
	ds_read_b128 v[218:221], v208 offset:33792
	ds_read_b128 v[222:225], v208 offset:34816
	ds_read_b128 v[226:229], v208 offset:35840
	ds_read_b128 v[230:233], v208 offset:36864
	ds_read_b128 v[234:237], v208 offset:37888
	ds_read_b128 v[238:241], v208 offset:38912
	ds_read_b128 v[242:245], v208 offset:39936
	global_load_lds_dwordx4 v[8:9], off
	v_lshl_add_u64 v[8:9], s[60:61], 0, v[142:143]
	s_mov_b32 m0, s74
	s_nop 0
	global_load_lds_dwordx4 v[8:9], off
	s_waitcnt vmcnt(8)
	s_waitcnt lgkmcnt(0)
	s_barrier
	s_setprio 1
	s_waitcnt lgkmcnt(0)
	v_mfma_f32_16x16x32_bf16 v[106:109], v[176:179], v[214:217], v[106:109]
	v_mfma_f32_16x16x32_bf16 v[106:109], v[180:183], v[218:221], v[106:109]
	v_mfma_f32_16x16x32_bf16 v[114:117], v[184:187], v[214:217], v[114:117]
	v_mfma_f32_16x16x32_bf16 v[114:117], v[188:191], v[218:221], v[114:117]
	v_mfma_f32_16x16x32_bf16 v[110:113], v[184:187], v[222:225], v[110:113]
	v_mfma_f32_16x16x32_bf16 v[110:113], v[188:191], v[226:229], v[110:113]
	v_mfma_f32_16x16x32_bf16 v[102:105], v[176:179], v[222:225], v[102:105]
	v_mfma_f32_16x16x32_bf16 v[102:105], v[180:183], v[226:229], v[102:105]
	v_mfma_f32_16x16x32_bf16 v[90:93], v[176:179], v[230:233], v[90:93]
	v_mfma_f32_16x16x32_bf16 v[90:93], v[180:183], v[234:237], v[90:93]
	v_mfma_f32_16x16x32_bf16 v[86:89], v[184:187], v[230:233], v[86:89]
	v_mfma_f32_16x16x32_bf16 v[86:89], v[188:191], v[234:237], v[86:89]
	v_mfma_f32_16x16x32_bf16 v[70:73], v[184:187], v[238:241], v[70:73]
	v_mfma_f32_16x16x32_bf16 v[70:73], v[188:191], v[242:245], v[70:73]
	v_mfma_f32_16x16x32_bf16 v[74:77], v[176:179], v[238:241], v[74:77]
	v_mfma_f32_16x16x32_bf16 v[74:77], v[180:183], v[242:245], v[74:77]
	s_setprio 0
	s_setprio 1
	v_mfma_f32_16x16x32_bf16 v[126:129], v[192:195], v[214:217], v[126:129]
	v_mfma_f32_16x16x32_bf16 v[126:129], v[196:199], v[218:221], v[126:129]
	v_mfma_f32_16x16x32_bf16 v[130:133], v[200:203], v[214:217], v[130:133]
	v_mfma_f32_16x16x32_bf16 v[130:133], v[210:213], v[218:221], v[130:133]
	v_mfma_f32_16x16x32_bf16 v[118:121], v[200:203], v[222:225], v[118:121]
	v_mfma_f32_16x16x32_bf16 v[118:121], v[210:213], v[226:229], v[118:121]
	v_mfma_f32_16x16x32_bf16 v[122:125], v[192:195], v[222:225], v[122:125]
	v_mfma_f32_16x16x32_bf16 v[122:125], v[196:199], v[226:229], v[122:125]
	v_mfma_f32_16x16x32_bf16 v[98:101], v[192:195], v[230:233], v[98:101]
	v_mfma_f32_16x16x32_bf16 v[98:101], v[196:199], v[234:237], v[98:101]
	v_mfma_f32_16x16x32_bf16 v[94:97], v[200:203], v[230:233], v[94:97]
	v_mfma_f32_16x16x32_bf16 v[94:97], v[210:213], v[234:237], v[94:97]
	v_mfma_f32_16x16x32_bf16 v[78:81], v[200:203], v[238:241], v[78:81]
	v_mfma_f32_16x16x32_bf16 v[78:81], v[210:213], v[242:245], v[78:81]
	v_mfma_f32_16x16x32_bf16 v[82:85], v[192:195], v[238:241], v[82:85]
	v_mfma_f32_16x16x32_bf16 v[82:85], v[196:199], v[242:245], v[82:85]
	s_setprio 0
	s_barrier
	s_add_i32 s60, s83, s66
	v_lshl_add_u64 v[8:9], v[246:247], 0, s[20:21]
	s_mov_b32 m0, s60
	ds_read_b128 v[214:217], v208 offset:49152
	ds_read_b128 v[218:221], v208 offset:50176
	ds_read_b128 v[222:225], v208 offset:51200
	ds_read_b128 v[226:229], v208 offset:52224
	ds_read_b128 v[230:233], v208 offset:53248
	ds_read_b128 v[234:237], v208 offset:54272
	ds_read_b128 v[238:241], v208 offset:55296
	ds_read_b128 v[242:245], v208 offset:56320
	global_load_lds_dwordx4 v[8:9], off
	s_add_i32 m0, s60, 0x2000
	s_add_u32 s58, s58, 0x100080
	v_lshl_add_u64 v[8:9], v[248:249], 0, s[20:21]
	s_addc_u32 s59, s59, 0
	s_add_i32 s60, vcc_lo, s66
	global_load_lds_dwordx4 v[8:9], off
	v_lshl_add_u64 v[8:9], s[58:59], 0, v[140:141]
	s_mov_b32 m0, s60
	s_nop 0
	global_load_lds_dwordx4 v[8:9], off
	v_lshl_add_u64 v[8:9], s[58:59], 0, v[144:145]
	s_add_i32 m0, s60, 0x2000
	s_nop 0
	global_load_lds_dwordx4 v[8:9], off
	v_lshl_add_u64 v[8:9], v[250:251], 0, s[20:21]
	s_mov_b32 m0, s76
	s_nop 0
	global_load_lds_dwordx4 v[8:9], off
	v_lshl_add_u64 v[8:9], v[252:253], 0, s[20:21]
	s_mov_b32 m0, s77
	s_nop 0
	global_load_lds_dwordx4 v[8:9], off
	s_waitcnt vmcnt(8)
	s_waitcnt lgkmcnt(0)
	s_barrier
	s_setprio 1
	s_waitcnt lgkmcnt(0)
	v_mfma_f32_16x16x32_bf16 v[66:69], v[176:179], v[214:217], v[66:69]
	v_mfma_f32_16x16x32_bf16 v[66:69], v[180:183], v[218:221], v[66:69]
	v_mfma_f32_16x16x32_bf16 v[58:61], v[184:187], v[214:217], v[58:61]
	v_mfma_f32_16x16x32_bf16 v[58:61], v[188:191], v[218:221], v[58:61]
	v_mfma_f32_16x16x32_bf16 v[42:45], v[184:187], v[222:225], v[42:45]
	v_mfma_f32_16x16x32_bf16 v[42:45], v[188:191], v[226:229], v[42:45]
	v_mfma_f32_16x16x32_bf16 v[50:53], v[176:179], v[222:225], v[50:53]
	v_mfma_f32_16x16x32_bf16 v[50:53], v[180:183], v[226:229], v[50:53]
	v_mfma_f32_16x16x32_bf16 v[34:37], v[176:179], v[230:233], v[34:37]
	v_mfma_f32_16x16x32_bf16 v[34:37], v[180:183], v[234:237], v[34:37]
	v_mfma_f32_16x16x32_bf16 v[26:29], v[184:187], v[230:233], v[26:29]
	v_mfma_f32_16x16x32_bf16 v[26:29], v[188:191], v[234:237], v[26:29]
	v_mfma_f32_16x16x32_bf16 v[8:11], v[184:187], v[238:241], v[10:13]
	v_mfma_f32_16x16x32_bf16 v[10:13], v[188:191], v[242:245], v[8:11]
	v_mfma_f32_16x16x32_bf16 v[18:21], v[176:179], v[238:241], v[18:21]
	v_mfma_f32_16x16x32_bf16 v[18:21], v[180:183], v[242:245], v[18:21]
	s_setprio 0
	s_setprio 1
	v_mfma_f32_16x16x32_bf16 v[62:65], v[192:195], v[214:217], v[62:65]
	v_mfma_f32_16x16x32_bf16 v[62:65], v[196:199], v[218:221], v[62:65]
	v_mfma_f32_16x16x32_bf16 v[54:57], v[200:203], v[214:217], v[54:57]
	v_mfma_f32_16x16x32_bf16 v[54:57], v[210:213], v[218:221], v[54:57]
	v_mfma_f32_16x16x32_bf16 v[38:41], v[200:203], v[222:225], v[38:41]
	v_mfma_f32_16x16x32_bf16 v[38:41], v[210:213], v[226:229], v[38:41]
	v_mfma_f32_16x16x32_bf16 v[46:49], v[192:195], v[222:225], v[46:49]
	v_mfma_f32_16x16x32_bf16 v[46:49], v[196:199], v[226:229], v[46:49]
	v_mfma_f32_16x16x32_bf16 v[30:33], v[192:195], v[230:233], v[30:33]
	v_mfma_f32_16x16x32_bf16 v[30:33], v[196:199], v[234:237], v[30:33]
	v_mfma_f32_16x16x32_bf16 v[22:25], v[200:203], v[230:233], v[22:25]
	v_mfma_f32_16x16x32_bf16 v[22:25], v[210:213], v[234:237], v[22:25]
	v_mfma_f32_16x16x32_bf16 v[4:7], v[200:203], v[238:241], v[4:7]
	v_mfma_f32_16x16x32_bf16 v[6:9], v[210:213], v[242:245], v[4:7]
	v_mfma_f32_16x16x32_bf16 v[14:17], v[192:195], v[238:241], v[14:17]
	v_mfma_f32_16x16x32_bf16 v[14:17], v[196:199], v[242:245], v[14:17]
	s_setprio 0
	s_barrier
	s_add_u32 s56, s56, 0x100
	s_addc_u32 s57, s57, 0
	s_add_u32 s93, s93, 0x100
	s_addc_u32 s82, s82, 0
	s_cmp_ge_i32 s14, s39
	s_cbranch_scc1 .LBB0_1288
	s_mov_b32 s58, s14
	s_branch .LBB0_1283

.LBB0_1461:
	ds_read_b128 v[146:149], v157
	ds_read_b128 v[162:165], v157 offset:1024
	ds_read_b128 v[166:169], v157 offset:2048
	ds_read_b128 v[170:173], v157 offset:3072
	ds_read_b128 v[174:177], v158
	ds_read_b128 v[178:181], v158 offset:1024
	ds_read_b128 v[182:185], v158 offset:2048
	ds_read_b128 v[186:189], v158 offset:3072
	s_add_i32 s89, s52, 2
	s_add_u32 s53, s50, 0xfff00080
	s_addc_u32 s54, s51, -1
	s_cmp_eq_u32 s39, s52
	s_cselect_b32 s52, s46, s41
	s_cselect_b32 s55, s45, s54
	s_cselect_b32 s54, s44, s53
	s_cselect_b32 s53, s47, s43
	v_lshl_add_u64 v[150:151], s[50:51], 0, v[142:143]
	s_add_i32 m0, s64, 0xc000
	ds_read_b128 v[190:193], v159
	ds_read_b128 v[194:197], v159 offset:1024
	ds_read_b128 v[198:201], v159 offset:2048
	ds_read_b128 v[206:209], v159 offset:3072
	ds_read_b128 v[210:213], v159 offset:4096
	ds_read_b128 v[214:217], v159 offset:5120
	ds_read_b128 v[218:221], v159 offset:6144
	ds_read_b128 v[222:225], v159 offset:7168
	global_load_lds_dwordx4 v[150:151], off
	v_lshl_add_u64 v[150:151], s[50:51], 0, v[144:145]
	s_add_i32 m0, s64, 0xe000
	s_nop 0
	global_load_lds_dwordx4 v[150:151], off
	s_waitcnt vmcnt(8)
	s_waitcnt lgkmcnt(0)
	s_barrier
	s_setprio 1
	s_waitcnt lgkmcnt(0)
	v_mfma_f32_16x16x32_bf16 v[126:129], v[146:149], v[190:193], v[126:129]
	v_mfma_f32_16x16x32_bf16 v[126:129], v[162:165], v[194:197], v[126:129]
	v_mfma_f32_16x16x32_bf16 v[122:125], v[166:169], v[190:193], v[122:125]
	v_mfma_f32_16x16x32_bf16 v[122:125], v[170:173], v[194:197], v[122:125]
	v_mfma_f32_16x16x32_bf16 v[114:117], v[166:169], v[198:201], v[114:117]
	v_mfma_f32_16x16x32_bf16 v[114:117], v[170:173], v[206:209], v[114:117]
	v_mfma_f32_16x16x32_bf16 v[118:121], v[146:149], v[198:201], v[118:121]
	v_mfma_f32_16x16x32_bf16 v[118:121], v[162:165], v[206:209], v[118:121]
	v_mfma_f32_16x16x32_bf16 v[110:113], v[146:149], v[210:213], v[110:113]
	v_mfma_f32_16x16x32_bf16 v[110:113], v[162:165], v[214:217], v[110:113]
	v_mfma_f32_16x16x32_bf16 v[106:109], v[166:169], v[210:213], v[106:109]
	v_mfma_f32_16x16x32_bf16 v[106:109], v[170:173], v[214:217], v[106:109]
	v_mfma_f32_16x16x32_bf16 v[98:101], v[166:169], v[218:221], v[98:101]
	v_mfma_f32_16x16x32_bf16 v[98:101], v[170:173], v[222:225], v[98:101]
	v_mfma_f32_16x16x32_bf16 v[102:105], v[146:149], v[218:221], v[102:105]
	v_mfma_f32_16x16x32_bf16 v[102:105], v[162:165], v[222:225], v[102:105]
	s_setprio 0
	s_setprio 1
	v_mfma_f32_16x16x32_bf16 v[94:97], v[174:177], v[190:193], v[94:97]
	v_mfma_f32_16x16x32_bf16 v[94:97], v[178:181], v[194:197], v[94:97]
	v_mfma_f32_16x16x32_bf16 v[90:93], v[182:185], v[190:193], v[90:93]
	v_mfma_f32_16x16x32_bf16 v[90:93], v[186:189], v[194:197], v[90:93]
	v_mfma_f32_16x16x32_bf16 v[82:85], v[182:185], v[198:201], v[82:85]
	v_mfma_f32_16x16x32_bf16 v[82:85], v[186:189], v[206:209], v[82:85]
	v_mfma_f32_16x16x32_bf16 v[86:89], v[174:177], v[198:201], v[86:89]
	v_mfma_f32_16x16x32_bf16 v[86:89], v[178:181], v[206:209], v[86:89]
	v_mfma_f32_16x16x32_bf16 v[78:81], v[174:177], v[210:213], v[78:81]
	v_mfma_f32_16x16x32_bf16 v[78:81], v[178:181], v[214:217], v[78:81]
	v_mfma_f32_16x16x32_bf16 v[74:77], v[182:185], v[210:213], v[74:77]
	v_mfma_f32_16x16x32_bf16 v[74:77], v[186:189], v[214:217], v[74:77]
	v_mfma_f32_16x16x32_bf16 v[66:69], v[182:185], v[218:221], v[66:69]
	v_mfma_f32_16x16x32_bf16 v[66:69], v[186:189], v[222:225], v[66:69]
	v_mfma_f32_16x16x32_bf16 v[70:73], v[174:177], v[218:221], v[70:73]
	v_mfma_f32_16x16x32_bf16 v[70:73], v[178:181], v[222:225], v[70:73]
	s_setprio 0
	s_barrier
	s_add_i32 s90, s82, s59
	v_lshl_add_u64 v[150:151], s[52:53], 0, v[132:133]
	s_mov_b32 m0, s90
	ds_read_b128 v[190:193], v159 offset:16384
	ds_read_b128 v[194:197], v159 offset:17408
	ds_read_b128 v[198:201], v159 offset:18432
	ds_read_b128 v[206:209], v159 offset:19456
	ds_read_b128 v[210:213], v159 offset:20480
	ds_read_b128 v[214:217], v159 offset:21504
	ds_read_b128 v[218:221], v159 offset:22528
	ds_read_b128 v[222:225], v159 offset:23552
	global_load_lds_dwordx4 v[150:151], off
	s_add_i32 m0, s90, 0x2000
	s_add_u32 s90, s52, 0x100000
	v_lshl_add_u64 v[202:203], s[52:53], 0, v[136:137]
	s_addc_u32 s91, s53, 0
	s_add_i32 s92, s83, s59
	global_load_lds_dwordx4 v[202:203], off
	v_lshl_add_u64 v[226:227], s[90:91], 0, v[132:133]
	s_mov_b32 m0, s92
	v_lshl_add_u64 v[228:229], s[54:55], 0, v[134:135]
	global_load_lds_dwordx4 v[226:227], off
	v_lshl_add_u64 v[226:227], s[90:91], 0, v[136:137]
	s_add_i32 m0, s92, 0x2000
	s_nop 0
	global_load_lds_dwordx4 v[226:227], off
	v_lshl_add_u64 v[226:227], s[54:55], 0, v[130:131]
	s_mov_b32 m0, s64
	s_nop 0
	global_load_lds_dwordx4 v[226:227], off
	s_mov_b32 m0, s66
	s_nop 0
	global_load_lds_dwordx4 v[228:229], off
	s_waitcnt vmcnt(8)
	s_waitcnt lgkmcnt(0)
	s_barrier
	s_setprio 1
	s_waitcnt lgkmcnt(0)
	v_mfma_f32_16x16x32_bf16 v[62:65], v[146:149], v[190:193], v[62:65]
	v_mfma_f32_16x16x32_bf16 v[62:65], v[162:165], v[194:197], v[62:65]
	v_mfma_f32_16x16x32_bf16 v[58:61], v[166:169], v[190:193], v[58:61]
	v_mfma_f32_16x16x32_bf16 v[58:61], v[170:173], v[194:197], v[58:61]
	v_mfma_f32_16x16x32_bf16 v[50:53], v[166:169], v[198:201], v[50:53]
	v_mfma_f32_16x16x32_bf16 v[50:53], v[170:173], v[206:209], v[50:53]
	v_mfma_f32_16x16x32_bf16 v[54:57], v[146:149], v[198:201], v[54:57]
	v_mfma_f32_16x16x32_bf16 v[54:57], v[162:165], v[206:209], v[54:57]
	v_mfma_f32_16x16x32_bf16 v[46:49], v[146:149], v[210:213], v[46:49]
	v_mfma_f32_16x16x32_bf16 v[46:49], v[162:165], v[214:217], v[46:49]
	v_mfma_f32_16x16x32_bf16 v[42:45], v[166:169], v[210:213], v[42:45]
	v_mfma_f32_16x16x32_bf16 v[42:45], v[170:173], v[214:217], v[42:45]
	v_mfma_f32_16x16x32_bf16 v[34:37], v[166:169], v[218:221], v[34:37]
	v_mfma_f32_16x16x32_bf16 v[34:37], v[170:173], v[222:225], v[34:37]
	v_mfma_f32_16x16x32_bf16 v[38:41], v[146:149], v[218:221], v[38:41]
	v_mfma_f32_16x16x32_bf16 v[38:41], v[162:165], v[222:225], v[38:41]
	s_setprio 0
	s_setprio 1
	v_mfma_f32_16x16x32_bf16 v[30:33], v[174:177], v[190:193], v[30:33]
	v_mfma_f32_16x16x32_bf16 v[30:33], v[178:181], v[194:197], v[30:33]
	v_mfma_f32_16x16x32_bf16 v[26:29], v[182:185], v[190:193], v[26:29]
	v_mfma_f32_16x16x32_bf16 v[26:29], v[186:189], v[194:197], v[26:29]
	v_mfma_f32_16x16x32_bf16 v[18:21], v[182:185], v[198:201], v[18:21]
	v_mfma_f32_16x16x32_bf16 v[18:21], v[186:189], v[206:209], v[18:21]
	v_mfma_f32_16x16x32_bf16 v[22:25], v[174:177], v[198:201], v[22:25]
	v_mfma_f32_16x16x32_bf16 v[22:25], v[178:181], v[206:209], v[22:25]
	v_mfma_f32_16x16x32_bf16 v[14:17], v[174:177], v[210:213], v[14:17]
	v_mfma_f32_16x16x32_bf16 v[14:17], v[178:181], v[214:217], v[14:17]
	v_mfma_f32_16x16x32_bf16 v[10:13], v[182:185], v[210:213], v[10:13]
	v_mfma_f32_16x16x32_bf16 v[10:13], v[186:189], v[214:217], v[10:13]
	v_mfma_f32_16x16x32_bf16 v[2:5], v[182:185], v[218:221], v[2:5]
	v_mfma_f32_16x16x32_bf16 v[2:5], v[186:189], v[222:225], v[2:5]
	v_mfma_f32_16x16x32_bf16 v[6:9], v[174:177], v[218:221], v[6:9]
	v_mfma_f32_16x16x32_bf16 v[6:9], v[178:181], v[222:225], v[6:9]
	s_setprio 0
	s_barrier
	s_add_i32 s90, 0, 0x18000
	v_add_u32_e32 v161, s90, v155
	s_add_i32 s91, 0, 0x1c000
	ds_read_b128 v[146:149], v161
	ds_read_b128 v[162:165], v161 offset:1024
	ds_read_b128 v[166:169], v161 offset:2048
	ds_read_b128 v[170:173], v161 offset:3072
	v_add_u32_e32 v161, s91, v155
	ds_read_b128 v[174:177], v161
	ds_read_b128 v[178:181], v161 offset:1024
	ds_read_b128 v[182:185], v161 offset:2048
	ds_read_b128 v[186:189], v161 offset:3072
	s_add_u32 s54, s54, 0x100000
	s_addc_u32 s55, s55, 0
	s_mov_b32 m0, s67
	v_lshl_add_u64 v[230:231], s[54:55], 0, v[130:131]
	ds_read_b128 v[190:193], v159 offset:32768
	ds_read_b128 v[194:197], v159 offset:33792
	ds_read_b128 v[198:201], v159 offset:34816
	ds_read_b128 v[206:209], v159 offset:35840
	ds_read_b128 v[210:213], v159 offset:36864
	ds_read_b128 v[214:217], v159 offset:37888
	ds_read_b128 v[218:221], v159 offset:38912
	ds_read_b128 v[222:225], v159 offset:39936
	global_load_lds_dwordx4 v[230:231], off
	v_lshl_add_u64 v[230:231], s[54:55], 0, v[134:135]
	s_mov_b32 m0, s68
	s_nop 0
	global_load_lds_dwordx4 v[230:231], off
	s_waitcnt vmcnt(8)
	s_waitcnt lgkmcnt(0)
	s_barrier
	s_setprio 1
	s_waitcnt lgkmcnt(0)
	v_mfma_f32_16x16x32_bf16 v[126:129], v[146:149], v[190:193], v[126:129]
	v_mfma_f32_16x16x32_bf16 v[126:129], v[162:165], v[194:197], v[126:129]
	v_mfma_f32_16x16x32_bf16 v[122:125], v[166:169], v[190:193], v[122:125]
	v_mfma_f32_16x16x32_bf16 v[122:125], v[170:173], v[194:197], v[122:125]
	v_mfma_f32_16x16x32_bf16 v[114:117], v[166:169], v[198:201], v[114:117]
	v_mfma_f32_16x16x32_bf16 v[114:117], v[170:173], v[206:209], v[114:117]
	v_mfma_f32_16x16x32_bf16 v[118:121], v[146:149], v[198:201], v[118:121]
	v_mfma_f32_16x16x32_bf16 v[118:121], v[162:165], v[206:209], v[118:121]
	v_mfma_f32_16x16x32_bf16 v[110:113], v[146:149], v[210:213], v[110:113]
	v_mfma_f32_16x16x32_bf16 v[110:113], v[162:165], v[214:217], v[110:113]
	v_mfma_f32_16x16x32_bf16 v[106:109], v[166:169], v[210:213], v[106:109]
	v_mfma_f32_16x16x32_bf16 v[106:109], v[170:173], v[214:217], v[106:109]
	v_mfma_f32_16x16x32_bf16 v[98:101], v[166:169], v[218:221], v[98:101]
	v_mfma_f32_16x16x32_bf16 v[98:101], v[170:173], v[222:225], v[98:101]
	v_mfma_f32_16x16x32_bf16 v[102:105], v[146:149], v[218:221], v[102:105]
	v_mfma_f32_16x16x32_bf16 v[102:105], v[162:165], v[222:225], v[102:105]
	s_setprio 0
	s_setprio 1
	v_mfma_f32_16x16x32_bf16 v[94:97], v[174:177], v[190:193], v[94:97]
	v_mfma_f32_16x16x32_bf16 v[94:97], v[178:181], v[194:197], v[94:97]
	v_mfma_f32_16x16x32_bf16 v[90:93], v[182:185], v[190:193], v[90:93]
	v_mfma_f32_16x16x32_bf16 v[90:93], v[186:189], v[194:197], v[90:93]
	v_mfma_f32_16x16x32_bf16 v[82:85], v[182:185], v[198:201], v[82:85]
	v_mfma_f32_16x16x32_bf16 v[82:85], v[186:189], v[206:209], v[82:85]
	v_mfma_f32_16x16x32_bf16 v[86:89], v[174:177], v[198:201], v[86:89]
	v_mfma_f32_16x16x32_bf16 v[86:89], v[178:181], v[206:209], v[86:89]
	v_mfma_f32_16x16x32_bf16 v[78:81], v[174:177], v[210:213], v[78:81]
	v_mfma_f32_16x16x32_bf16 v[78:81], v[178:181], v[214:217], v[78:81]
	v_mfma_f32_16x16x32_bf16 v[74:77], v[182:185], v[210:213], v[74:77]
	v_mfma_f32_16x16x32_bf16 v[74:77], v[186:189], v[214:217], v[74:77]
	v_mfma_f32_16x16x32_bf16 v[66:69], v[182:185], v[218:221], v[66:69]
	v_mfma_f32_16x16x32_bf16 v[66:69], v[186:189], v[222:225], v[66:69]
	v_mfma_f32_16x16x32_bf16 v[70:73], v[174:177], v[218:221], v[70:73]
	v_mfma_f32_16x16x32_bf16 v[70:73], v[178:181], v[222:225], v[70:73]
	s_setprio 0
	s_barrier
	s_add_i32 s54, s90, s59
	v_lshl_add_u64 v[150:151], v[150:151], 0, s[22:23]
	s_mov_b32 m0, s54
	ds_read_b128 v[190:193], v159 offset:49152
	ds_read_b128 v[194:197], v159 offset:50176
	ds_read_b128 v[198:201], v159 offset:51200
	ds_read_b128 v[206:209], v159 offset:52224
	ds_read_b128 v[210:213], v159 offset:53248
	ds_read_b128 v[214:217], v159 offset:54272
	ds_read_b128 v[218:221], v159 offset:55296
	ds_read_b128 v[222:225], v159 offset:56320
	global_load_lds_dwordx4 v[150:151], off
	s_add_i32 m0, s54, 0x2000
	s_add_u32 s52, s52, 0x100080
	v_lshl_add_u64 v[150:151], v[202:203], 0, s[22:23]
	s_addc_u32 s53, s53, 0
	s_add_i32 s54, s91, s59
	global_load_lds_dwordx4 v[150:151], off
	v_lshl_add_u64 v[150:151], s[52:53], 0, v[132:133]
	s_mov_b32 m0, s54
	s_nop 0
	global_load_lds_dwordx4 v[150:151], off
	v_lshl_add_u64 v[150:151], s[52:53], 0, v[136:137]
	s_add_i32 m0, s54, 0x2000
	s_nop 0
	global_load_lds_dwordx4 v[150:151], off
	v_lshl_add_u64 v[150:151], v[226:227], 0, s[22:23]
	s_mov_b32 m0, s70
	s_nop 0
	global_load_lds_dwordx4 v[150:151], off
	v_lshl_add_u64 v[150:151], v[228:229], 0, s[22:23]
	s_mov_b32 m0, s71
	s_nop 0
	global_load_lds_dwordx4 v[150:151], off
	s_waitcnt vmcnt(8)
	s_waitcnt lgkmcnt(0)
	s_barrier
	s_setprio 1
	s_waitcnt lgkmcnt(0)
	v_mfma_f32_16x16x32_bf16 v[62:65], v[146:149], v[190:193], v[62:65]
	v_mfma_f32_16x16x32_bf16 v[62:65], v[162:165], v[194:197], v[62:65]
	v_mfma_f32_16x16x32_bf16 v[58:61], v[166:169], v[190:193], v[58:61]
	v_mfma_f32_16x16x32_bf16 v[58:61], v[170:173], v[194:197], v[58:61]
	v_mfma_f32_16x16x32_bf16 v[50:53], v[166:169], v[198:201], v[50:53]
	v_mfma_f32_16x16x32_bf16 v[50:53], v[170:173], v[206:209], v[50:53]
	v_mfma_f32_16x16x32_bf16 v[54:57], v[146:149], v[198:201], v[54:57]
	v_mfma_f32_16x16x32_bf16 v[54:57], v[162:165], v[206:209], v[54:57]
	v_mfma_f32_16x16x32_bf16 v[46:49], v[146:149], v[210:213], v[46:49]
	v_mfma_f32_16x16x32_bf16 v[46:49], v[162:165], v[214:217], v[46:49]
	v_mfma_f32_16x16x32_bf16 v[42:45], v[166:169], v[210:213], v[42:45]
	v_mfma_f32_16x16x32_bf16 v[42:45], v[170:173], v[214:217], v[42:45]
	v_mfma_f32_16x16x32_bf16 v[34:37], v[166:169], v[218:221], v[34:37]
	v_mfma_f32_16x16x32_bf16 v[34:37], v[170:173], v[222:225], v[34:37]
	v_mfma_f32_16x16x32_bf16 v[38:41], v[146:149], v[218:221], v[38:41]
	v_mfma_f32_16x16x32_bf16 v[38:41], v[162:165], v[222:225], v[38:41]
	s_setprio 0
	s_setprio 1
	v_mfma_f32_16x16x32_bf16 v[30:33], v[174:177], v[190:193], v[30:33]
	v_mfma_f32_16x16x32_bf16 v[30:33], v[178:181], v[194:197], v[30:33]
	v_mfma_f32_16x16x32_bf16 v[26:29], v[182:185], v[190:193], v[26:29]
	v_mfma_f32_16x16x32_bf16 v[26:29], v[186:189], v[194:197], v[26:29]
	v_mfma_f32_16x16x32_bf16 v[18:21], v[182:185], v[198:201], v[18:21]
	v_mfma_f32_16x16x32_bf16 v[18:21], v[186:189], v[206:209], v[18:21]
	v_mfma_f32_16x16x32_bf16 v[22:25], v[174:177], v[198:201], v[22:25]
	v_mfma_f32_16x16x32_bf16 v[22:25], v[178:181], v[206:209], v[22:25]
	v_mfma_f32_16x16x32_bf16 v[14:17], v[174:177], v[210:213], v[14:17]
	v_mfma_f32_16x16x32_bf16 v[14:17], v[178:181], v[214:217], v[14:17]
	v_mfma_f32_16x16x32_bf16 v[10:13], v[182:185], v[210:213], v[10:13]
	v_mfma_f32_16x16x32_bf16 v[10:13], v[186:189], v[214:217], v[10:13]
	v_mfma_f32_16x16x32_bf16 v[2:5], v[182:185], v[218:221], v[2:5]
	v_mfma_f32_16x16x32_bf16 v[2:5], v[186:189], v[222:225], v[2:5]
	v_mfma_f32_16x16x32_bf16 v[6:9], v[174:177], v[218:221], v[6:9]
	v_mfma_f32_16x16x32_bf16 v[6:9], v[178:181], v[222:225], v[6:9]
	s_setprio 0
	s_barrier
	s_add_u32 s50, s50, 0x100
	s_addc_u32 s51, s51, 0
	s_add_u32 s41, s41, 0x100
	s_addc_u32 s43, s43, 0
	s_cmp_ge_i32 s89, s49
	s_mov_b32 s52, s89
	s_cbranch_scc0 .LBB0_1461
	s_and_b64 vcc, exec, s[24:25]
	s_cbranch_vccz .LBB0_1464

.LBB0_1644:
	ds_read_b128 v[152:155], v149
	ds_read_b128 v[156:159], v149 offset:1024
	ds_read_b128 v[160:163], v149 offset:2048
	ds_read_b128 v[164:167], v149 offset:3072
	ds_read_b128 v[168:171], v150
	ds_read_b128 v[172:175], v150 offset:1024
	ds_read_b128 v[176:179], v150 offset:2048
	ds_read_b128 v[180:183], v150 offset:3072
	s_add_u32 s28, s26, 0xfff00080
	s_addc_u32 s29, s27, -1
	s_cmp_eq_u32 s55, 60
	s_cselect_b32 s31, s17, s29
	s_cselect_b32 s30, s51, s28
	s_cselect_b32 s29, s15, s54
	s_cselect_b32 s28, s52, s53
	v_lshl_add_u64 v[144:145], s[26:27], 0, v[140:141]
	s_add_i32 m0, s25, 0xc000
	ds_read_b128 v[184:187], v151
	ds_read_b128 v[188:191], v151 offset:1024
	ds_read_b128 v[192:195], v151 offset:2048
	ds_read_b128 v[196:199], v151 offset:3072
	ds_read_b128 v[200:203], v151 offset:4096
	ds_read_b128 v[206:209], v151 offset:5120
	ds_read_b128 v[210:213], v151 offset:6144
	ds_read_b128 v[214:217], v151 offset:7168
	global_load_lds_dwordx4 v[144:145], off
	v_lshl_add_u64 v[144:145], s[26:27], 0, v[142:143]
	s_add_i32 m0, s25, 0xe000
	s_nop 0
	global_load_lds_dwordx4 v[144:145], off
	s_waitcnt vmcnt(8)
	s_waitcnt lgkmcnt(0)
	s_barrier
	s_setprio 1
	s_waitcnt lgkmcnt(0)
	v_mfma_f32_16x16x32_bf16 v[126:129], v[152:155], v[184:187], v[126:129]
	v_mfma_f32_16x16x32_bf16 v[126:129], v[156:159], v[188:191], v[126:129]
	v_mfma_f32_16x16x32_bf16 v[122:125], v[160:163], v[184:187], v[122:125]
	v_mfma_f32_16x16x32_bf16 v[122:125], v[164:167], v[188:191], v[122:125]
	v_mfma_f32_16x16x32_bf16 v[106:109], v[160:163], v[192:195], v[106:109]
	v_mfma_f32_16x16x32_bf16 v[106:109], v[164:167], v[196:199], v[106:109]
	v_mfma_f32_16x16x32_bf16 v[110:113], v[152:155], v[192:195], v[110:113]
	v_mfma_f32_16x16x32_bf16 v[110:113], v[156:159], v[196:199], v[110:113]
	v_mfma_f32_16x16x32_bf16 v[98:101], v[152:155], v[200:203], v[98:101]
	v_mfma_f32_16x16x32_bf16 v[98:101], v[156:159], v[206:209], v[98:101]
	v_mfma_f32_16x16x32_bf16 v[90:93], v[160:163], v[200:203], v[90:93]
	v_mfma_f32_16x16x32_bf16 v[90:93], v[164:167], v[206:209], v[90:93]
	v_mfma_f32_16x16x32_bf16 v[74:77], v[160:163], v[210:213], v[74:77]
	v_mfma_f32_16x16x32_bf16 v[74:77], v[164:167], v[214:217], v[74:77]
	v_mfma_f32_16x16x32_bf16 v[82:85], v[152:155], v[210:213], v[82:85]
	v_mfma_f32_16x16x32_bf16 v[82:85], v[156:159], v[214:217], v[82:85]
	s_setprio 0
	s_setprio 1
	v_mfma_f32_16x16x32_bf16 v[118:121], v[168:171], v[184:187], v[118:121]
	v_mfma_f32_16x16x32_bf16 v[118:121], v[172:175], v[188:191], v[118:121]
	v_mfma_f32_16x16x32_bf16 v[114:117], v[176:179], v[184:187], v[114:117]
	v_mfma_f32_16x16x32_bf16 v[114:117], v[180:183], v[188:191], v[114:117]
	v_mfma_f32_16x16x32_bf16 v[94:97], v[176:179], v[192:195], v[94:97]
	v_mfma_f32_16x16x32_bf16 v[94:97], v[180:183], v[196:199], v[94:97]
	v_mfma_f32_16x16x32_bf16 v[102:105], v[168:171], v[192:195], v[102:105]
	v_mfma_f32_16x16x32_bf16 v[102:105], v[172:175], v[196:199], v[102:105]
	v_mfma_f32_16x16x32_bf16 v[86:89], v[168:171], v[200:203], v[86:89]
	v_mfma_f32_16x16x32_bf16 v[86:89], v[172:175], v[206:209], v[86:89]
	v_mfma_f32_16x16x32_bf16 v[78:81], v[176:179], v[200:203], v[78:81]
	v_mfma_f32_16x16x32_bf16 v[78:81], v[180:183], v[206:209], v[78:81]
	v_mfma_f32_16x16x32_bf16 v[66:69], v[176:179], v[210:213], v[66:69]
	v_mfma_f32_16x16x32_bf16 v[66:69], v[180:183], v[214:217], v[66:69]
	v_mfma_f32_16x16x32_bf16 v[70:73], v[168:171], v[210:213], v[70:73]
	v_mfma_f32_16x16x32_bf16 v[70:73], v[172:175], v[214:217], v[70:73]
	s_setprio 0
	s_barrier
	s_add_i32 s56, s48, s13
	v_lshl_add_u64 v[144:145], s[28:29], 0, v[132:133]
	s_mov_b32 m0, s56
	ds_read_b128 v[184:187], v151 offset:16384
	ds_read_b128 v[188:191], v151 offset:17408
	ds_read_b128 v[192:195], v151 offset:18432
	ds_read_b128 v[196:199], v151 offset:19456
	ds_read_b128 v[200:203], v151 offset:20480
	ds_read_b128 v[206:209], v151 offset:21504
	ds_read_b128 v[210:213], v151 offset:22528
	ds_read_b128 v[214:217], v151 offset:23552
	global_load_lds_dwordx4 v[144:145], off
	s_add_i32 m0, s56, 0x2000
	s_add_u32 s56, s28, 0x100000
	v_lshl_add_u64 v[218:219], s[28:29], 0, v[136:137]
	s_addc_u32 s57, s29, 0
	s_add_i32 s58, s49, s13
	global_load_lds_dwordx4 v[218:219], off
	v_lshl_add_u64 v[220:221], s[56:57], 0, v[132:133]
	s_mov_b32 m0, s58
	v_lshl_add_u64 v[222:223], s[30:31], 0, v[134:135]
	global_load_lds_dwordx4 v[220:221], off
	v_lshl_add_u64 v[220:221], s[56:57], 0, v[136:137]
	s_add_i32 m0, s58, 0x2000
	s_nop 0
	global_load_lds_dwordx4 v[220:221], off
	v_lshl_add_u64 v[220:221], s[30:31], 0, v[130:131]
	s_mov_b32 m0, s25
	s_nop 0
	global_load_lds_dwordx4 v[220:221], off
	s_mov_b32 m0, s39
	s_nop 0
	global_load_lds_dwordx4 v[222:223], off
	s_waitcnt vmcnt(8)
	s_waitcnt lgkmcnt(0)
	s_barrier
	s_setprio 1
	s_waitcnt lgkmcnt(0)
	v_mfma_f32_16x16x32_bf16 v[62:65], v[152:155], v[184:187], v[62:65]
	v_mfma_f32_16x16x32_bf16 v[62:65], v[156:159], v[188:191], v[62:65]
	v_mfma_f32_16x16x32_bf16 v[58:61], v[160:163], v[184:187], v[58:61]
	v_mfma_f32_16x16x32_bf16 v[58:61], v[164:167], v[188:191], v[58:61]
	v_mfma_f32_16x16x32_bf16 v[42:45], v[160:163], v[192:195], v[42:45]
	v_mfma_f32_16x16x32_bf16 v[42:45], v[164:167], v[196:199], v[42:45]
	v_mfma_f32_16x16x32_bf16 v[50:53], v[152:155], v[192:195], v[50:53]
	v_mfma_f32_16x16x32_bf16 v[50:53], v[156:159], v[196:199], v[50:53]
	v_mfma_f32_16x16x32_bf16 v[34:37], v[152:155], v[200:203], v[34:37]
	v_mfma_f32_16x16x32_bf16 v[34:37], v[156:159], v[206:209], v[34:37]
	v_mfma_f32_16x16x32_bf16 v[26:29], v[160:163], v[200:203], v[26:29]
	v_mfma_f32_16x16x32_bf16 v[26:29], v[164:167], v[206:209], v[26:29]
	v_mfma_f32_16x16x32_bf16 v[10:13], v[160:163], v[210:213], v[10:13]
	v_mfma_f32_16x16x32_bf16 v[10:13], v[164:167], v[214:217], v[10:13]
	v_mfma_f32_16x16x32_bf16 v[14:17], v[152:155], v[210:213], v[14:17]
	v_mfma_f32_16x16x32_bf16 v[14:17], v[156:159], v[214:217], v[14:17]
	s_setprio 0
	s_setprio 1
	v_mfma_f32_16x16x32_bf16 v[54:57], v[168:171], v[184:187], v[54:57]
	v_mfma_f32_16x16x32_bf16 v[54:57], v[172:175], v[188:191], v[54:57]
	v_mfma_f32_16x16x32_bf16 v[46:49], v[176:179], v[184:187], v[46:49]
	v_mfma_f32_16x16x32_bf16 v[46:49], v[180:183], v[188:191], v[46:49]
	v_mfma_f32_16x16x32_bf16 v[30:33], v[176:179], v[192:195], v[30:33]
	v_mfma_f32_16x16x32_bf16 v[30:33], v[180:183], v[196:199], v[30:33]
	v_mfma_f32_16x16x32_bf16 v[38:41], v[168:171], v[192:195], v[38:41]
	v_mfma_f32_16x16x32_bf16 v[38:41], v[172:175], v[196:199], v[38:41]
	v_mfma_f32_16x16x32_bf16 v[22:25], v[168:171], v[200:203], v[22:25]
	v_mfma_f32_16x16x32_bf16 v[22:25], v[172:175], v[206:209], v[22:25]
	v_mfma_f32_16x16x32_bf16 v[18:21], v[176:179], v[200:203], v[18:21]
	v_mfma_f32_16x16x32_bf16 v[18:21], v[180:183], v[206:209], v[18:21]
	v_mfma_f32_16x16x32_bf16 v[2:5], v[176:179], v[210:213], v[2:5]
	v_mfma_f32_16x16x32_bf16 v[2:5], v[180:183], v[214:217], v[2:5]
	v_mfma_f32_16x16x32_bf16 v[6:9], v[168:171], v[210:213], v[6:9]
	v_mfma_f32_16x16x32_bf16 v[6:9], v[172:175], v[214:217], v[6:9]
	s_setprio 0
	s_barrier
	s_add_i32 s56, 0, 0x18000
	s_add_i32 s57, 0, 0x1c000
	v_add_u32_e32 v164, s56, v147
	v_add_u32_e32 v180, s57, v147
	ds_read_b128 v[152:155], v164
	ds_read_b128 v[156:159], v164 offset:1024
	ds_read_b128 v[160:163], v164 offset:2048
	ds_read_b128 v[164:167], v164 offset:3072
	ds_read_b128 v[168:171], v180
	ds_read_b128 v[172:175], v180 offset:1024
	ds_read_b128 v[176:179], v180 offset:2048
	ds_read_b128 v[180:183], v180 offset:3072
	s_add_u32 s30, s30, 0x100000
	s_addc_u32 s31, s31, 0
	s_mov_b32 m0, s40
	v_lshl_add_u64 v[224:225], s[30:31], 0, v[130:131]
	ds_read_b128 v[184:187], v151 offset:32768
	ds_read_b128 v[188:191], v151 offset:33792
	ds_read_b128 v[192:195], v151 offset:34816
	ds_read_b128 v[196:199], v151 offset:35840
	ds_read_b128 v[200:203], v151 offset:36864
	ds_read_b128 v[206:209], v151 offset:37888
	ds_read_b128 v[210:213], v151 offset:38912
	ds_read_b128 v[214:217], v151 offset:39936
	global_load_lds_dwordx4 v[224:225], off
	v_lshl_add_u64 v[224:225], s[30:31], 0, v[134:135]
	s_mov_b32 m0, s41
	s_nop 0
	global_load_lds_dwordx4 v[224:225], off
	s_waitcnt vmcnt(8)
	s_waitcnt lgkmcnt(0)
	s_barrier
	s_setprio 1
	s_waitcnt lgkmcnt(0)
	v_mfma_f32_16x16x32_bf16 v[126:129], v[152:155], v[184:187], v[126:129]
	v_mfma_f32_16x16x32_bf16 v[126:129], v[156:159], v[188:191], v[126:129]
	v_mfma_f32_16x16x32_bf16 v[122:125], v[160:163], v[184:187], v[122:125]
	v_mfma_f32_16x16x32_bf16 v[122:125], v[164:167], v[188:191], v[122:125]
	v_mfma_f32_16x16x32_bf16 v[106:109], v[160:163], v[192:195], v[106:109]
	v_mfma_f32_16x16x32_bf16 v[106:109], v[164:167], v[196:199], v[106:109]
	v_mfma_f32_16x16x32_bf16 v[110:113], v[152:155], v[192:195], v[110:113]
	v_mfma_f32_16x16x32_bf16 v[110:113], v[156:159], v[196:199], v[110:113]
	v_mfma_f32_16x16x32_bf16 v[98:101], v[152:155], v[200:203], v[98:101]
	v_mfma_f32_16x16x32_bf16 v[98:101], v[156:159], v[206:209], v[98:101]
	v_mfma_f32_16x16x32_bf16 v[90:93], v[160:163], v[200:203], v[90:93]
	v_mfma_f32_16x16x32_bf16 v[90:93], v[164:167], v[206:209], v[90:93]
	v_mfma_f32_16x16x32_bf16 v[74:77], v[160:163], v[210:213], v[74:77]
	v_mfma_f32_16x16x32_bf16 v[74:77], v[164:167], v[214:217], v[74:77]
	v_mfma_f32_16x16x32_bf16 v[82:85], v[152:155], v[210:213], v[82:85]
	v_mfma_f32_16x16x32_bf16 v[82:85], v[156:159], v[214:217], v[82:85]
	s_setprio 0
	s_setprio 1
	v_mfma_f32_16x16x32_bf16 v[118:121], v[168:171], v[184:187], v[118:121]
	v_mfma_f32_16x16x32_bf16 v[118:121], v[172:175], v[188:191], v[118:121]
	v_mfma_f32_16x16x32_bf16 v[114:117], v[176:179], v[184:187], v[114:117]
	v_mfma_f32_16x16x32_bf16 v[114:117], v[180:183], v[188:191], v[114:117]
	v_mfma_f32_16x16x32_bf16 v[94:97], v[176:179], v[192:195], v[94:97]
	v_mfma_f32_16x16x32_bf16 v[94:97], v[180:183], v[196:199], v[94:97]
	v_mfma_f32_16x16x32_bf16 v[102:105], v[168:171], v[192:195], v[102:105]
	v_mfma_f32_16x16x32_bf16 v[102:105], v[172:175], v[196:199], v[102:105]
	v_mfma_f32_16x16x32_bf16 v[86:89], v[168:171], v[200:203], v[86:89]
	v_mfma_f32_16x16x32_bf16 v[86:89], v[172:175], v[206:209], v[86:89]
	v_mfma_f32_16x16x32_bf16 v[78:81], v[176:179], v[200:203], v[78:81]
	v_mfma_f32_16x16x32_bf16 v[78:81], v[180:183], v[206:209], v[78:81]
	v_mfma_f32_16x16x32_bf16 v[66:69], v[176:179], v[210:213], v[66:69]
	v_mfma_f32_16x16x32_bf16 v[66:69], v[180:183], v[214:217], v[66:69]
	v_mfma_f32_16x16x32_bf16 v[70:73], v[168:171], v[210:213], v[70:73]
	v_mfma_f32_16x16x32_bf16 v[70:73], v[172:175], v[214:217], v[70:73]
	s_setprio 0
	s_barrier
	s_add_i32 s30, s56, s13
	v_lshl_add_u64 v[144:145], v[144:145], 0, s[8:9]
	s_mov_b32 m0, s30
	ds_read_b128 v[184:187], v151 offset:49152
	ds_read_b128 v[188:191], v151 offset:50176
	ds_read_b128 v[192:195], v151 offset:51200
	ds_read_b128 v[196:199], v151 offset:52224
	ds_read_b128 v[200:203], v151 offset:53248
	ds_read_b128 v[206:209], v151 offset:54272
	ds_read_b128 v[210:213], v151 offset:55296
	ds_read_b128 v[214:217], v151 offset:56320
	global_load_lds_dwordx4 v[144:145], off
	s_add_i32 m0, s30, 0x2000
	s_add_u32 s28, s28, 0x100080
	v_lshl_add_u64 v[144:145], v[218:219], 0, s[8:9]
	s_addc_u32 s29, s29, 0
	s_add_i32 s30, s57, s13
	global_load_lds_dwordx4 v[144:145], off
	v_lshl_add_u64 v[144:145], s[28:29], 0, v[132:133]
	s_mov_b32 m0, s30
	s_nop 0
	global_load_lds_dwordx4 v[144:145], off
	v_lshl_add_u64 v[144:145], s[28:29], 0, v[136:137]
	s_add_i32 m0, s30, 0x2000
	s_nop 0
	global_load_lds_dwordx4 v[144:145], off
	v_lshl_add_u64 v[144:145], v[220:221], 0, s[8:9]
	s_mov_b32 m0, s42
	s_nop 0
	global_load_lds_dwordx4 v[144:145], off
	v_lshl_add_u64 v[144:145], v[222:223], 0, s[8:9]
	s_mov_b32 m0, s43
	s_nop 0
	global_load_lds_dwordx4 v[144:145], off
	s_waitcnt vmcnt(8)
	s_waitcnt lgkmcnt(0)
	s_barrier
	s_setprio 1
	s_waitcnt lgkmcnt(0)
	v_mfma_f32_16x16x32_bf16 v[62:65], v[152:155], v[184:187], v[62:65]
	v_mfma_f32_16x16x32_bf16 v[62:65], v[156:159], v[188:191], v[62:65]
	v_mfma_f32_16x16x32_bf16 v[58:61], v[160:163], v[184:187], v[58:61]
	v_mfma_f32_16x16x32_bf16 v[58:61], v[164:167], v[188:191], v[58:61]
	v_mfma_f32_16x16x32_bf16 v[42:45], v[160:163], v[192:195], v[42:45]
	v_mfma_f32_16x16x32_bf16 v[42:45], v[164:167], v[196:199], v[42:45]
	v_mfma_f32_16x16x32_bf16 v[50:53], v[152:155], v[192:195], v[50:53]
	v_mfma_f32_16x16x32_bf16 v[50:53], v[156:159], v[196:199], v[50:53]
	v_mfma_f32_16x16x32_bf16 v[34:37], v[152:155], v[200:203], v[34:37]
	v_mfma_f32_16x16x32_bf16 v[34:37], v[156:159], v[206:209], v[34:37]
	v_mfma_f32_16x16x32_bf16 v[26:29], v[160:163], v[200:203], v[26:29]
	v_mfma_f32_16x16x32_bf16 v[26:29], v[164:167], v[206:209], v[26:29]
	v_mfma_f32_16x16x32_bf16 v[10:13], v[160:163], v[210:213], v[10:13]
	v_mfma_f32_16x16x32_bf16 v[10:13], v[164:167], v[214:217], v[10:13]
	v_mfma_f32_16x16x32_bf16 v[14:17], v[152:155], v[210:213], v[14:17]
	v_mfma_f32_16x16x32_bf16 v[14:17], v[156:159], v[214:217], v[14:17]
	s_setprio 0
	s_setprio 1
	v_mfma_f32_16x16x32_bf16 v[54:57], v[168:171], v[184:187], v[54:57]
	v_mfma_f32_16x16x32_bf16 v[54:57], v[172:175], v[188:191], v[54:57]
	v_mfma_f32_16x16x32_bf16 v[46:49], v[176:179], v[184:187], v[46:49]
	v_mfma_f32_16x16x32_bf16 v[46:49], v[180:183], v[188:191], v[46:49]
	v_mfma_f32_16x16x32_bf16 v[30:33], v[176:179], v[192:195], v[30:33]
	v_mfma_f32_16x16x32_bf16 v[30:33], v[180:183], v[196:199], v[30:33]
	v_mfma_f32_16x16x32_bf16 v[38:41], v[168:171], v[192:195], v[38:41]
	v_mfma_f32_16x16x32_bf16 v[38:41], v[172:175], v[196:199], v[38:41]
	v_mfma_f32_16x16x32_bf16 v[22:25], v[168:171], v[200:203], v[22:25]
	v_mfma_f32_16x16x32_bf16 v[22:25], v[172:175], v[206:209], v[22:25]
	v_mfma_f32_16x16x32_bf16 v[18:21], v[176:179], v[200:203], v[18:21]
	v_mfma_f32_16x16x32_bf16 v[18:21], v[180:183], v[206:209], v[18:21]
	v_mfma_f32_16x16x32_bf16 v[2:5], v[176:179], v[210:213], v[2:5]
	v_mfma_f32_16x16x32_bf16 v[2:5], v[180:183], v[214:217], v[2:5]
	v_mfma_f32_16x16x32_bf16 v[6:9], v[168:171], v[210:213], v[6:9]
	v_mfma_f32_16x16x32_bf16 v[6:9], v[172:175], v[214:217], v[6:9]
	s_setprio 0
	s_barrier
	s_add_i32 s55, s55, 2
	s_add_u32 s26, s26, 0x100
	s_addc_u32 s27, s27, 0
	s_add_u32 s53, s53, 0x100
	s_addc_u32 s54, s54, 0
	s_cmp_gt_u32 s55, 61
	s_cbranch_scc0 .LBB0_1644
	s_and_b64 vcc, exec, s[10:11]
	s_cbranch_vccz .LBB0_1647
	s_barrier

.LBB0_1749:
	s_waitcnt lgkmcnt(0)
	ds_read_b128 v[144:147], v154
	ds_read_b128 v[158:161], v154 offset:1024
	ds_read_b128 v[162:165], v154 offset:2048
	ds_read_b128 v[166:169], v154 offset:3072
	ds_read_b128 v[170:173], v155
	ds_read_b128 v[174:177], v155 offset:1024
	ds_read_b128 v[178:181], v155 offset:2048
	ds_read_b128 v[182:185], v155 offset:3072
	s_add_i32 s89, s46, 2
	s_add_u32 s47, s44, 0xffd50080
	s_addc_u32 s48, s45, -1
	s_cmp_eq_u32 s39, s46
	s_cselect_b32 s46, s42, s87
	s_cselect_b32 s49, s41, s48
	s_cselect_b32 s48, s40, s47
	s_cselect_b32 s47, s43, s88
	v_lshl_add_u64 v[148:149], s[44:45], 0, v[140:141]
	s_add_i32 m0, s58, 0xc000
	ds_read_b128 v[186:189], v156
	ds_read_b128 v[190:193], v156 offset:1024
	ds_read_b128 v[194:197], v156 offset:2048
	ds_read_b128 v[198:201], v156 offset:3072
	ds_read_b128 v[202:205], v156 offset:4096
	ds_read_b128 v[206:209], v156 offset:5120
	ds_read_b128 v[210:213], v156 offset:6144
	ds_read_b128 v[214:217], v156 offset:7168
	global_load_lds_dwordx4 v[148:149], off
	v_lshl_add_u64 v[148:149], s[44:45], 0, v[142:143]
	s_add_i32 m0, s58, 0xe000
	s_nop 0
	global_load_lds_dwordx4 v[148:149], off
	s_waitcnt vmcnt(8)
	s_waitcnt lgkmcnt(0)
	s_barrier
	s_setprio 1
	s_waitcnt lgkmcnt(0)
	v_mfma_f32_16x16x32_bf16 v[124:127], v[144:147], v[186:189], v[124:127]
	v_mfma_f32_16x16x32_bf16 v[124:127], v[158:161], v[190:193], v[124:127]
	v_mfma_f32_16x16x32_bf16 v[120:123], v[162:165], v[186:189], v[120:123]
	v_mfma_f32_16x16x32_bf16 v[120:123], v[166:169], v[190:193], v[120:123]
	v_mfma_f32_16x16x32_bf16 v[112:115], v[162:165], v[194:197], v[112:115]
	v_mfma_f32_16x16x32_bf16 v[112:115], v[166:169], v[198:201], v[112:115]
	v_mfma_f32_16x16x32_bf16 v[116:119], v[144:147], v[194:197], v[116:119]
	v_mfma_f32_16x16x32_bf16 v[116:119], v[158:161], v[198:201], v[116:119]
	v_mfma_f32_16x16x32_bf16 v[108:111], v[144:147], v[202:205], v[108:111]
	v_mfma_f32_16x16x32_bf16 v[108:111], v[158:161], v[206:209], v[108:111]
	v_mfma_f32_16x16x32_bf16 v[104:107], v[162:165], v[202:205], v[104:107]
	v_mfma_f32_16x16x32_bf16 v[104:107], v[166:169], v[206:209], v[104:107]
	v_mfma_f32_16x16x32_bf16 v[96:99], v[162:165], v[210:213], v[96:99]
	v_mfma_f32_16x16x32_bf16 v[96:99], v[166:169], v[214:217], v[96:99]
	v_mfma_f32_16x16x32_bf16 v[100:103], v[144:147], v[210:213], v[100:103]
	v_mfma_f32_16x16x32_bf16 v[100:103], v[158:161], v[214:217], v[100:103]
	s_setprio 0
	s_setprio 1
	v_mfma_f32_16x16x32_bf16 v[92:95], v[170:173], v[186:189], v[92:95]
	v_mfma_f32_16x16x32_bf16 v[92:95], v[174:177], v[190:193], v[92:95]
	v_mfma_f32_16x16x32_bf16 v[88:91], v[178:181], v[186:189], v[88:91]
	v_mfma_f32_16x16x32_bf16 v[88:91], v[182:185], v[190:193], v[88:91]
	v_mfma_f32_16x16x32_bf16 v[80:83], v[178:181], v[194:197], v[80:83]
	v_mfma_f32_16x16x32_bf16 v[80:83], v[182:185], v[198:201], v[80:83]
	v_mfma_f32_16x16x32_bf16 v[84:87], v[170:173], v[194:197], v[84:87]
	v_mfma_f32_16x16x32_bf16 v[84:87], v[174:177], v[198:201], v[84:87]
	v_mfma_f32_16x16x32_bf16 v[76:79], v[170:173], v[202:205], v[76:79]
	v_mfma_f32_16x16x32_bf16 v[76:79], v[174:177], v[206:209], v[76:79]
	v_mfma_f32_16x16x32_bf16 v[72:75], v[178:181], v[202:205], v[72:75]
	v_mfma_f32_16x16x32_bf16 v[72:75], v[182:185], v[206:209], v[72:75]
	v_mfma_f32_16x16x32_bf16 v[64:67], v[178:181], v[210:213], v[64:67]
	v_mfma_f32_16x16x32_bf16 v[64:67], v[182:185], v[214:217], v[64:67]
	v_mfma_f32_16x16x32_bf16 v[68:71], v[170:173], v[210:213], v[68:71]
	v_mfma_f32_16x16x32_bf16 v[68:71], v[174:177], v[214:217], v[68:71]
	s_setprio 0
	s_barrier
	s_add_i32 s90, s76, s53
	v_lshl_add_u64 v[148:149], s[46:47], 0, v[130:131]
	s_mov_b32 m0, s90
	ds_read_b128 v[186:189], v156 offset:16384
	ds_read_b128 v[190:193], v156 offset:17408
	ds_read_b128 v[194:197], v156 offset:18432
	ds_read_b128 v[198:201], v156 offset:19456
	ds_read_b128 v[202:205], v156 offset:20480
	ds_read_b128 v[206:209], v156 offset:21504
	ds_read_b128 v[210:213], v156 offset:22528
	ds_read_b128 v[214:217], v156 offset:23552
	global_load_lds_dwordx4 v[148:149], off
	s_add_i32 m0, s90, 0x2000
	s_add_u32 s90, s46, 0x2b0000
	v_lshl_add_u64 v[218:219], s[46:47], 0, v[134:135]
	s_addc_u32 s91, s47, 0
	s_add_i32 s92, s77, s53
	global_load_lds_dwordx4 v[218:219], off
	v_lshl_add_u64 v[220:221], s[90:91], 0, v[130:131]
	s_mov_b32 m0, s92
	v_lshl_add_u64 v[222:223], s[48:49], 0, v[132:133]
	global_load_lds_dwordx4 v[220:221], off
	v_lshl_add_u64 v[220:221], s[90:91], 0, v[134:135]
	s_add_i32 m0, s92, 0x2000
	s_nop 0
	global_load_lds_dwordx4 v[220:221], off
	v_lshl_add_u64 v[220:221], s[48:49], 0, v[128:129]
	s_mov_b32 m0, s58
	s_nop 0
	global_load_lds_dwordx4 v[220:221], off
	s_mov_b32 m0, s60
	s_nop 0
	global_load_lds_dwordx4 v[222:223], off
	s_waitcnt vmcnt(8)
	s_waitcnt lgkmcnt(0)
	s_barrier
	s_setprio 1
	s_waitcnt lgkmcnt(0)
	v_mfma_f32_16x16x32_bf16 v[60:63], v[144:147], v[186:189], v[60:63]
	v_mfma_f32_16x16x32_bf16 v[60:63], v[158:161], v[190:193], v[60:63]
	v_mfma_f32_16x16x32_bf16 v[56:59], v[162:165], v[186:189], v[56:59]
	v_mfma_f32_16x16x32_bf16 v[56:59], v[166:169], v[190:193], v[56:59]
	v_mfma_f32_16x16x32_bf16 v[48:51], v[162:165], v[194:197], v[48:51]
	v_mfma_f32_16x16x32_bf16 v[48:51], v[166:169], v[198:201], v[48:51]
	v_mfma_f32_16x16x32_bf16 v[52:55], v[144:147], v[194:197], v[52:55]
	v_mfma_f32_16x16x32_bf16 v[52:55], v[158:161], v[198:201], v[52:55]
	v_mfma_f32_16x16x32_bf16 v[44:47], v[144:147], v[202:205], v[44:47]
	v_mfma_f32_16x16x32_bf16 v[44:47], v[158:161], v[206:209], v[44:47]
	v_mfma_f32_16x16x32_bf16 v[40:43], v[162:165], v[202:205], v[40:43]
	v_mfma_f32_16x16x32_bf16 v[40:43], v[166:169], v[206:209], v[40:43]
	v_mfma_f32_16x16x32_bf16 v[32:35], v[162:165], v[210:213], v[32:35]
	v_mfma_f32_16x16x32_bf16 v[32:35], v[166:169], v[214:217], v[32:35]
	v_mfma_f32_16x16x32_bf16 v[36:39], v[144:147], v[210:213], v[36:39]
	v_mfma_f32_16x16x32_bf16 v[36:39], v[158:161], v[214:217], v[36:39]
	s_setprio 0
	s_setprio 1
	v_mfma_f32_16x16x32_bf16 v[28:31], v[170:173], v[186:189], v[28:31]
	v_mfma_f32_16x16x32_bf16 v[28:31], v[174:177], v[190:193], v[28:31]
	v_mfma_f32_16x16x32_bf16 v[24:27], v[178:181], v[186:189], v[24:27]
	v_mfma_f32_16x16x32_bf16 v[24:27], v[182:185], v[190:193], v[24:27]
	v_mfma_f32_16x16x32_bf16 v[16:19], v[178:181], v[194:197], v[16:19]
	v_mfma_f32_16x16x32_bf16 v[16:19], v[182:185], v[198:201], v[16:19]
	v_mfma_f32_16x16x32_bf16 v[20:23], v[170:173], v[194:197], v[20:23]
	v_mfma_f32_16x16x32_bf16 v[20:23], v[174:177], v[198:201], v[20:23]
	v_mfma_f32_16x16x32_bf16 v[12:15], v[170:173], v[202:205], v[12:15]
	v_mfma_f32_16x16x32_bf16 v[12:15], v[174:177], v[206:209], v[12:15]
	v_mfma_f32_16x16x32_bf16 v[8:11], v[178:181], v[202:205], v[8:11]
	v_mfma_f32_16x16x32_bf16 v[8:11], v[182:185], v[206:209], v[8:11]
	v_mfma_f32_16x16x32_bf16 v[0:3], v[178:181], v[210:213], v[0:3]
	v_mfma_f32_16x16x32_bf16 v[0:3], v[182:185], v[214:217], v[0:3]
	v_mfma_f32_16x16x32_bf16 v[4:7], v[170:173], v[210:213], v[4:7]
	v_mfma_f32_16x16x32_bf16 v[4:7], v[174:177], v[214:217], v[4:7]
	s_setprio 0
	s_barrier
	s_add_i32 s90, 0, 0x18000
	s_add_i32 s91, 0, 0x1c000
	v_add_u32_e32 v166, s90, v139
	v_add_u32_e32 v182, s91, v139
	ds_read_b128 v[144:147], v166
	ds_read_b128 v[158:161], v166 offset:1024
	ds_read_b128 v[162:165], v166 offset:2048
	ds_read_b128 v[166:169], v166 offset:3072
	ds_read_b128 v[170:173], v182
	ds_read_b128 v[174:177], v182 offset:1024
	ds_read_b128 v[178:181], v182 offset:2048
	ds_read_b128 v[182:185], v182 offset:3072
	s_add_u32 s48, s48, 0x2b0000
	s_addc_u32 s49, s49, 0
	s_mov_b32 m0, s61
	v_lshl_add_u64 v[224:225], s[48:49], 0, v[128:129]
	ds_read_b128 v[186:189], v156 offset:32768
	ds_read_b128 v[190:193], v156 offset:33792
	ds_read_b128 v[194:197], v156 offset:34816
	ds_read_b128 v[198:201], v156 offset:35840
	ds_read_b128 v[202:205], v156 offset:36864
	ds_read_b128 v[206:209], v156 offset:37888
	ds_read_b128 v[210:213], v156 offset:38912
	ds_read_b128 v[214:217], v156 offset:39936
	global_load_lds_dwordx4 v[224:225], off
	v_lshl_add_u64 v[224:225], s[48:49], 0, v[132:133]
	s_mov_b32 m0, s62
	s_nop 0
	global_load_lds_dwordx4 v[224:225], off
	s_waitcnt vmcnt(8)
	s_waitcnt lgkmcnt(0)
	s_barrier
	s_setprio 1
	s_waitcnt lgkmcnt(0)
	v_mfma_f32_16x16x32_bf16 v[124:127], v[144:147], v[186:189], v[124:127]
	v_mfma_f32_16x16x32_bf16 v[124:127], v[158:161], v[190:193], v[124:127]
	v_mfma_f32_16x16x32_bf16 v[120:123], v[162:165], v[186:189], v[120:123]
	v_mfma_f32_16x16x32_bf16 v[120:123], v[166:169], v[190:193], v[120:123]
	v_mfma_f32_16x16x32_bf16 v[112:115], v[162:165], v[194:197], v[112:115]
	v_mfma_f32_16x16x32_bf16 v[112:115], v[166:169], v[198:201], v[112:115]
	v_mfma_f32_16x16x32_bf16 v[116:119], v[144:147], v[194:197], v[116:119]
	v_mfma_f32_16x16x32_bf16 v[116:119], v[158:161], v[198:201], v[116:119]
	v_mfma_f32_16x16x32_bf16 v[108:111], v[144:147], v[202:205], v[108:111]
	v_mfma_f32_16x16x32_bf16 v[108:111], v[158:161], v[206:209], v[108:111]
	v_mfma_f32_16x16x32_bf16 v[104:107], v[162:165], v[202:205], v[104:107]
	v_mfma_f32_16x16x32_bf16 v[104:107], v[166:169], v[206:209], v[104:107]
	v_mfma_f32_16x16x32_bf16 v[96:99], v[162:165], v[210:213], v[96:99]
	v_mfma_f32_16x16x32_bf16 v[96:99], v[166:169], v[214:217], v[96:99]
	v_mfma_f32_16x16x32_bf16 v[100:103], v[144:147], v[210:213], v[100:103]
	v_mfma_f32_16x16x32_bf16 v[100:103], v[158:161], v[214:217], v[100:103]
	s_setprio 0
	s_setprio 1
	v_mfma_f32_16x16x32_bf16 v[92:95], v[170:173], v[186:189], v[92:95]
	v_mfma_f32_16x16x32_bf16 v[92:95], v[174:177], v[190:193], v[92:95]
	v_mfma_f32_16x16x32_bf16 v[88:91], v[178:181], v[186:189], v[88:91]
	v_mfma_f32_16x16x32_bf16 v[88:91], v[182:185], v[190:193], v[88:91]
	v_mfma_f32_16x16x32_bf16 v[80:83], v[178:181], v[194:197], v[80:83]
	v_mfma_f32_16x16x32_bf16 v[80:83], v[182:185], v[198:201], v[80:83]
	v_mfma_f32_16x16x32_bf16 v[84:87], v[170:173], v[194:197], v[84:87]
	v_mfma_f32_16x16x32_bf16 v[84:87], v[174:177], v[198:201], v[84:87]
	v_mfma_f32_16x16x32_bf16 v[76:79], v[170:173], v[202:205], v[76:79]
	v_mfma_f32_16x16x32_bf16 v[76:79], v[174:177], v[206:209], v[76:79]
	v_mfma_f32_16x16x32_bf16 v[72:75], v[178:181], v[202:205], v[72:75]
	v_mfma_f32_16x16x32_bf16 v[72:75], v[182:185], v[206:209], v[72:75]
	v_mfma_f32_16x16x32_bf16 v[64:67], v[178:181], v[210:213], v[64:67]
	v_mfma_f32_16x16x32_bf16 v[64:67], v[182:185], v[214:217], v[64:67]
	v_mfma_f32_16x16x32_bf16 v[68:71], v[170:173], v[210:213], v[68:71]
	v_mfma_f32_16x16x32_bf16 v[68:71], v[174:177], v[214:217], v[68:71]
	s_setprio 0
	s_barrier
	s_add_i32 s48, s90, s53
	v_lshl_add_u64 v[148:149], v[148:149], 0, s[22:23]
	s_mov_b32 m0, s48
	ds_read_b128 v[186:189], v156 offset:49152
	ds_read_b128 v[190:193], v156 offset:50176
	ds_read_b128 v[194:197], v156 offset:51200
	ds_read_b128 v[198:201], v156 offset:52224
	ds_read_b128 v[202:205], v156 offset:53248
	ds_read_b128 v[206:209], v156 offset:54272
	ds_read_b128 v[210:213], v156 offset:55296
	ds_read_b128 v[214:217], v156 offset:56320
	global_load_lds_dwordx4 v[148:149], off
	s_add_i32 m0, s48, 0x2000
	s_add_u32 s46, s46, 0x2b0080
	v_lshl_add_u64 v[148:149], v[218:219], 0, s[22:23]
	s_addc_u32 s47, s47, 0
	s_add_i32 s48, s91, s53
	global_load_lds_dwordx4 v[148:149], off
	v_lshl_add_u64 v[148:149], s[46:47], 0, v[130:131]
	s_mov_b32 m0, s48
	s_nop 0
	global_load_lds_dwordx4 v[148:149], off
	v_lshl_add_u64 v[148:149], s[46:47], 0, v[134:135]
	s_add_i32 m0, s48, 0x2000
	s_nop 0
	global_load_lds_dwordx4 v[148:149], off
	v_lshl_add_u64 v[148:149], v[220:221], 0, s[22:23]
	s_mov_b32 m0, s64
	s_nop 0
	global_load_lds_dwordx4 v[148:149], off
	v_lshl_add_u64 v[148:149], v[222:223], 0, s[22:23]
	s_mov_b32 m0, s65
	s_nop 0
	global_load_lds_dwordx4 v[148:149], off
	s_waitcnt vmcnt(8)
	s_waitcnt lgkmcnt(0)
	s_barrier
	s_setprio 1
	s_waitcnt lgkmcnt(0)
	v_mfma_f32_16x16x32_bf16 v[60:63], v[144:147], v[186:189], v[60:63]
	v_mfma_f32_16x16x32_bf16 v[60:63], v[158:161], v[190:193], v[60:63]
	v_mfma_f32_16x16x32_bf16 v[56:59], v[162:165], v[186:189], v[56:59]
	v_mfma_f32_16x16x32_bf16 v[56:59], v[166:169], v[190:193], v[56:59]
	v_mfma_f32_16x16x32_bf16 v[48:51], v[162:165], v[194:197], v[48:51]
	v_mfma_f32_16x16x32_bf16 v[48:51], v[166:169], v[198:201], v[48:51]
	v_mfma_f32_16x16x32_bf16 v[52:55], v[144:147], v[194:197], v[52:55]
	v_mfma_f32_16x16x32_bf16 v[52:55], v[158:161], v[198:201], v[52:55]
	v_mfma_f32_16x16x32_bf16 v[44:47], v[144:147], v[202:205], v[44:47]
	v_mfma_f32_16x16x32_bf16 v[44:47], v[158:161], v[206:209], v[44:47]
	v_mfma_f32_16x16x32_bf16 v[40:43], v[162:165], v[202:205], v[40:43]
	v_mfma_f32_16x16x32_bf16 v[40:43], v[166:169], v[206:209], v[40:43]
	v_mfma_f32_16x16x32_bf16 v[32:35], v[162:165], v[210:213], v[32:35]
	v_mfma_f32_16x16x32_bf16 v[32:35], v[166:169], v[214:217], v[32:35]
	v_mfma_f32_16x16x32_bf16 v[36:39], v[144:147], v[210:213], v[36:39]
	v_mfma_f32_16x16x32_bf16 v[36:39], v[158:161], v[214:217], v[36:39]
	s_setprio 0
	s_setprio 1
	v_mfma_f32_16x16x32_bf16 v[28:31], v[170:173], v[186:189], v[28:31]
	v_mfma_f32_16x16x32_bf16 v[28:31], v[174:177], v[190:193], v[28:31]
	v_mfma_f32_16x16x32_bf16 v[24:27], v[178:181], v[186:189], v[24:27]
	v_mfma_f32_16x16x32_bf16 v[24:27], v[182:185], v[190:193], v[24:27]
	v_mfma_f32_16x16x32_bf16 v[16:19], v[178:181], v[194:197], v[16:19]
	v_mfma_f32_16x16x32_bf16 v[16:19], v[182:185], v[198:201], v[16:19]
	v_mfma_f32_16x16x32_bf16 v[20:23], v[170:173], v[194:197], v[20:23]
	v_mfma_f32_16x16x32_bf16 v[20:23], v[174:177], v[198:201], v[20:23]
	v_mfma_f32_16x16x32_bf16 v[12:15], v[170:173], v[202:205], v[12:15]
	v_mfma_f32_16x16x32_bf16 v[12:15], v[174:177], v[206:209], v[12:15]
	v_mfma_f32_16x16x32_bf16 v[8:11], v[178:181], v[202:205], v[8:11]
	v_mfma_f32_16x16x32_bf16 v[8:11], v[182:185], v[206:209], v[8:11]
	v_mfma_f32_16x16x32_bf16 v[0:3], v[178:181], v[210:213], v[0:3]
	v_mfma_f32_16x16x32_bf16 v[0:3], v[182:185], v[214:217], v[0:3]
	v_mfma_f32_16x16x32_bf16 v[4:7], v[170:173], v[210:213], v[4:7]
	v_mfma_f32_16x16x32_bf16 v[4:7], v[174:177], v[214:217], v[4:7]
	s_setprio 0
	s_barrier
	s_add_u32 s44, s44, 0x100
	s_addc_u32 s45, s45, 0
	s_add_u32 s87, s87, 0x100
	s_addc_u32 s88, s88, 0
	s_cmp_ge_i32 s89, s86
	s_mov_b32 s46, s89
	s_cbranch_scc0 .LBB0_1749
	s_and_b64 vcc, exec, s[24:25]
	s_cbranch_vccz .LBB0_1752
